# K-loops: next load segment's prep (m0/address/offset arithmetic) hoisted into the mid-block slot of the preceding MFMA block so ds_reads start right after the barrier (21 sites), on top of the hand-of
# speedup vs baseline: 1.0033x; 1.0033x over previous
; #define PG8_STAGE(bufoff, gbase, voff) do { _Pragma("unroll") for (int _i = 0; _i < 2; ++_i) \
;         __builtin_amdgcn_global_load_lds((const unsigned*)((const char*)(gbase) + (voff)[_i]), (LAS unsigned*)(lds + (bufoff) + ldsw + _i * 8192), 16, 0, 0); } while (0)
; #define PG8_LDA(dst, b, h) do { _Pragma("unroll") for (int m = 0; m < 4; ++m) _Pragma("unroll") for (int k = 0; k < 2; ++k) dst[m][k] = *(const LAS bf16x8*)(lds + PG8_SA(b, h) + aoff + m * 2048 + k * 1024); } while (0)
; #define PG8_LDB(dst, b, h) do { _Pragma("unroll") for (int n = 0; n < 2; ++n) _Pragma("unroll") for (int k = 0; k < 2; ++k) dst[n][k] = *(const LAS bf16x8*)(lds + PG8_SB(b, h) + boff + n * 2048 + k * 1024); } while (0)
; #define PG8_MMA(ai, bj, At, Bt) do { __builtin_amdgcn_s_setprio(1); _Pragma("unroll") for (int m = 0; m < 4; ++m) _Pragma("unroll") for (int n = 0; n < 2; ++n) _Pragma("unroll") for (int k = 0; k < 2; ++k) \
;         acc[ai][bj][m][n] = __builtin_amdgcn_mfma_f32_16x16x32_bf16(Bt[n][k], At[m][k], acc[ai][bj][m][n], 0, 0, 0); __builtin_amdgcn_s_setprio(0); } while (0)
; #define PG8_WAIT_V(n) asm volatile("s_waitcnt vmcnt(" #n ")" ::: "memory")
; #define PG8_WAIT_L(n) asm volatile("s_waitcnt lgkmcnt(" #n ")" ::: "memory")
; #define PG8_BAR __builtin_amdgcn_s_barrier()
; template <class Epi>
; __device__ __forceinline__ void gemm_phase(LAS unsigned char* lds, const GemmD g, const Epi& E, int G, int c) {
;     ...
;             const bool last = (t == nt - 2);
;             const char* a1 = cA + (size_t)(t + 1) * kstep;
;             const char* a2 = last ? nA : cA + (size_t)(t + 2) * kstep; const char* b2 = last ? nB : cB + (size_t)(t + 2) * kstep;
;             const char* a3 = a2 + kstep; const char* b3 = b2 + kstep;
;             PG8_LDB(B0, 0, 0); PG8_LDB(B1, 0, 1); PG8_SCHED; PG8_LDA(At, 0, 0); PG8_STAGE(PG8_SA(1, 1), a1 + hstepA, voffA);
;             PG8_WAIT_V(8); PG8_WAIT_L(0); PG8_BAR; PG8_MMA(0, 0, At, B0); PG8_MMA(0, 1, At, B1); PG8_BAR; PG8_SCHED;
;             PG8_LDA(At, 0, 1); PG8_STAGE(PG8_SB(0, 0), b2, voffB); PG8_STAGE(PG8_SB(0, 1), b2 + hstepB, voffB); PG8_STAGE(PG8_SA(0, 0), a2, voffA);
;             PG8_WAIT_V(8); PG8_WAIT_L(0); PG8_BAR; PG8_MMA(1, 0, At, B0); PG8_MMA(1, 1, At, B1); PG8_BAR; PG8_SCHED;
;             PG8_LDB(B0, 1, 0); PG8_LDB(B1, 1, 1); PG8_SCHED; PG8_LDA(At, 1, 0); PG8_STAGE(PG8_SA(0, 1), a2 + hstepA, voffA);
.LBB0_106:
	s_add_u32 s88, s46, 0x100
	s_addc_u32 s89, s47, 0
	s_add_i32 s31, 0, 0x10000
	s_cmpk_eq_i32 s30, 0x54
	s_cselect_b32 s5, s85, s89
	s_cselect_b32 s4, s84, s88
	v_add_u32_e32 v153, s31, v149
	s_cselect_b32 s91, s87, s29
	s_cselect_b32 s90, s86, s28
	s_add_i32 s33, 0, 0x14000
	ds_read_b128 v[140:143], v153
	ds_read_b128 v[144:147], v153 offset:1024
	ds_read_b128 v[154:157], v153 offset:2048
	ds_read_b128 v[158:161], v153 offset:3072
	v_add_u32_e32 v153, s33, v149
	ds_read_b128 v[162:165], v153
	ds_read_b128 v[166:169], v153 offset:1024
	ds_read_b128 v[170:173], v153 offset:2048
	ds_read_b128 v[180:183], v153 offset:3072
	v_lshl_add_u64 v[174:175], s[46:47], 0, v[136:137]
	s_add_i32 m0, s6, 0xc000
	ds_read_b128 v[184:187], v151
	ds_read_b128 v[188:191], v151 offset:1024
	ds_read_b128 v[192:195], v151 offset:2048
	ds_read_b128 v[210:213], v151 offset:3072
	ds_read_b128 v[214:217], v151 offset:4096
	ds_read_b128 v[218:221], v151 offset:5120
	ds_read_b128 v[222:225], v151 offset:6144
	ds_read_b128 v[226:229], v151 offset:7168
	global_load_lds_dwordx4 v[174:175], off
	v_lshl_add_u64 v[174:175], s[46:47], 0, v[138:139]
	s_add_i32 m0, s6, 0xe000
	s_nop 0
	global_load_lds_dwordx4 v[174:175], off
	s_waitcnt vmcnt(8)
	s_waitcnt lgkmcnt(0)
	s_setprio 1
	s_barrier
	v_mfma_f32_16x16x32_bf16 v[124:127], v[140:143], v[184:187], v[124:127]
	v_mfma_f32_16x16x32_bf16 v[116:119], v[154:157], v[184:187], v[116:119]
	v_mfma_f32_16x16x32_bf16 v[104:107], v[140:143], v[192:195], v[104:107]
	v_mfma_f32_16x16x32_bf16 v[96:99], v[154:157], v[192:195], v[96:99]
	v_mfma_f32_16x16x32_bf16 v[88:91], v[140:143], v[214:217], v[88:91]
	v_mfma_f32_16x16x32_bf16 v[80:83], v[154:157], v[214:217], v[80:83]
	v_mfma_f32_16x16x32_bf16 v[72:75], v[140:143], v[222:225], v[72:75]
	v_mfma_f32_16x16x32_bf16 v[64:67], v[154:157], v[222:225], v[64:67]
	v_mfma_f32_16x16x32_bf16 v[124:127], v[144:147], v[188:191], v[124:127]
	v_mfma_f32_16x16x32_bf16 v[116:119], v[158:161], v[188:191], v[116:119]
	v_mfma_f32_16x16x32_bf16 v[104:107], v[144:147], v[210:213], v[104:107]
	v_mfma_f32_16x16x32_bf16 v[96:99], v[158:161], v[210:213], v[96:99]
	v_mfma_f32_16x16x32_bf16 v[88:91], v[144:147], v[218:221], v[88:91]
	v_mfma_f32_16x16x32_bf16 v[80:83], v[158:161], v[218:221], v[80:83]
	v_mfma_f32_16x16x32_bf16 v[72:75], v[144:147], v[226:229], v[72:75]
	v_mfma_f32_16x16x32_bf16 v[64:67], v[158:161], v[226:229], v[64:67]
	s_setprio 0
	s_setprio 1
	s_add_i32 s31, s31, s2
	v_lshl_add_u64 v[174:175], s[90:91], 0, v[178:179]
	s_mov_b32 m0, s31
	v_mfma_f32_16x16x32_bf16 v[120:123], v[162:165], v[184:187], v[120:123]
	v_mfma_f32_16x16x32_bf16 v[112:115], v[170:173], v[184:187], v[112:115]
	v_mfma_f32_16x16x32_bf16 v[108:111], v[162:165], v[192:195], v[108:111]
	v_mfma_f32_16x16x32_bf16 v[100:103], v[170:173], v[192:195], v[100:103]
	v_mfma_f32_16x16x32_bf16 v[92:95], v[162:165], v[214:217], v[92:95]
	v_mfma_f32_16x16x32_bf16 v[84:87], v[170:173], v[214:217], v[84:87]
	v_mfma_f32_16x16x32_bf16 v[76:79], v[162:165], v[222:225], v[76:79]
	v_mfma_f32_16x16x32_bf16 v[68:71], v[170:173], v[222:225], v[68:71]
	v_mfma_f32_16x16x32_bf16 v[120:123], v[166:169], v[188:191], v[120:123]
	v_mfma_f32_16x16x32_bf16 v[112:115], v[180:183], v[188:191], v[112:115]
	v_mfma_f32_16x16x32_bf16 v[108:111], v[166:169], v[210:213], v[108:111]
	v_mfma_f32_16x16x32_bf16 v[100:103], v[180:183], v[210:213], v[100:103]
	v_mfma_f32_16x16x32_bf16 v[92:95], v[166:169], v[218:221], v[92:95]
	v_mfma_f32_16x16x32_bf16 v[84:87], v[180:183], v[218:221], v[84:87]
	v_mfma_f32_16x16x32_bf16 v[76:79], v[166:169], v[226:229], v[76:79]
	v_mfma_f32_16x16x32_bf16 v[68:71], v[180:183], v[226:229], v[68:71]
	s_barrier
	s_setprio 0
	ds_read_b128 v[184:187], v151 offset:16384
	ds_read_b128 v[188:191], v151 offset:17408
	ds_read_b128 v[192:195], v151 offset:18432
	ds_read_b128 v[210:213], v151 offset:19456
	ds_read_b128 v[214:217], v151 offset:20480
	ds_read_b128 v[218:221], v151 offset:21504
	ds_read_b128 v[222:225], v151 offset:22528
	ds_read_b128 v[226:229], v151 offset:23552
	global_load_lds_dwordx4 v[174:175], off
	s_add_i32 m0, s31, 0x2000
	s_add_u32 s38, s90, 0x160000
	v_lshl_add_u64 v[198:199], s[90:91], 0, v[128:129]
	s_addc_u32 s39, s91, 0
	s_add_i32 s31, s33, s2
	global_load_lds_dwordx4 v[198:199], off
	v_lshl_add_u64 v[230:231], s[38:39], 0, v[178:179]
	s_mov_b32 m0, s31
	v_lshl_add_u64 v[232:233], s[4:5], 0, v[130:131]
	global_load_lds_dwordx4 v[230:231], off
	v_lshl_add_u64 v[230:231], s[38:39], 0, v[128:129]
	s_add_i32 m0, s31, 0x2000
	s_nop 0
	global_load_lds_dwordx4 v[230:231], off
	v_lshl_add_u64 v[230:231], s[4:5], 0, v[132:133]
	s_mov_b32 m0, s6
	s_nop 0
	global_load_lds_dwordx4 v[230:231], off
	s_mov_b32 m0, s9
	s_nop 0
	global_load_lds_dwordx4 v[232:233], off
	s_waitcnt vmcnt(8)
	s_waitcnt lgkmcnt(0)
	s_setprio 1
	s_barrier
; #define PG8_STAGE(bufoff, gbase, voff) do { _Pragma("unroll") for (int _i = 0; _i < 2; ++_i) \
;         __builtin_amdgcn_global_load_lds((const unsigned*)((const char*)(gbase) + (voff)[_i]), (LAS unsigned*)(lds + (bufoff) + ldsw + _i * 8192), 16, 0, 0); } while (0)
; #define PG8_LDA(dst, b, h) do { _Pragma("unroll") for (int m = 0; m < 4; ++m) _Pragma("unroll") for (int k = 0; k < 2; ++k) dst[m][k] = *(const LAS bf16x8*)(lds + PG8_SA(b, h) + aoff + m * 2048 + k * 1024); } while (0)
; #define PG8_LDB(dst, b, h) do { _Pragma("unroll") for (int n = 0; n < 2; ++n) _Pragma("unroll") for (int k = 0; k < 2; ++k) dst[n][k] = *(const LAS bf16x8*)(lds + PG8_SB(b, h) + boff + n * 2048 + k * 1024); } while (0)
; #define PG8_MMA(ai, bj, At, Bt) do { __builtin_amdgcn_s_setprio(1); _Pragma("unroll") for (int m = 0; m < 4; ++m) _Pragma("unroll") for (int n = 0; n < 2; ++n) _Pragma("unroll") for (int k = 0; k < 2; ++k) \
;         acc[ai][bj][m][n] = __builtin_amdgcn_mfma_f32_16x16x32_bf16(Bt[n][k], At[m][k], acc[ai][bj][m][n], 0, 0, 0); __builtin_amdgcn_s_setprio(0); } while (0)
; #define PG8_WAIT_V(n) asm volatile("s_waitcnt vmcnt(" #n ")" ::: "memory")
; #define PG8_WAIT_L(n) asm volatile("s_waitcnt lgkmcnt(" #n ")" ::: "memory")
; #define PG8_BAR __builtin_amdgcn_s_barrier()
; #define PG8_SCHED __builtin_amdgcn_sched_barrier(0)
; template <class Epi>
; __device__ __forceinline__ void gemm_phase(LAS unsigned char* lds, const GemmD g, const Epi& E, int G, int c) {
;     ...
;             PG8_WAIT_V(8); PG8_WAIT_L(0); PG8_BAR; PG8_MMA(1, 0, At, B0); PG8_MMA(1, 1, At, B1); PG8_BAR; PG8_SCHED;
;             PG8_LDB(B0, 1, 0); PG8_LDB(B1, 1, 1); PG8_SCHED; PG8_LDA(At, 1, 0); PG8_STAGE(PG8_SA(0, 1), a2 + hstepA, voffA);
;             PG8_WAIT_V(8); PG8_WAIT_L(0); PG8_BAR; PG8_MMA(0, 0, At, B0); PG8_MMA(0, 1, At, B1); PG8_BAR; PG8_SCHED;
;             PG8_LDA(At, 1, 1); PG8_STAGE(PG8_SB(1, 0), b3, voffB); PG8_STAGE(PG8_SB(1, 1), b3 + hstepB, voffB); PG8_STAGE(PG8_SA(1, 0), a3, voffA);
	v_mfma_f32_16x16x32_bf16 v[52:55], v[140:143], v[184:187], v[52:55]
	v_mfma_f32_16x16x32_bf16 v[56:59], v[154:157], v[184:187], v[56:59]
	v_mfma_f32_16x16x32_bf16 v[40:43], v[140:143], v[192:195], v[40:43]
	v_mfma_f32_16x16x32_bf16 v[32:35], v[154:157], v[192:195], v[32:35]
	v_mfma_f32_16x16x32_bf16 v[20:23], v[140:143], v[214:217], v[20:23]
	v_mfma_f32_16x16x32_bf16 v[16:19], v[154:157], v[214:217], v[16:19]
	v_mfma_f32_16x16x32_bf16 v[4:7], v[140:143], v[222:225], v[4:7]
	v_mfma_f32_16x16x32_bf16 v[0:3], v[154:157], v[222:225], v[0:3]
	v_mfma_f32_16x16x32_bf16 v[52:55], v[144:147], v[188:191], v[52:55]
	v_mfma_f32_16x16x32_bf16 v[56:59], v[158:161], v[188:191], v[56:59]
	v_mfma_f32_16x16x32_bf16 v[40:43], v[144:147], v[210:213], v[40:43]
	v_mfma_f32_16x16x32_bf16 v[32:35], v[158:161], v[210:213], v[32:35]
	v_mfma_f32_16x16x32_bf16 v[20:23], v[144:147], v[218:221], v[20:23]
	v_mfma_f32_16x16x32_bf16 v[16:19], v[158:161], v[218:221], v[16:19]
	v_mfma_f32_16x16x32_bf16 v[4:7], v[144:147], v[226:229], v[4:7]
	v_mfma_f32_16x16x32_bf16 v[0:3], v[158:161], v[226:229], v[0:3]
	s_setprio 0
	s_setprio 1
	s_add_i32 s31, 0, 0x18000
	v_add_u32_e32 v153, s31, v149
	s_add_i32 s33, 0, 0x1c000
	v_mfma_f32_16x16x32_bf16 v[60:63], v[162:165], v[184:187], v[60:63]
	v_mfma_f32_16x16x32_bf16 v[48:51], v[170:173], v[184:187], v[48:51]
	v_mfma_f32_16x16x32_bf16 v[44:47], v[162:165], v[192:195], v[44:47]
	v_mfma_f32_16x16x32_bf16 v[36:39], v[170:173], v[192:195], v[36:39]
	v_mfma_f32_16x16x32_bf16 v[28:31], v[162:165], v[214:217], v[28:31]
	v_mfma_f32_16x16x32_bf16 v[24:27], v[170:173], v[214:217], v[24:27]
	v_mfma_f32_16x16x32_bf16 v[12:15], v[162:165], v[222:225], v[12:15]
	v_mfma_f32_16x16x32_bf16 v[8:11], v[170:173], v[222:225], v[8:11]
	v_mfma_f32_16x16x32_bf16 v[60:63], v[166:169], v[188:191], v[60:63]
	v_mfma_f32_16x16x32_bf16 v[48:51], v[180:183], v[188:191], v[48:51]
	v_mfma_f32_16x16x32_bf16 v[44:47], v[166:169], v[210:213], v[44:47]
	v_mfma_f32_16x16x32_bf16 v[36:39], v[180:183], v[210:213], v[36:39]
	v_mfma_f32_16x16x32_bf16 v[28:31], v[166:169], v[218:221], v[28:31]
	v_mfma_f32_16x16x32_bf16 v[24:27], v[180:183], v[218:221], v[24:27]
	v_mfma_f32_16x16x32_bf16 v[12:15], v[166:169], v[226:229], v[12:15]
	v_mfma_f32_16x16x32_bf16 v[8:11], v[180:183], v[226:229], v[8:11]
	s_barrier
	s_setprio 0
	ds_read_b128 v[140:143], v153
	ds_read_b128 v[144:147], v153 offset:1024
	ds_read_b128 v[154:157], v153 offset:2048
	ds_read_b128 v[158:161], v153 offset:3072
	v_add_u32_e32 v153, s33, v149
	ds_read_b128 v[162:165], v153
	ds_read_b128 v[166:169], v153 offset:1024
	ds_read_b128 v[170:173], v153 offset:2048
	ds_read_b128 v[180:183], v153 offset:3072
	s_add_u32 s4, s4, 0x160000
	s_addc_u32 s5, s5, 0
	s_mov_b32 m0, s10
	v_lshl_add_u64 v[234:235], s[4:5], 0, v[132:133]
	ds_read_b128 v[184:187], v151 offset:32768
	ds_read_b128 v[188:191], v151 offset:33792
	ds_read_b128 v[192:195], v151 offset:34816
	ds_read_b128 v[210:213], v151 offset:35840
	ds_read_b128 v[214:217], v151 offset:36864
	ds_read_b128 v[218:221], v151 offset:37888
	ds_read_b128 v[222:225], v151 offset:38912
	ds_read_b128 v[226:229], v151 offset:39936
	global_load_lds_dwordx4 v[234:235], off
	v_lshl_add_u64 v[234:235], s[4:5], 0, v[130:131]
	s_mov_b32 m0, s11
	s_nop 0
	global_load_lds_dwordx4 v[234:235], off
	s_waitcnt vmcnt(8)
	s_waitcnt lgkmcnt(0)
	s_setprio 1
	s_barrier
	v_mfma_f32_16x16x32_bf16 v[124:127], v[140:143], v[184:187], v[124:127]
	v_mfma_f32_16x16x32_bf16 v[116:119], v[154:157], v[184:187], v[116:119]
	v_mfma_f32_16x16x32_bf16 v[104:107], v[140:143], v[192:195], v[104:107]
	v_mfma_f32_16x16x32_bf16 v[96:99], v[154:157], v[192:195], v[96:99]
	v_mfma_f32_16x16x32_bf16 v[88:91], v[140:143], v[214:217], v[88:91]
	v_mfma_f32_16x16x32_bf16 v[80:83], v[154:157], v[214:217], v[80:83]
	v_mfma_f32_16x16x32_bf16 v[72:75], v[140:143], v[222:225], v[72:75]
	v_mfma_f32_16x16x32_bf16 v[64:67], v[154:157], v[222:225], v[64:67]
	v_mfma_f32_16x16x32_bf16 v[124:127], v[144:147], v[188:191], v[124:127]
	v_mfma_f32_16x16x32_bf16 v[116:119], v[158:161], v[188:191], v[116:119]
	v_mfma_f32_16x16x32_bf16 v[104:107], v[144:147], v[210:213], v[104:107]
	v_mfma_f32_16x16x32_bf16 v[96:99], v[158:161], v[210:213], v[96:99]
	v_mfma_f32_16x16x32_bf16 v[88:91], v[144:147], v[218:221], v[88:91]
	v_mfma_f32_16x16x32_bf16 v[80:83], v[158:161], v[218:221], v[80:83]
	v_mfma_f32_16x16x32_bf16 v[72:75], v[144:147], v[226:229], v[72:75]
	v_mfma_f32_16x16x32_bf16 v[64:67], v[158:161], v[226:229], v[64:67]
	s_setprio 0
	s_setprio 1
	s_add_i32 s4, s31, s2
	v_lshl_add_u64 v[174:175], v[174:175], 0, s[48:49]
	s_mov_b32 m0, s4
	v_mfma_f32_16x16x32_bf16 v[120:123], v[162:165], v[184:187], v[120:123]
	v_mfma_f32_16x16x32_bf16 v[112:115], v[170:173], v[184:187], v[112:115]
	v_mfma_f32_16x16x32_bf16 v[108:111], v[162:165], v[192:195], v[108:111]
	v_mfma_f32_16x16x32_bf16 v[100:103], v[170:173], v[192:195], v[100:103]
	v_mfma_f32_16x16x32_bf16 v[92:95], v[162:165], v[214:217], v[92:95]
	v_mfma_f32_16x16x32_bf16 v[84:87], v[170:173], v[214:217], v[84:87]
	v_mfma_f32_16x16x32_bf16 v[76:79], v[162:165], v[222:225], v[76:79]
	v_mfma_f32_16x16x32_bf16 v[68:71], v[170:173], v[222:225], v[68:71]
	v_mfma_f32_16x16x32_bf16 v[120:123], v[166:169], v[188:191], v[120:123]
	v_mfma_f32_16x16x32_bf16 v[112:115], v[180:183], v[188:191], v[112:115]
	v_mfma_f32_16x16x32_bf16 v[108:111], v[166:169], v[210:213], v[108:111]
	v_mfma_f32_16x16x32_bf16 v[100:103], v[180:183], v[210:213], v[100:103]
	v_mfma_f32_16x16x32_bf16 v[92:95], v[166:169], v[218:221], v[92:95]
	v_mfma_f32_16x16x32_bf16 v[84:87], v[180:183], v[218:221], v[84:87]
	v_mfma_f32_16x16x32_bf16 v[76:79], v[166:169], v[226:229], v[76:79]
	v_mfma_f32_16x16x32_bf16 v[68:71], v[180:183], v[226:229], v[68:71]
	s_barrier
; #define PG8_STAGE(bufoff, gbase, voff) do { _Pragma("unroll") for (int _i = 0; _i < 2; ++_i) \
;         __builtin_amdgcn_global_load_lds((const unsigned*)((const char*)(gbase) + (voff)[_i]), (LAS unsigned*)(lds + (bufoff) + ldsw + _i * 8192), 16, 0, 0); } while (0)
; #define PG8_LDA(dst, b, h) do { _Pragma("unroll") for (int m = 0; m < 4; ++m) _Pragma("unroll") for (int k = 0; k < 2; ++k) dst[m][k] = *(const LAS bf16x8*)(lds + PG8_SA(b, h) + aoff + m * 2048 + k * 1024); } while (0)
; #define PG8_MMA(ai, bj, At, Bt) do { __builtin_amdgcn_s_setprio(1); _Pragma("unroll") for (int m = 0; m < 4; ++m) _Pragma("unroll") for (int n = 0; n < 2; ++n) _Pragma("unroll") for (int k = 0; k < 2; ++k) \
;         acc[ai][bj][m][n] = __builtin_amdgcn_mfma_f32_16x16x32_bf16(Bt[n][k], At[m][k], acc[ai][bj][m][n], 0, 0, 0); __builtin_amdgcn_s_setprio(0); } while (0)
; #define PG8_WAIT_V(n) asm volatile("s_waitcnt vmcnt(" #n ")" ::: "memory")
; #define PG8_WAIT_L(n) asm volatile("s_waitcnt lgkmcnt(" #n ")" ::: "memory")
; #define PG8_BAR __builtin_amdgcn_s_barrier()
; #define PG8_SCHED __builtin_amdgcn_sched_barrier(0)
; template <class Epi>
; __device__ __forceinline__ void gemm_phase(LAS unsigned char* lds, const GemmD g, const Epi& E, int G, int c) {
;     ...
;             PG8_LDA(At, 1, 1); PG8_STAGE(PG8_SB(1, 0), b3, voffB); PG8_STAGE(PG8_SB(1, 1), b3 + hstepB, voffB); PG8_STAGE(PG8_SA(1, 0), a3, voffA);
;             PG8_WAIT_V(8); PG8_WAIT_L(0); PG8_BAR; PG8_MMA(1, 0, At, B0); PG8_MMA(1, 1, At, B1); PG8_BAR; PG8_SCHED;
;         }
;         if (wr == 0) PG8_BAR;
	s_setprio 0
	ds_read_b128 v[184:187], v151 offset:49152
	ds_read_b128 v[188:191], v151 offset:50176
	ds_read_b128 v[192:195], v151 offset:51200
	ds_read_b128 v[210:213], v151 offset:52224
	ds_read_b128 v[214:217], v151 offset:53248
	ds_read_b128 v[218:221], v151 offset:54272
	ds_read_b128 v[222:225], v151 offset:55296
	ds_read_b128 v[226:229], v151 offset:56320
	global_load_lds_dwordx4 v[174:175], off
	s_add_i32 m0, s4, 0x2000
	s_add_u32 s4, s90, 0x160080
	v_lshl_add_u64 v[174:175], v[198:199], 0, s[48:49]
	s_addc_u32 s5, s91, 0
	s_add_i32 s31, s33, s2
	global_load_lds_dwordx4 v[174:175], off
	v_lshl_add_u64 v[174:175], s[4:5], 0, v[178:179]
	s_mov_b32 m0, s31
	s_nop 0
	global_load_lds_dwordx4 v[174:175], off
	v_lshl_add_u64 v[174:175], s[4:5], 0, v[128:129]
	s_add_i32 m0, s31, 0x2000
	s_nop 0
	global_load_lds_dwordx4 v[174:175], off
	v_lshl_add_u64 v[174:175], v[230:231], 0, s[48:49]
	s_mov_b32 m0, s16
	s_nop 0
	global_load_lds_dwordx4 v[174:175], off
	v_lshl_add_u64 v[174:175], v[232:233], 0, s[48:49]
	s_mov_b32 m0, s17
	s_nop 0
	global_load_lds_dwordx4 v[174:175], off
	s_waitcnt vmcnt(8)
	s_waitcnt lgkmcnt(0)
	s_setprio 1
	s_barrier
	v_mfma_f32_16x16x32_bf16 v[52:55], v[140:143], v[184:187], v[52:55]
	v_mfma_f32_16x16x32_bf16 v[56:59], v[154:157], v[184:187], v[56:59]
	v_mfma_f32_16x16x32_bf16 v[40:43], v[140:143], v[192:195], v[40:43]
	v_mfma_f32_16x16x32_bf16 v[32:35], v[154:157], v[192:195], v[32:35]
	v_mfma_f32_16x16x32_bf16 v[20:23], v[140:143], v[214:217], v[20:23]
	v_mfma_f32_16x16x32_bf16 v[16:19], v[154:157], v[214:217], v[16:19]
	v_mfma_f32_16x16x32_bf16 v[4:7], v[140:143], v[222:225], v[4:7]
	v_mfma_f32_16x16x32_bf16 v[0:3], v[154:157], v[222:225], v[0:3]
	v_mfma_f32_16x16x32_bf16 v[52:55], v[144:147], v[188:191], v[52:55]
	v_mfma_f32_16x16x32_bf16 v[56:59], v[158:161], v[188:191], v[56:59]
	v_mfma_f32_16x16x32_bf16 v[40:43], v[144:147], v[210:213], v[40:43]
	v_mfma_f32_16x16x32_bf16 v[32:35], v[158:161], v[210:213], v[32:35]
	v_mfma_f32_16x16x32_bf16 v[20:23], v[144:147], v[218:221], v[20:23]
	v_mfma_f32_16x16x32_bf16 v[16:19], v[158:161], v[218:221], v[16:19]
	v_mfma_f32_16x16x32_bf16 v[4:7], v[144:147], v[226:229], v[4:7]
	v_mfma_f32_16x16x32_bf16 v[0:3], v[158:161], v[226:229], v[0:3]
	s_setprio 0
	s_setprio 1
	v_mfma_f32_16x16x32_bf16 v[60:63], v[162:165], v[184:187], v[60:63]
	v_mfma_f32_16x16x32_bf16 v[48:51], v[170:173], v[184:187], v[48:51]
	v_mfma_f32_16x16x32_bf16 v[44:47], v[162:165], v[192:195], v[44:47]
	v_mfma_f32_16x16x32_bf16 v[36:39], v[170:173], v[192:195], v[36:39]
	v_mfma_f32_16x16x32_bf16 v[28:31], v[162:165], v[214:217], v[28:31]
	v_mfma_f32_16x16x32_bf16 v[24:27], v[170:173], v[214:217], v[24:27]
	v_mfma_f32_16x16x32_bf16 v[12:15], v[162:165], v[222:225], v[12:15]
	v_mfma_f32_16x16x32_bf16 v[8:11], v[170:173], v[222:225], v[8:11]
	v_mfma_f32_16x16x32_bf16 v[60:63], v[166:169], v[188:191], v[60:63]
	v_mfma_f32_16x16x32_bf16 v[48:51], v[180:183], v[188:191], v[48:51]
	v_mfma_f32_16x16x32_bf16 v[44:47], v[166:169], v[210:213], v[44:47]
	v_mfma_f32_16x16x32_bf16 v[36:39], v[180:183], v[210:213], v[36:39]
	v_mfma_f32_16x16x32_bf16 v[28:31], v[166:169], v[218:221], v[28:31]
	v_mfma_f32_16x16x32_bf16 v[24:27], v[180:183], v[218:221], v[24:27]
	v_mfma_f32_16x16x32_bf16 v[12:15], v[166:169], v[226:229], v[12:15]
	v_mfma_f32_16x16x32_bf16 v[8:11], v[180:183], v[226:229], v[8:11]
	s_barrier
	s_setprio 0
	s_add_i32 s30, s30, 2
	s_add_u32 s28, s28, 0x100
	s_addc_u32 s29, s29, 0
	s_cmpk_gt_u32 s30, 0x55
	s_mov_b64 s[46:47], s[88:89]
	s_cbranch_scc0 .LBB0_106
	s_and_b64 vcc, exec, s[80:81]
	s_cbranch_vccz .LBB0_109
	s_barrier

; #define PG8_STAGE(bufoff, gbase, voff) do { _Pragma("unroll") for (int _i = 0; _i < 2; ++_i) \
;         __builtin_amdgcn_global_load_lds((const unsigned*)((const char*)(gbase) + (voff)[_i]), (LAS unsigned*)(lds + (bufoff) + ldsw + _i * 8192), 16, 0, 0); } while (0)
; #define PG8_LDA(dst, b, h) do { _Pragma("unroll") for (int m = 0; m < 4; ++m) _Pragma("unroll") for (int k = 0; k < 2; ++k) dst[m][k] = *(const LAS bf16x8*)(lds + PG8_SA(b, h) + aoff + m * 2048 + k * 1024); } while (0)
; #define PG8_MMA(ai, bj, At, Bt) do { __builtin_amdgcn_s_setprio(1); _Pragma("unroll") for (int m = 0; m < 4; ++m) _Pragma("unroll") for (int n = 0; n < 2; ++n) _Pragma("unroll") for (int k = 0; k < 2; ++k) \
;         acc[ai][bj][m][n] = __builtin_amdgcn_mfma_f32_16x16x32_bf16(Bt[n][k], At[m][k], acc[ai][bj][m][n], 0, 0, 0); __builtin_amdgcn_s_setprio(0); } while (0)
; #define PG8_WAIT_V(n) asm volatile("s_waitcnt vmcnt(" #n ")" ::: "memory")
; #define PG8_WAIT_L(n) asm volatile("s_waitcnt lgkmcnt(" #n ")" ::: "memory")
; #define PG8_BAR __builtin_amdgcn_s_barrier()
; #define PG8_SCHED __builtin_amdgcn_sched_barrier(0)
; template <class Epi>
; __device__ __forceinline__ void gemm_phase(LAS unsigned char* lds, const GemmD g, const Epi& E, int G, int c) {
;     ...
;             PG8_WAIT_V(8); PG8_WAIT_L(0); PG8_BAR; PG8_MMA(0, 0, At, B0); PG8_MMA(0, 1, At, B1); PG8_BAR; PG8_SCHED;
;             PG8_LDA(At, 0, 1); PG8_STAGE(PG8_SB(0, 0), b2, voffB); PG8_STAGE(PG8_SB(0, 1), b2 + hstepB, voffB); PG8_STAGE(PG8_SA(0, 0), a2, voffA);
.Lrw_FfnUp_0_d:
	s_waitcnt lgkmcnt(0)
	s_setprio 1
	s_barrier
	v_mfma_f32_16x16x32_bf16 v[124:127], v[138:141], v[184:187], v[124:127]
	v_mfma_f32_16x16x32_bf16 v[116:119], v[156:159], v[184:187], v[116:119]
	v_mfma_f32_16x16x32_bf16 v[108:111], v[138:141], v[192:195], v[108:111]
	v_mfma_f32_16x16x32_bf16 v[100:103], v[156:159], v[192:195], v[100:103]
	v_mfma_f32_16x16x32_bf16 v[92:95], v[138:141], v[214:217], v[92:95]
	v_mfma_f32_16x16x32_bf16 v[84:87], v[156:159], v[214:217], v[84:87]
	v_mfma_f32_16x16x32_bf16 v[76:79], v[138:141], v[222:225], v[76:79]
	v_mfma_f32_16x16x32_bf16 v[68:71], v[156:159], v[222:225], v[68:71]
	v_mfma_f32_16x16x32_bf16 v[124:127], v[152:155], v[188:191], v[124:127]
	v_mfma_f32_16x16x32_bf16 v[116:119], v[160:163], v[188:191], v[116:119]
	v_mfma_f32_16x16x32_bf16 v[108:111], v[152:155], v[210:213], v[108:111]
	v_mfma_f32_16x16x32_bf16 v[100:103], v[160:163], v[210:213], v[100:103]
	v_mfma_f32_16x16x32_bf16 v[92:95], v[152:155], v[218:221], v[92:95]
	v_mfma_f32_16x16x32_bf16 v[84:87], v[160:163], v[218:221], v[84:87]
	v_mfma_f32_16x16x32_bf16 v[76:79], v[152:155], v[226:229], v[76:79]
	v_mfma_f32_16x16x32_bf16 v[68:71], v[160:163], v[226:229], v[68:71]
	s_setprio 0
	s_setprio 1
	s_add_i32 s35, s35, s2
	v_lshl_add_u64 v[146:147], s[86:87], 0, v[178:179]
	s_mov_b32 m0, s35
	v_mfma_f32_16x16x32_bf16 v[120:123], v[164:167], v[184:187], v[120:123]
	v_mfma_f32_16x16x32_bf16 v[112:115], v[172:175], v[184:187], v[112:115]
	v_mfma_f32_16x16x32_bf16 v[104:107], v[164:167], v[192:195], v[104:107]
	v_mfma_f32_16x16x32_bf16 v[96:99], v[172:175], v[192:195], v[96:99]
	v_mfma_f32_16x16x32_bf16 v[88:91], v[164:167], v[214:217], v[88:91]
	v_mfma_f32_16x16x32_bf16 v[80:83], v[172:175], v[214:217], v[80:83]
	v_mfma_f32_16x16x32_bf16 v[72:75], v[164:167], v[222:225], v[72:75]
	v_mfma_f32_16x16x32_bf16 v[64:67], v[172:175], v[222:225], v[64:67]
	v_mfma_f32_16x16x32_bf16 v[120:123], v[168:171], v[188:191], v[120:123]
	v_mfma_f32_16x16x32_bf16 v[112:115], v[180:183], v[188:191], v[112:115]
	v_mfma_f32_16x16x32_bf16 v[104:107], v[168:171], v[210:213], v[104:107]
	v_mfma_f32_16x16x32_bf16 v[96:99], v[180:183], v[210:213], v[96:99]
	v_mfma_f32_16x16x32_bf16 v[88:91], v[168:171], v[218:221], v[88:91]
	v_mfma_f32_16x16x32_bf16 v[80:83], v[180:183], v[218:221], v[80:83]
	v_mfma_f32_16x16x32_bf16 v[72:75], v[168:171], v[226:229], v[72:75]
	v_mfma_f32_16x16x32_bf16 v[64:67], v[180:183], v[226:229], v[64:67]
	s_barrier
	s_setprio 0
	ds_read_b128 v[184:187], v151 offset:16384
	ds_read_b128 v[188:191], v151 offset:17408
	ds_read_b128 v[192:195], v151 offset:18432
	ds_read_b128 v[210:213], v151 offset:19456
	ds_read_b128 v[214:217], v151 offset:20480
	ds_read_b128 v[218:221], v151 offset:21504
	ds_read_b128 v[222:225], v151 offset:22528
	ds_read_b128 v[226:229], v151 offset:23552
	global_load_lds_dwordx4 v[146:147], off
	s_add_i32 m0, s35, 0x2000
	s_add_u32 s38, s86, 0x80000
	v_lshl_add_u64 v[198:199], s[86:87], 0, v[128:129]
	s_addc_u32 s39, s87, 0
	s_add_i32 s35, s36, s2
	global_load_lds_dwordx4 v[198:199], off
	v_lshl_add_u64 v[230:231], s[38:39], 0, v[178:179]
	s_mov_b32 m0, s35
	v_lshl_add_u64 v[232:233], s[4:5], 0, v[130:131]
	global_load_lds_dwordx4 v[230:231], off
	v_lshl_add_u64 v[230:231], s[38:39], 0, v[128:129]
	s_add_i32 m0, s35, 0x2000
	s_nop 0
	global_load_lds_dwordx4 v[230:231], off
	v_lshl_add_u64 v[230:231], s[4:5], 0, v[132:133]
	s_mov_b32 m0, s6
	s_nop 0
	global_load_lds_dwordx4 v[230:231], off
	s_mov_b32 m0, s9
	s_nop 0
	global_load_lds_dwordx4 v[232:233], off
	s_cmp_lg_u32 s99, 0
	s_cbranch_scc1 .Lrw_FfnUp_1_r
	s_waitcnt vmcnt(8)
	s_branch .Lrw_FfnUp_1_d

; #define PG8_STAGE(bufoff, gbase, voff) do { _Pragma("unroll") for (int _i = 0; _i < 2; ++_i) \
;         __builtin_amdgcn_global_load_lds((const unsigned*)((const char*)(gbase) + (voff)[_i]), (LAS unsigned*)(lds + (bufoff) + ldsw + _i * 8192), 16, 0, 0); } while (0)
; #define PG8_LDA(dst, b, h) do { _Pragma("unroll") for (int m = 0; m < 4; ++m) _Pragma("unroll") for (int k = 0; k < 2; ++k) dst[m][k] = *(const LAS bf16x8*)(lds + PG8_SA(b, h) + aoff + m * 2048 + k * 1024); } while (0)
; #define PG8_LDB(dst, b, h) do { _Pragma("unroll") for (int n = 0; n < 2; ++n) _Pragma("unroll") for (int k = 0; k < 2; ++k) dst[n][k] = *(const LAS bf16x8*)(lds + PG8_SB(b, h) + boff + n * 2048 + k * 1024); } while (0)
; #define PG8_MMA(ai, bj, At, Bt) do { __builtin_amdgcn_s_setprio(1); _Pragma("unroll") for (int m = 0; m < 4; ++m) _Pragma("unroll") for (int n = 0; n < 2; ++n) _Pragma("unroll") for (int k = 0; k < 2; ++k) \
;         acc[ai][bj][m][n] = __builtin_amdgcn_mfma_f32_16x16x32_bf16(Bt[n][k], At[m][k], acc[ai][bj][m][n], 0, 0, 0); __builtin_amdgcn_s_setprio(0); } while (0)
; #define PG8_WAIT_V(n) asm volatile("s_waitcnt vmcnt(" #n ")" ::: "memory")
; #define PG8_WAIT_L(n) asm volatile("s_waitcnt lgkmcnt(" #n ")" ::: "memory")
; #define PG8_BAR __builtin_amdgcn_s_barrier()
; #define PG8_SCHED __builtin_amdgcn_sched_barrier(0)
; template <class Epi>
; __device__ __forceinline__ void gemm_phase(LAS unsigned char* lds, const GemmD g, const Epi& E, int G, int c) {
;     ...
;             PG8_WAIT_V(8); PG8_WAIT_L(0); PG8_BAR; PG8_MMA(1, 0, At, B0); PG8_MMA(1, 1, At, B1); PG8_BAR; PG8_SCHED;
;             PG8_LDB(B0, 1, 0); PG8_LDB(B1, 1, 1); PG8_SCHED; PG8_LDA(At, 1, 0); PG8_STAGE(PG8_SA(0, 1), a2 + hstepA, voffA);
;             PG8_WAIT_V(8); PG8_WAIT_L(0); PG8_BAR; PG8_MMA(0, 0, At, B0); PG8_MMA(0, 1, At, B1); PG8_BAR; PG8_SCHED;
.Lrw_FfnUp_1_d:
	s_waitcnt lgkmcnt(0)
	s_setprio 1
	s_barrier
	v_mfma_f32_16x16x32_bf16 v[60:63], v[138:141], v[184:187], v[60:63]
	v_mfma_f32_16x16x32_bf16 v[52:55], v[156:159], v[184:187], v[52:55]
	v_mfma_f32_16x16x32_bf16 v[44:47], v[138:141], v[192:195], v[44:47]
	v_mfma_f32_16x16x32_bf16 v[36:39], v[156:159], v[192:195], v[36:39]
	v_mfma_f32_16x16x32_bf16 v[28:31], v[138:141], v[214:217], v[28:31]
	v_mfma_f32_16x16x32_bf16 v[20:23], v[156:159], v[214:217], v[20:23]
	v_mfma_f32_16x16x32_bf16 v[12:15], v[138:141], v[222:225], v[12:15]
	v_mfma_f32_16x16x32_bf16 v[4:7], v[156:159], v[222:225], v[4:7]
	v_mfma_f32_16x16x32_bf16 v[60:63], v[152:155], v[188:191], v[60:63]
	v_mfma_f32_16x16x32_bf16 v[52:55], v[160:163], v[188:191], v[52:55]
	v_mfma_f32_16x16x32_bf16 v[44:47], v[152:155], v[210:213], v[44:47]
	v_mfma_f32_16x16x32_bf16 v[36:39], v[160:163], v[210:213], v[36:39]
	v_mfma_f32_16x16x32_bf16 v[28:31], v[152:155], v[218:221], v[28:31]
	v_mfma_f32_16x16x32_bf16 v[20:23], v[160:163], v[218:221], v[20:23]
	v_mfma_f32_16x16x32_bf16 v[12:15], v[152:155], v[226:229], v[12:15]
	v_mfma_f32_16x16x32_bf16 v[4:7], v[160:163], v[226:229], v[4:7]
	s_setprio 0
	s_setprio 1
	s_add_i32 s35, 0, 0x18000
	v_add_u32_e32 v142, s35, v145
	s_add_i32 s36, 0, 0x1c000
	v_mfma_f32_16x16x32_bf16 v[56:59], v[164:167], v[184:187], v[56:59]
	v_mfma_f32_16x16x32_bf16 v[48:51], v[172:175], v[184:187], v[48:51]
	v_mfma_f32_16x16x32_bf16 v[40:43], v[164:167], v[192:195], v[40:43]
	v_mfma_f32_16x16x32_bf16 v[32:35], v[172:175], v[192:195], v[32:35]
	v_mfma_f32_16x16x32_bf16 v[24:27], v[164:167], v[214:217], v[24:27]
	v_mfma_f32_16x16x32_bf16 v[16:19], v[172:175], v[214:217], v[16:19]
	v_mfma_f32_16x16x32_bf16 v[8:11], v[164:167], v[222:225], v[8:11]
	v_mfma_f32_16x16x32_bf16 v[0:3], v[172:175], v[222:225], v[0:3]
	v_mfma_f32_16x16x32_bf16 v[56:59], v[168:171], v[188:191], v[56:59]
	v_mfma_f32_16x16x32_bf16 v[48:51], v[180:183], v[188:191], v[48:51]
	v_mfma_f32_16x16x32_bf16 v[40:43], v[168:171], v[210:213], v[40:43]
	v_mfma_f32_16x16x32_bf16 v[32:35], v[180:183], v[210:213], v[32:35]
	v_mfma_f32_16x16x32_bf16 v[24:27], v[168:171], v[218:221], v[24:27]
	v_mfma_f32_16x16x32_bf16 v[16:19], v[180:183], v[218:221], v[16:19]
	v_mfma_f32_16x16x32_bf16 v[8:11], v[168:171], v[226:229], v[8:11]
	v_mfma_f32_16x16x32_bf16 v[0:3], v[180:183], v[226:229], v[0:3]
	s_barrier
	s_setprio 0
	ds_read_b128 v[138:141], v142
	ds_read_b128 v[152:155], v142 offset:1024
	ds_read_b128 v[156:159], v142 offset:2048
	ds_read_b128 v[160:163], v142 offset:3072
	v_add_u32_e32 v142, s36, v145
	ds_read_b128 v[164:167], v142
	ds_read_b128 v[168:171], v142 offset:1024
	ds_read_b128 v[172:175], v142 offset:2048
	ds_read_b128 v[180:183], v142 offset:3072
	s_add_u32 s4, s4, 0x80000
	s_addc_u32 s5, s5, 0
	s_mov_b32 m0, s10
	v_lshl_add_u64 v[234:235], s[4:5], 0, v[132:133]
	ds_read_b128 v[184:187], v151 offset:32768
	ds_read_b128 v[188:191], v151 offset:33792
	ds_read_b128 v[192:195], v151 offset:34816
	ds_read_b128 v[210:213], v151 offset:35840
	ds_read_b128 v[214:217], v151 offset:36864
	ds_read_b128 v[218:221], v151 offset:37888
	ds_read_b128 v[222:225], v151 offset:38912
	ds_read_b128 v[226:229], v151 offset:39936
	global_load_lds_dwordx4 v[234:235], off
	v_lshl_add_u64 v[234:235], s[4:5], 0, v[130:131]
	s_mov_b32 m0, s11
	s_nop 0
	global_load_lds_dwordx4 v[234:235], off
	s_waitcnt vmcnt(8)
	s_waitcnt lgkmcnt(0)
	s_setprio 1
	s_barrier
	v_mfma_f32_16x16x32_bf16 v[124:127], v[138:141], v[184:187], v[124:127]
	v_mfma_f32_16x16x32_bf16 v[116:119], v[156:159], v[184:187], v[116:119]
	v_mfma_f32_16x16x32_bf16 v[108:111], v[138:141], v[192:195], v[108:111]
	v_mfma_f32_16x16x32_bf16 v[100:103], v[156:159], v[192:195], v[100:103]
	v_mfma_f32_16x16x32_bf16 v[92:95], v[138:141], v[214:217], v[92:95]
	v_mfma_f32_16x16x32_bf16 v[84:87], v[156:159], v[214:217], v[84:87]
	v_mfma_f32_16x16x32_bf16 v[76:79], v[138:141], v[222:225], v[76:79]
	v_mfma_f32_16x16x32_bf16 v[68:71], v[156:159], v[222:225], v[68:71]
	v_mfma_f32_16x16x32_bf16 v[124:127], v[152:155], v[188:191], v[124:127]
	v_mfma_f32_16x16x32_bf16 v[116:119], v[160:163], v[188:191], v[116:119]
	v_mfma_f32_16x16x32_bf16 v[108:111], v[152:155], v[210:213], v[108:111]
	v_mfma_f32_16x16x32_bf16 v[100:103], v[160:163], v[210:213], v[100:103]
	v_mfma_f32_16x16x32_bf16 v[92:95], v[152:155], v[218:221], v[92:95]
	v_mfma_f32_16x16x32_bf16 v[84:87], v[160:163], v[218:221], v[84:87]
	v_mfma_f32_16x16x32_bf16 v[76:79], v[152:155], v[226:229], v[76:79]
	v_mfma_f32_16x16x32_bf16 v[68:71], v[160:163], v[226:229], v[68:71]
	s_setprio 0
	s_setprio 1
	s_add_i32 s4, s35, s2
	v_lshl_add_u64 v[146:147], v[146:147], 0, s[48:49]
	s_mov_b32 m0, s4
	v_mfma_f32_16x16x32_bf16 v[120:123], v[164:167], v[184:187], v[120:123]
	v_mfma_f32_16x16x32_bf16 v[112:115], v[172:175], v[184:187], v[112:115]
	v_mfma_f32_16x16x32_bf16 v[104:107], v[164:167], v[192:195], v[104:107]
	v_mfma_f32_16x16x32_bf16 v[96:99], v[172:175], v[192:195], v[96:99]
	v_mfma_f32_16x16x32_bf16 v[88:91], v[164:167], v[214:217], v[88:91]
	v_mfma_f32_16x16x32_bf16 v[80:83], v[172:175], v[214:217], v[80:83]
	v_mfma_f32_16x16x32_bf16 v[72:75], v[164:167], v[222:225], v[72:75]
	v_mfma_f32_16x16x32_bf16 v[64:67], v[172:175], v[222:225], v[64:67]
	v_mfma_f32_16x16x32_bf16 v[120:123], v[168:171], v[188:191], v[120:123]
	v_mfma_f32_16x16x32_bf16 v[112:115], v[180:183], v[188:191], v[112:115]
	v_mfma_f32_16x16x32_bf16 v[104:107], v[168:171], v[210:213], v[104:107]
	v_mfma_f32_16x16x32_bf16 v[96:99], v[180:183], v[210:213], v[96:99]
	v_mfma_f32_16x16x32_bf16 v[88:91], v[168:171], v[218:221], v[88:91]
	v_mfma_f32_16x16x32_bf16 v[80:83], v[180:183], v[218:221], v[80:83]
	v_mfma_f32_16x16x32_bf16 v[72:75], v[168:171], v[226:229], v[72:75]
	v_mfma_f32_16x16x32_bf16 v[64:67], v[180:183], v[226:229], v[64:67]
	s_barrier
; #define PG8_STAGE(bufoff, gbase, voff) do { _Pragma("unroll") for (int _i = 0; _i < 2; ++_i) \
;         __builtin_amdgcn_global_load_lds((const unsigned*)((const char*)(gbase) + (voff)[_i]), (LAS unsigned*)(lds + (bufoff) + ldsw + _i * 8192), 16, 0, 0); } while (0)
; #define PG8_LDA(dst, b, h) do { _Pragma("unroll") for (int m = 0; m < 4; ++m) _Pragma("unroll") for (int k = 0; k < 2; ++k) dst[m][k] = *(const LAS bf16x8*)(lds + PG8_SA(b, h) + aoff + m * 2048 + k * 1024); } while (0)
; #define PG8_MMA(ai, bj, At, Bt) do { __builtin_amdgcn_s_setprio(1); _Pragma("unroll") for (int m = 0; m < 4; ++m) _Pragma("unroll") for (int n = 0; n < 2; ++n) _Pragma("unroll") for (int k = 0; k < 2; ++k) \
;         acc[ai][bj][m][n] = __builtin_amdgcn_mfma_f32_16x16x32_bf16(Bt[n][k], At[m][k], acc[ai][bj][m][n], 0, 0, 0); __builtin_amdgcn_s_setprio(0); } while (0)
; #define PG8_WAIT_V(n) asm volatile("s_waitcnt vmcnt(" #n ")" ::: "memory")
; #define PG8_WAIT_L(n) asm volatile("s_waitcnt lgkmcnt(" #n ")" ::: "memory")
; #define PG8_BAR __builtin_amdgcn_s_barrier()
; #define PG8_SCHED __builtin_amdgcn_sched_barrier(0)
; template <class Epi>
; __device__ __forceinline__ void gemm_phase(LAS unsigned char* lds, const GemmD g, const Epi& E, int G, int c) {
;     ...
;             PG8_LDA(At, 1, 1); PG8_STAGE(PG8_SB(1, 0), b3, voffB); PG8_STAGE(PG8_SB(1, 1), b3 + hstepB, voffB); PG8_STAGE(PG8_SA(1, 0), a3, voffA);
;             PG8_WAIT_V(8); PG8_WAIT_L(0); PG8_BAR; PG8_MMA(1, 0, At, B0); PG8_MMA(1, 1, At, B1); PG8_BAR; PG8_SCHED;
;         }
;         if (wr == 0) PG8_BAR;
	s_setprio 0
	ds_read_b128 v[184:187], v151 offset:49152
	ds_read_b128 v[188:191], v151 offset:50176
	ds_read_b128 v[192:195], v151 offset:51200
	ds_read_b128 v[210:213], v151 offset:52224
	ds_read_b128 v[214:217], v151 offset:53248
	ds_read_b128 v[218:221], v151 offset:54272
	ds_read_b128 v[222:225], v151 offset:55296
	ds_read_b128 v[226:229], v151 offset:56320
	global_load_lds_dwordx4 v[146:147], off
	s_add_i32 m0, s4, 0x2000
	s_add_u32 s4, s86, 0x80080
	v_lshl_add_u64 v[146:147], v[198:199], 0, s[48:49]
	s_addc_u32 s5, s87, 0
	s_add_i32 s35, s36, s2
	global_load_lds_dwordx4 v[146:147], off
	v_lshl_add_u64 v[146:147], s[4:5], 0, v[178:179]
	s_mov_b32 m0, s35
	s_nop 0
	global_load_lds_dwordx4 v[146:147], off
	v_lshl_add_u64 v[146:147], s[4:5], 0, v[128:129]
	s_add_i32 m0, s35, 0x2000
	s_nop 0
	global_load_lds_dwordx4 v[146:147], off
	v_lshl_add_u64 v[146:147], v[230:231], 0, s[48:49]
	s_mov_b32 m0, s16
	s_nop 0
	global_load_lds_dwordx4 v[146:147], off
	v_lshl_add_u64 v[146:147], v[232:233], 0, s[48:49]
	s_mov_b32 m0, s17
	s_nop 0
	global_load_lds_dwordx4 v[146:147], off
	s_waitcnt vmcnt(8)
	s_waitcnt lgkmcnt(0)
	s_setprio 1
	s_barrier
	v_mfma_f32_16x16x32_bf16 v[60:63], v[138:141], v[184:187], v[60:63]
	v_mfma_f32_16x16x32_bf16 v[52:55], v[156:159], v[184:187], v[52:55]
	v_mfma_f32_16x16x32_bf16 v[44:47], v[138:141], v[192:195], v[44:47]
	v_mfma_f32_16x16x32_bf16 v[36:39], v[156:159], v[192:195], v[36:39]
	v_mfma_f32_16x16x32_bf16 v[28:31], v[138:141], v[214:217], v[28:31]
	v_mfma_f32_16x16x32_bf16 v[20:23], v[156:159], v[214:217], v[20:23]
	v_mfma_f32_16x16x32_bf16 v[12:15], v[138:141], v[222:225], v[12:15]
	v_mfma_f32_16x16x32_bf16 v[4:7], v[156:159], v[222:225], v[4:7]
	v_mfma_f32_16x16x32_bf16 v[60:63], v[152:155], v[188:191], v[60:63]
	v_mfma_f32_16x16x32_bf16 v[52:55], v[160:163], v[188:191], v[52:55]
	v_mfma_f32_16x16x32_bf16 v[44:47], v[152:155], v[210:213], v[44:47]
	v_mfma_f32_16x16x32_bf16 v[36:39], v[160:163], v[210:213], v[36:39]
	v_mfma_f32_16x16x32_bf16 v[28:31], v[152:155], v[218:221], v[28:31]
	v_mfma_f32_16x16x32_bf16 v[20:23], v[160:163], v[218:221], v[20:23]
	v_mfma_f32_16x16x32_bf16 v[12:15], v[152:155], v[226:229], v[12:15]
	v_mfma_f32_16x16x32_bf16 v[4:7], v[160:163], v[226:229], v[4:7]
	s_setprio 0
	s_setprio 1
	v_mfma_f32_16x16x32_bf16 v[56:59], v[164:167], v[184:187], v[56:59]
	v_mfma_f32_16x16x32_bf16 v[48:51], v[172:175], v[184:187], v[48:51]
	v_mfma_f32_16x16x32_bf16 v[40:43], v[164:167], v[192:195], v[40:43]
	v_mfma_f32_16x16x32_bf16 v[32:35], v[172:175], v[192:195], v[32:35]
	v_mfma_f32_16x16x32_bf16 v[24:27], v[164:167], v[214:217], v[24:27]
	v_mfma_f32_16x16x32_bf16 v[16:19], v[172:175], v[214:217], v[16:19]
	v_mfma_f32_16x16x32_bf16 v[8:11], v[164:167], v[222:225], v[8:11]
	v_mfma_f32_16x16x32_bf16 v[0:3], v[172:175], v[222:225], v[0:3]
	v_mfma_f32_16x16x32_bf16 v[56:59], v[168:171], v[188:191], v[56:59]
	v_mfma_f32_16x16x32_bf16 v[48:51], v[180:183], v[188:191], v[48:51]
	v_mfma_f32_16x16x32_bf16 v[40:43], v[168:171], v[210:213], v[40:43]
	v_mfma_f32_16x16x32_bf16 v[32:35], v[180:183], v[210:213], v[32:35]
	v_mfma_f32_16x16x32_bf16 v[24:27], v[168:171], v[218:221], v[24:27]
	v_mfma_f32_16x16x32_bf16 v[16:19], v[180:183], v[218:221], v[16:19]
	v_mfma_f32_16x16x32_bf16 v[8:11], v[168:171], v[226:229], v[8:11]
	v_mfma_f32_16x16x32_bf16 v[0:3], v[180:183], v[226:229], v[0:3]
	s_barrier
	s_setprio 0
	s_add_i32 s33, s33, 2
	s_add_u32 s42, s42, 0x100
	s_addc_u32 s43, s43, 0
	s_add_u32 s30, s30, 0x100
	s_addc_u32 s31, s31, 0
	s_cmp_gt_u32 s33, 29
	s_cbranch_scc0 .LBB0_202
	s_and_b64 vcc, exec, s[46:47]
	s_cbranch_vccz .LBB0_205
	s_barrier

; #define PG8_STAGE(bufoff, gbase, voff) do { _Pragma("unroll") for (int _i = 0; _i < 2; ++_i) \
;         __builtin_amdgcn_global_load_lds((const unsigned*)((const char*)(gbase) + (voff)[_i]), (LAS unsigned*)(lds + (bufoff) + ldsw + _i * 8192), 16, 0, 0); } while (0)
; #define PG8_LDA(dst, b, h) do { _Pragma("unroll") for (int m = 0; m < 4; ++m) _Pragma("unroll") for (int k = 0; k < 2; ++k) dst[m][k] = *(const LAS bf16x8*)(lds + PG8_SA(b, h) + aoff + m * 2048 + k * 1024); } while (0)
; #define PG8_LDB(dst, b, h) do { _Pragma("unroll") for (int n = 0; n < 2; ++n) _Pragma("unroll") for (int k = 0; k < 2; ++k) dst[n][k] = *(const LAS bf16x8*)(lds + PG8_SB(b, h) + boff + n * 2048 + k * 1024); } while (0)
; #define PG8_MMA(ai, bj, At, Bt) do { __builtin_amdgcn_s_setprio(1); _Pragma("unroll") for (int m = 0; m < 4; ++m) _Pragma("unroll") for (int n = 0; n < 2; ++n) _Pragma("unroll") for (int k = 0; k < 2; ++k) \
;         acc[ai][bj][m][n] = __builtin_amdgcn_mfma_f32_16x16x32_bf16(Bt[n][k], At[m][k], acc[ai][bj][m][n], 0, 0, 0); __builtin_amdgcn_s_setprio(0); } while (0)
; #define PG8_WAIT_V(n) asm volatile("s_waitcnt vmcnt(" #n ")" ::: "memory")
; #define PG8_WAIT_L(n) asm volatile("s_waitcnt lgkmcnt(" #n ")" ::: "memory")
; #define PG8_BAR __builtin_amdgcn_s_barrier()
; #define PG8_SCHED __builtin_amdgcn_sched_barrier(0)
; template <class Epi>
; __device__ __forceinline__ void gemm_phase(LAS unsigned char* lds, const GemmD g, const Epi& E, int G, int c) {
;     ...
;             const bool last = (t == nt - 2);
;             const char* a1 = cA + (size_t)(t + 1) * kstep;
;             const char* a2 = last ? nA : cA + (size_t)(t + 2) * kstep; const char* b2 = last ? nB : cB + (size_t)(t + 2) * kstep;
;             const char* a3 = a2 + kstep; const char* b3 = b2 + kstep;
;             PG8_LDB(B0, 0, 0); PG8_LDB(B1, 0, 1); PG8_SCHED; PG8_LDA(At, 0, 0); PG8_STAGE(PG8_SA(1, 1), a1 + hstepA, voffA);
;             PG8_WAIT_V(8); PG8_WAIT_L(0); PG8_BAR; PG8_MMA(0, 0, At, B0); PG8_MMA(0, 1, At, B1); PG8_BAR; PG8_SCHED;
;             PG8_LDA(At, 0, 1); PG8_STAGE(PG8_SB(0, 0), b2, voffB); PG8_STAGE(PG8_SB(0, 1), b2 + hstepB, voffB); PG8_STAGE(PG8_SA(0, 0), a2, voffA);
;             PG8_WAIT_V(8); PG8_WAIT_L(0); PG8_BAR; PG8_MMA(1, 0, At, B0); PG8_MMA(1, 1, At, B1); PG8_BAR; PG8_SCHED;
.LBB0_224:
	s_add_u32 s4, s86, 0xfff80080
	s_addc_u32 s5, s87, -1
	s_add_i32 s35, 0, 0x10000
	s_cmp_eq_u32 s33, 28
	s_cselect_b32 s5, s26, s5
	s_cselect_b32 s4, s27, s4
	v_add_u32_e32 v140, s35, v143
	s_cselect_b32 s85, s28, s31
	s_cselect_b32 s84, s29, s30
	s_add_i32 s36, 0, 0x14000
	ds_read_b128 v[148:151], v140
	ds_read_b128 v[152:155], v140 offset:1024
	ds_read_b128 v[156:159], v140 offset:2048
	ds_read_b128 v[160:163], v140 offset:3072
	v_add_u32_e32 v140, s36, v143
	ds_read_b128 v[164:167], v140
	ds_read_b128 v[168:171], v140 offset:1024
	ds_read_b128 v[172:175], v140 offset:2048
	ds_read_b128 v[180:183], v140 offset:3072
	v_lshl_add_u64 v[140:141], s[86:87], 0, v[136:137]
	s_add_i32 m0, s6, 0xc000
	ds_read_b128 v[184:187], v145
	ds_read_b128 v[188:191], v145 offset:1024
	ds_read_b128 v[192:195], v145 offset:2048
	ds_read_b128 v[210:213], v145 offset:3072
	ds_read_b128 v[214:217], v145 offset:4096
	ds_read_b128 v[218:221], v145 offset:5120
	ds_read_b128 v[222:225], v145 offset:6144
	ds_read_b128 v[226:229], v145 offset:7168
	global_load_lds_dwordx4 v[140:141], off
	v_lshl_add_u64 v[140:141], s[86:87], 0, v[138:139]
	s_add_i32 m0, s6, 0xe000
	s_nop 0
	global_load_lds_dwordx4 v[140:141], off
	s_waitcnt vmcnt(8)
	s_waitcnt lgkmcnt(0)
	s_setprio 1
	s_barrier
	v_mfma_f32_16x16x32_bf16 v[124:127], v[148:151], v[184:187], v[124:127]
	v_mfma_f32_16x16x32_bf16 v[120:123], v[156:159], v[184:187], v[120:123]
	v_mfma_f32_16x16x32_bf16 v[108:111], v[148:151], v[192:195], v[108:111]
	v_mfma_f32_16x16x32_bf16 v[104:107], v[156:159], v[192:195], v[104:107]
	v_mfma_f32_16x16x32_bf16 v[92:95], v[148:151], v[214:217], v[92:95]
	v_mfma_f32_16x16x32_bf16 v[88:91], v[156:159], v[214:217], v[88:91]
	v_mfma_f32_16x16x32_bf16 v[76:79], v[148:151], v[222:225], v[76:79]
	v_mfma_f32_16x16x32_bf16 v[72:75], v[156:159], v[222:225], v[72:75]
	v_mfma_f32_16x16x32_bf16 v[124:127], v[152:155], v[188:191], v[124:127]
	v_mfma_f32_16x16x32_bf16 v[120:123], v[160:163], v[188:191], v[120:123]
	v_mfma_f32_16x16x32_bf16 v[108:111], v[152:155], v[210:213], v[108:111]
	v_mfma_f32_16x16x32_bf16 v[104:107], v[160:163], v[210:213], v[104:107]
	v_mfma_f32_16x16x32_bf16 v[92:95], v[152:155], v[218:221], v[92:95]
	v_mfma_f32_16x16x32_bf16 v[88:91], v[160:163], v[218:221], v[88:91]
	v_mfma_f32_16x16x32_bf16 v[76:79], v[152:155], v[226:229], v[76:79]
	v_mfma_f32_16x16x32_bf16 v[72:75], v[160:163], v[226:229], v[72:75]
	s_setprio 0
	s_setprio 1
	s_add_i32 s35, s35, s2
	v_lshl_add_u64 v[140:141], s[84:85], 0, v[178:179]
	s_mov_b32 m0, s35
	v_mfma_f32_16x16x32_bf16 v[116:119], v[164:167], v[184:187], v[116:119]
	v_mfma_f32_16x16x32_bf16 v[112:115], v[172:175], v[184:187], v[112:115]
	v_mfma_f32_16x16x32_bf16 v[100:103], v[164:167], v[192:195], v[100:103]
	v_mfma_f32_16x16x32_bf16 v[96:99], v[172:175], v[192:195], v[96:99]
	v_mfma_f32_16x16x32_bf16 v[84:87], v[164:167], v[214:217], v[84:87]
	v_mfma_f32_16x16x32_bf16 v[80:83], v[172:175], v[214:217], v[80:83]
	v_mfma_f32_16x16x32_bf16 v[68:71], v[164:167], v[222:225], v[68:71]
	v_mfma_f32_16x16x32_bf16 v[64:67], v[172:175], v[222:225], v[64:67]
	v_mfma_f32_16x16x32_bf16 v[116:119], v[168:171], v[188:191], v[116:119]
	v_mfma_f32_16x16x32_bf16 v[112:115], v[180:183], v[188:191], v[112:115]
	v_mfma_f32_16x16x32_bf16 v[100:103], v[168:171], v[210:213], v[100:103]
	v_mfma_f32_16x16x32_bf16 v[96:99], v[180:183], v[210:213], v[96:99]
	v_mfma_f32_16x16x32_bf16 v[84:87], v[168:171], v[218:221], v[84:87]
	v_mfma_f32_16x16x32_bf16 v[80:83], v[180:183], v[218:221], v[80:83]
	v_mfma_f32_16x16x32_bf16 v[68:71], v[168:171], v[226:229], v[68:71]
	v_mfma_f32_16x16x32_bf16 v[64:67], v[180:183], v[226:229], v[64:67]
	s_barrier
	s_setprio 0
	ds_read_b128 v[184:187], v145 offset:16384
	ds_read_b128 v[188:191], v145 offset:17408
	ds_read_b128 v[192:195], v145 offset:18432
	ds_read_b128 v[210:213], v145 offset:19456
	ds_read_b128 v[214:217], v145 offset:20480
	ds_read_b128 v[218:221], v145 offset:21504
	ds_read_b128 v[222:225], v145 offset:22528
	ds_read_b128 v[226:229], v145 offset:23552
	global_load_lds_dwordx4 v[140:141], off
	s_add_i32 m0, s35, 0x2000
	s_add_u32 s38, s84, 0x80000
	v_lshl_add_u64 v[198:199], s[84:85], 0, v[128:129]
	s_addc_u32 s39, s85, 0
	s_add_i32 s35, s36, s2
	global_load_lds_dwordx4 v[198:199], off
	v_lshl_add_u64 v[230:231], s[38:39], 0, v[178:179]
	s_mov_b32 m0, s35
	v_lshl_add_u64 v[232:233], s[4:5], 0, v[130:131]
	global_load_lds_dwordx4 v[230:231], off
	v_lshl_add_u64 v[230:231], s[38:39], 0, v[128:129]
	s_add_i32 m0, s35, 0x2000
	s_nop 0
	global_load_lds_dwordx4 v[230:231], off
	v_lshl_add_u64 v[230:231], s[4:5], 0, v[132:133]
	s_mov_b32 m0, s6
	s_nop 0
	global_load_lds_dwordx4 v[230:231], off
	s_mov_b32 m0, s9
	s_nop 0
	global_load_lds_dwordx4 v[232:233], off
	s_waitcnt vmcnt(8)
	s_waitcnt lgkmcnt(0)
	s_setprio 1
	s_barrier
; #define PG8_STAGE(bufoff, gbase, voff) do { _Pragma("unroll") for (int _i = 0; _i < 2; ++_i) \
;         __builtin_amdgcn_global_load_lds((const unsigned*)((const char*)(gbase) + (voff)[_i]), (LAS unsigned*)(lds + (bufoff) + ldsw + _i * 8192), 16, 0, 0); } while (0)
; #define PG8_LDA(dst, b, h) do { _Pragma("unroll") for (int m = 0; m < 4; ++m) _Pragma("unroll") for (int k = 0; k < 2; ++k) dst[m][k] = *(const LAS bf16x8*)(lds + PG8_SA(b, h) + aoff + m * 2048 + k * 1024); } while (0)
; #define PG8_LDB(dst, b, h) do { _Pragma("unroll") for (int n = 0; n < 2; ++n) _Pragma("unroll") for (int k = 0; k < 2; ++k) dst[n][k] = *(const LAS bf16x8*)(lds + PG8_SB(b, h) + boff + n * 2048 + k * 1024); } while (0)
; #define PG8_MMA(ai, bj, At, Bt) do { __builtin_amdgcn_s_setprio(1); _Pragma("unroll") for (int m = 0; m < 4; ++m) _Pragma("unroll") for (int n = 0; n < 2; ++n) _Pragma("unroll") for (int k = 0; k < 2; ++k) \
;         acc[ai][bj][m][n] = __builtin_amdgcn_mfma_f32_16x16x32_bf16(Bt[n][k], At[m][k], acc[ai][bj][m][n], 0, 0, 0); __builtin_amdgcn_s_setprio(0); } while (0)
; #define PG8_WAIT_V(n) asm volatile("s_waitcnt vmcnt(" #n ")" ::: "memory")
; #define PG8_WAIT_L(n) asm volatile("s_waitcnt lgkmcnt(" #n ")" ::: "memory")
; #define PG8_BAR __builtin_amdgcn_s_barrier()
; #define PG8_SCHED __builtin_amdgcn_sched_barrier(0)
; template <class Epi>
; __device__ __forceinline__ void gemm_phase(LAS unsigned char* lds, const GemmD g, const Epi& E, int G, int c) {
;     ...
;             PG8_WAIT_V(8); PG8_WAIT_L(0); PG8_BAR; PG8_MMA(1, 0, At, B0); PG8_MMA(1, 1, At, B1); PG8_BAR; PG8_SCHED;
;             PG8_LDB(B0, 1, 0); PG8_LDB(B1, 1, 1); PG8_SCHED; PG8_LDA(At, 1, 0); PG8_STAGE(PG8_SA(0, 1), a2 + hstepA, voffA);
;             PG8_WAIT_V(8); PG8_WAIT_L(0); PG8_BAR; PG8_MMA(0, 0, At, B0); PG8_MMA(0, 1, At, B1); PG8_BAR; PG8_SCHED;
	v_mfma_f32_16x16x32_bf16 v[56:59], v[148:151], v[184:187], v[56:59]
	v_mfma_f32_16x16x32_bf16 v[60:63], v[156:159], v[184:187], v[60:63]
	v_mfma_f32_16x16x32_bf16 v[40:43], v[148:151], v[192:195], v[40:43]
	v_mfma_f32_16x16x32_bf16 v[36:39], v[156:159], v[192:195], v[36:39]
	v_mfma_f32_16x16x32_bf16 v[28:31], v[148:151], v[214:217], v[28:31]
	v_mfma_f32_16x16x32_bf16 v[24:27], v[156:159], v[214:217], v[24:27]
	v_mfma_f32_16x16x32_bf16 v[12:15], v[148:151], v[222:225], v[12:15]
	v_mfma_f32_16x16x32_bf16 v[8:11], v[156:159], v[222:225], v[8:11]
	v_mfma_f32_16x16x32_bf16 v[56:59], v[152:155], v[188:191], v[56:59]
	v_mfma_f32_16x16x32_bf16 v[60:63], v[160:163], v[188:191], v[60:63]
	v_mfma_f32_16x16x32_bf16 v[40:43], v[152:155], v[210:213], v[40:43]
	v_mfma_f32_16x16x32_bf16 v[36:39], v[160:163], v[210:213], v[36:39]
	v_mfma_f32_16x16x32_bf16 v[28:31], v[152:155], v[218:221], v[28:31]
	v_mfma_f32_16x16x32_bf16 v[24:27], v[160:163], v[218:221], v[24:27]
	v_mfma_f32_16x16x32_bf16 v[12:15], v[152:155], v[226:229], v[12:15]
	v_mfma_f32_16x16x32_bf16 v[8:11], v[160:163], v[226:229], v[8:11]
	s_setprio 0
	s_setprio 1
	s_add_i32 s35, 0, 0x18000
	v_add_u32_e32 v147, s35, v143
	s_add_i32 s36, 0, 0x1c000
	v_mfma_f32_16x16x32_bf16 v[52:55], v[164:167], v[184:187], v[52:55]
	v_mfma_f32_16x16x32_bf16 v[48:51], v[172:175], v[184:187], v[48:51]
	v_mfma_f32_16x16x32_bf16 v[44:47], v[164:167], v[192:195], v[44:47]
	v_mfma_f32_16x16x32_bf16 v[32:35], v[172:175], v[192:195], v[32:35]
	v_mfma_f32_16x16x32_bf16 v[20:23], v[164:167], v[214:217], v[20:23]
	v_mfma_f32_16x16x32_bf16 v[16:19], v[172:175], v[214:217], v[16:19]
	v_mfma_f32_16x16x32_bf16 v[4:7], v[164:167], v[222:225], v[4:7]
	v_mfma_f32_16x16x32_bf16 v[0:3], v[172:175], v[222:225], v[0:3]
	v_mfma_f32_16x16x32_bf16 v[52:55], v[168:171], v[188:191], v[52:55]
	v_mfma_f32_16x16x32_bf16 v[48:51], v[180:183], v[188:191], v[48:51]
	v_mfma_f32_16x16x32_bf16 v[44:47], v[168:171], v[210:213], v[44:47]
	v_mfma_f32_16x16x32_bf16 v[32:35], v[180:183], v[210:213], v[32:35]
	v_mfma_f32_16x16x32_bf16 v[20:23], v[168:171], v[218:221], v[20:23]
	v_mfma_f32_16x16x32_bf16 v[16:19], v[180:183], v[218:221], v[16:19]
	v_mfma_f32_16x16x32_bf16 v[4:7], v[168:171], v[226:229], v[4:7]
	v_mfma_f32_16x16x32_bf16 v[0:3], v[180:183], v[226:229], v[0:3]
	s_barrier
	s_setprio 0
	ds_read_b128 v[148:151], v147
	ds_read_b128 v[152:155], v147 offset:1024
	ds_read_b128 v[156:159], v147 offset:2048
	ds_read_b128 v[160:163], v147 offset:3072
	v_add_u32_e32 v147, s36, v143
	ds_read_b128 v[164:167], v147
	ds_read_b128 v[168:171], v147 offset:1024
	ds_read_b128 v[172:175], v147 offset:2048
	ds_read_b128 v[180:183], v147 offset:3072
	s_add_u32 s4, s4, 0x80000
	s_addc_u32 s5, s5, 0
	s_mov_b32 m0, s10
	v_lshl_add_u64 v[234:235], s[4:5], 0, v[132:133]
	ds_read_b128 v[184:187], v145 offset:32768
	ds_read_b128 v[188:191], v145 offset:33792
	ds_read_b128 v[192:195], v145 offset:34816
	ds_read_b128 v[210:213], v145 offset:35840
	ds_read_b128 v[214:217], v145 offset:36864
	ds_read_b128 v[218:221], v145 offset:37888
	ds_read_b128 v[222:225], v145 offset:38912
	ds_read_b128 v[226:229], v145 offset:39936
	global_load_lds_dwordx4 v[234:235], off
	v_lshl_add_u64 v[234:235], s[4:5], 0, v[130:131]
	s_mov_b32 m0, s11
	s_nop 0
	global_load_lds_dwordx4 v[234:235], off
	s_waitcnt vmcnt(8)
	s_waitcnt lgkmcnt(0)
	s_setprio 1
	s_barrier
	v_mfma_f32_16x16x32_bf16 v[124:127], v[148:151], v[184:187], v[124:127]
	v_mfma_f32_16x16x32_bf16 v[120:123], v[156:159], v[184:187], v[120:123]
	v_mfma_f32_16x16x32_bf16 v[108:111], v[148:151], v[192:195], v[108:111]
	v_mfma_f32_16x16x32_bf16 v[104:107], v[156:159], v[192:195], v[104:107]
	v_mfma_f32_16x16x32_bf16 v[92:95], v[148:151], v[214:217], v[92:95]
	v_mfma_f32_16x16x32_bf16 v[88:91], v[156:159], v[214:217], v[88:91]
	v_mfma_f32_16x16x32_bf16 v[76:79], v[148:151], v[222:225], v[76:79]
	v_mfma_f32_16x16x32_bf16 v[72:75], v[156:159], v[222:225], v[72:75]
	v_mfma_f32_16x16x32_bf16 v[124:127], v[152:155], v[188:191], v[124:127]
	v_mfma_f32_16x16x32_bf16 v[120:123], v[160:163], v[188:191], v[120:123]
	v_mfma_f32_16x16x32_bf16 v[108:111], v[152:155], v[210:213], v[108:111]
	v_mfma_f32_16x16x32_bf16 v[104:107], v[160:163], v[210:213], v[104:107]
	v_mfma_f32_16x16x32_bf16 v[92:95], v[152:155], v[218:221], v[92:95]
	v_mfma_f32_16x16x32_bf16 v[88:91], v[160:163], v[218:221], v[88:91]
	v_mfma_f32_16x16x32_bf16 v[76:79], v[152:155], v[226:229], v[76:79]
	v_mfma_f32_16x16x32_bf16 v[72:75], v[160:163], v[226:229], v[72:75]
	s_setprio 0
	s_setprio 1
	s_add_i32 s4, s35, s2
	v_lshl_add_u64 v[140:141], v[140:141], 0, s[48:49]
	s_mov_b32 m0, s4
	v_mfma_f32_16x16x32_bf16 v[116:119], v[164:167], v[184:187], v[116:119]
	v_mfma_f32_16x16x32_bf16 v[112:115], v[172:175], v[184:187], v[112:115]
	v_mfma_f32_16x16x32_bf16 v[100:103], v[164:167], v[192:195], v[100:103]
	v_mfma_f32_16x16x32_bf16 v[96:99], v[172:175], v[192:195], v[96:99]
	v_mfma_f32_16x16x32_bf16 v[84:87], v[164:167], v[214:217], v[84:87]
	v_mfma_f32_16x16x32_bf16 v[80:83], v[172:175], v[214:217], v[80:83]
	v_mfma_f32_16x16x32_bf16 v[68:71], v[164:167], v[222:225], v[68:71]
	v_mfma_f32_16x16x32_bf16 v[64:67], v[172:175], v[222:225], v[64:67]
	v_mfma_f32_16x16x32_bf16 v[116:119], v[168:171], v[188:191], v[116:119]
	v_mfma_f32_16x16x32_bf16 v[112:115], v[180:183], v[188:191], v[112:115]
	v_mfma_f32_16x16x32_bf16 v[100:103], v[168:171], v[210:213], v[100:103]
	v_mfma_f32_16x16x32_bf16 v[96:99], v[180:183], v[210:213], v[96:99]
	v_mfma_f32_16x16x32_bf16 v[84:87], v[168:171], v[218:221], v[84:87]
	v_mfma_f32_16x16x32_bf16 v[80:83], v[180:183], v[218:221], v[80:83]
	v_mfma_f32_16x16x32_bf16 v[68:71], v[168:171], v[226:229], v[68:71]
	v_mfma_f32_16x16x32_bf16 v[64:67], v[180:183], v[226:229], v[64:67]
	s_barrier
; #define PG8_STAGE(bufoff, gbase, voff) do { _Pragma("unroll") for (int _i = 0; _i < 2; ++_i) \
;         __builtin_amdgcn_global_load_lds((const unsigned*)((const char*)(gbase) + (voff)[_i]), (LAS unsigned*)(lds + (bufoff) + ldsw + _i * 8192), 16, 0, 0); } while (0)
; #define PG8_LDA(dst, b, h) do { _Pragma("unroll") for (int m = 0; m < 4; ++m) _Pragma("unroll") for (int k = 0; k < 2; ++k) dst[m][k] = *(const LAS bf16x8*)(lds + PG8_SA(b, h) + aoff + m * 2048 + k * 1024); } while (0)
; #define PG8_MMA(ai, bj, At, Bt) do { __builtin_amdgcn_s_setprio(1); _Pragma("unroll") for (int m = 0; m < 4; ++m) _Pragma("unroll") for (int n = 0; n < 2; ++n) _Pragma("unroll") for (int k = 0; k < 2; ++k) \
;         acc[ai][bj][m][n] = __builtin_amdgcn_mfma_f32_16x16x32_bf16(Bt[n][k], At[m][k], acc[ai][bj][m][n], 0, 0, 0); __builtin_amdgcn_s_setprio(0); } while (0)
; #define PG8_WAIT_V(n) asm volatile("s_waitcnt vmcnt(" #n ")" ::: "memory")
; #define PG8_WAIT_L(n) asm volatile("s_waitcnt lgkmcnt(" #n ")" ::: "memory")
; #define PG8_BAR __builtin_amdgcn_s_barrier()
; #define PG8_SCHED __builtin_amdgcn_sched_barrier(0)
; template <class Epi>
; __device__ __forceinline__ void gemm_phase(LAS unsigned char* lds, const GemmD g, const Epi& E, int G, int c) {
;     ...
;             PG8_LDA(At, 1, 1); PG8_STAGE(PG8_SB(1, 0), b3, voffB); PG8_STAGE(PG8_SB(1, 1), b3 + hstepB, voffB); PG8_STAGE(PG8_SA(1, 0), a3, voffA);
;             PG8_WAIT_V(8); PG8_WAIT_L(0); PG8_BAR; PG8_MMA(1, 0, At, B0); PG8_MMA(1, 1, At, B1); PG8_BAR; PG8_SCHED;
;         }
;         if (wr == 0) PG8_BAR;
	s_setprio 0
	ds_read_b128 v[184:187], v145 offset:49152
	ds_read_b128 v[188:191], v145 offset:50176
	ds_read_b128 v[192:195], v145 offset:51200
	ds_read_b128 v[210:213], v145 offset:52224
	ds_read_b128 v[214:217], v145 offset:53248
	ds_read_b128 v[218:221], v145 offset:54272
	ds_read_b128 v[222:225], v145 offset:55296
	ds_read_b128 v[226:229], v145 offset:56320
	global_load_lds_dwordx4 v[140:141], off
	s_add_i32 m0, s4, 0x2000
	s_add_u32 s4, s84, 0x80080
	v_lshl_add_u64 v[140:141], v[198:199], 0, s[48:49]
	s_addc_u32 s5, s85, 0
	s_add_i32 s35, s36, s2
	global_load_lds_dwordx4 v[140:141], off
	v_lshl_add_u64 v[140:141], s[4:5], 0, v[178:179]
	s_mov_b32 m0, s35
	s_nop 0
	global_load_lds_dwordx4 v[140:141], off
	v_lshl_add_u64 v[140:141], s[4:5], 0, v[128:129]
	s_add_i32 m0, s35, 0x2000
	s_nop 0
	global_load_lds_dwordx4 v[140:141], off
	v_lshl_add_u64 v[140:141], v[230:231], 0, s[48:49]
	s_mov_b32 m0, s16
	s_nop 0
	global_load_lds_dwordx4 v[140:141], off
	v_lshl_add_u64 v[140:141], v[232:233], 0, s[48:49]
	s_mov_b32 m0, s17
	s_nop 0
	global_load_lds_dwordx4 v[140:141], off
	s_waitcnt vmcnt(8)
	s_waitcnt lgkmcnt(0)
	s_setprio 1
	s_barrier
	v_mfma_f32_16x16x32_bf16 v[56:59], v[148:151], v[184:187], v[56:59]
	v_mfma_f32_16x16x32_bf16 v[60:63], v[156:159], v[184:187], v[60:63]
	v_mfma_f32_16x16x32_bf16 v[40:43], v[148:151], v[192:195], v[40:43]
	v_mfma_f32_16x16x32_bf16 v[36:39], v[156:159], v[192:195], v[36:39]
	v_mfma_f32_16x16x32_bf16 v[28:31], v[148:151], v[214:217], v[28:31]
	v_mfma_f32_16x16x32_bf16 v[24:27], v[156:159], v[214:217], v[24:27]
	v_mfma_f32_16x16x32_bf16 v[12:15], v[148:151], v[222:225], v[12:15]
	v_mfma_f32_16x16x32_bf16 v[8:11], v[156:159], v[222:225], v[8:11]
	v_mfma_f32_16x16x32_bf16 v[56:59], v[152:155], v[188:191], v[56:59]
	v_mfma_f32_16x16x32_bf16 v[60:63], v[160:163], v[188:191], v[60:63]
	v_mfma_f32_16x16x32_bf16 v[40:43], v[152:155], v[210:213], v[40:43]
	v_mfma_f32_16x16x32_bf16 v[36:39], v[160:163], v[210:213], v[36:39]
	v_mfma_f32_16x16x32_bf16 v[28:31], v[152:155], v[218:221], v[28:31]
	v_mfma_f32_16x16x32_bf16 v[24:27], v[160:163], v[218:221], v[24:27]
	v_mfma_f32_16x16x32_bf16 v[12:15], v[152:155], v[226:229], v[12:15]
	v_mfma_f32_16x16x32_bf16 v[8:11], v[160:163], v[226:229], v[8:11]
	s_setprio 0
	s_setprio 1
	v_mfma_f32_16x16x32_bf16 v[52:55], v[164:167], v[184:187], v[52:55]
	v_mfma_f32_16x16x32_bf16 v[48:51], v[172:175], v[184:187], v[48:51]
	v_mfma_f32_16x16x32_bf16 v[44:47], v[164:167], v[192:195], v[44:47]
	v_mfma_f32_16x16x32_bf16 v[32:35], v[172:175], v[192:195], v[32:35]
	v_mfma_f32_16x16x32_bf16 v[20:23], v[164:167], v[214:217], v[20:23]
	v_mfma_f32_16x16x32_bf16 v[16:19], v[172:175], v[214:217], v[16:19]
	v_mfma_f32_16x16x32_bf16 v[4:7], v[164:167], v[222:225], v[4:7]
	v_mfma_f32_16x16x32_bf16 v[0:3], v[172:175], v[222:225], v[0:3]
	v_mfma_f32_16x16x32_bf16 v[52:55], v[168:171], v[188:191], v[52:55]
	v_mfma_f32_16x16x32_bf16 v[48:51], v[180:183], v[188:191], v[48:51]
	v_mfma_f32_16x16x32_bf16 v[44:47], v[168:171], v[210:213], v[44:47]
	v_mfma_f32_16x16x32_bf16 v[32:35], v[180:183], v[210:213], v[32:35]
	v_mfma_f32_16x16x32_bf16 v[20:23], v[168:171], v[218:221], v[20:23]
	v_mfma_f32_16x16x32_bf16 v[16:19], v[180:183], v[218:221], v[16:19]
	v_mfma_f32_16x16x32_bf16 v[4:7], v[168:171], v[226:229], v[4:7]
	v_mfma_f32_16x16x32_bf16 v[0:3], v[180:183], v[226:229], v[0:3]
	s_barrier
	s_setprio 0
	s_add_i32 s33, s33, 2
	s_add_u32 s86, s86, 0x100
	s_addc_u32 s87, s87, 0
	s_add_u32 s30, s30, 0x100
	s_addc_u32 s31, s31, 0
	s_cmp_gt_u32 s33, 29
	s_cbranch_scc0 .LBB0_224
	s_and_b64 vcc, exec, s[46:47]
	s_cbranch_vccz .LBB0_227
	s_barrier

; #define PG8_STAGE(bufoff, gbase, voff) do { _Pragma("unroll") for (int _i = 0; _i < 2; ++_i) \
;         __builtin_amdgcn_global_load_lds((const unsigned*)((const char*)(gbase) + (voff)[_i]), (LAS unsigned*)(lds + (bufoff) + ldsw + _i * 8192), 16, 0, 0); } while (0)
; #define PG8_LDA(dst, b, h) do { _Pragma("unroll") for (int m = 0; m < 4; ++m) _Pragma("unroll") for (int k = 0; k < 2; ++k) dst[m][k] = *(const LAS bf16x8*)(lds + PG8_SA(b, h) + aoff + m * 2048 + k * 1024); } while (0)
; #define PG8_MMA(ai, bj, At, Bt) do { __builtin_amdgcn_s_setprio(1); _Pragma("unroll") for (int m = 0; m < 4; ++m) _Pragma("unroll") for (int n = 0; n < 2; ++n) _Pragma("unroll") for (int k = 0; k < 2; ++k) \
;         acc[ai][bj][m][n] = __builtin_amdgcn_mfma_f32_16x16x32_bf16(Bt[n][k], At[m][k], acc[ai][bj][m][n], 0, 0, 0); __builtin_amdgcn_s_setprio(0); } while (0)
; #define PG8_WAIT_V(n) asm volatile("s_waitcnt vmcnt(" #n ")" ::: "memory")
; #define PG8_WAIT_L(n) asm volatile("s_waitcnt lgkmcnt(" #n ")" ::: "memory")
; #define PG8_BAR __builtin_amdgcn_s_barrier()
; #define PG8_SCHED __builtin_amdgcn_sched_barrier(0)
; template <class Epi>
; __device__ __forceinline__ void gemm_phase(LAS unsigned char* lds, const GemmD g, const Epi& E, int G, int c) {
;     ...
;             PG8_WAIT_V(8); PG8_WAIT_L(0); PG8_BAR; PG8_MMA(0, 0, At, B0); PG8_MMA(0, 1, At, B1); PG8_BAR; PG8_SCHED;
;             PG8_LDA(At, 0, 1); PG8_STAGE(PG8_SB(0, 0), b2, voffB); PG8_STAGE(PG8_SB(0, 1), b2 + hstepB, voffB); PG8_STAGE(PG8_SA(0, 0), a2, voffA);
.Lrw_Glu_0_d:
	s_waitcnt lgkmcnt(0)
	s_setprio 1
	s_barrier
	v_mfma_f32_16x16x32_bf16 v[140:143], v[24:27], v[160:163], v[140:143]
	v_mfma_f32_16x16x32_bf16 v[136:139], v[36:39], v[160:163], v[136:139]
	v_mfma_f32_16x16x32_bf16 v[124:127], v[24:27], v[168:171], v[124:127]
	v_mfma_f32_16x16x32_bf16 v[120:123], v[36:39], v[168:171], v[120:123]
	v_mfma_f32_16x16x32_bf16 v[108:111], v[24:27], v[190:193], v[108:111]
	v_mfma_f32_16x16x32_bf16 v[104:107], v[36:39], v[190:193], v[104:107]
	v_mfma_f32_16x16x32_bf16 v[92:95], v[24:27], v[218:221], v[92:95]
	v_mfma_f32_16x16x32_bf16 v[88:91], v[36:39], v[218:221], v[88:91]
	v_mfma_f32_16x16x32_bf16 v[140:143], v[28:31], v[164:167], v[140:143]
	v_mfma_f32_16x16x32_bf16 v[136:139], v[44:47], v[164:167], v[136:139]
	v_mfma_f32_16x16x32_bf16 v[124:127], v[28:31], v[172:175], v[124:127]
	v_mfma_f32_16x16x32_bf16 v[120:123], v[44:47], v[172:175], v[120:123]
	v_mfma_f32_16x16x32_bf16 v[108:111], v[28:31], v[214:217], v[108:111]
	v_mfma_f32_16x16x32_bf16 v[104:107], v[44:47], v[214:217], v[104:107]
	v_mfma_f32_16x16x32_bf16 v[92:95], v[28:31], v[222:225], v[92:95]
	v_mfma_f32_16x16x32_bf16 v[88:91], v[44:47], v[222:225], v[88:91]
	s_setprio 0
	s_setprio 1
	s_add_i32 s28, s28, s16
	v_lshl_add_u64 v[194:195], s[88:89], 0, v[178:179]
	s_mov_b32 m0, s28
	v_mfma_f32_16x16x32_bf16 v[132:135], v[144:147], v[160:163], v[132:135]
	v_mfma_f32_16x16x32_bf16 v[128:131], v[152:155], v[160:163], v[128:131]
	v_mfma_f32_16x16x32_bf16 v[116:119], v[144:147], v[168:171], v[116:119]
	v_mfma_f32_16x16x32_bf16 v[112:115], v[152:155], v[168:171], v[112:115]
	v_mfma_f32_16x16x32_bf16 v[100:103], v[144:147], v[190:193], v[100:103]
	v_mfma_f32_16x16x32_bf16 v[96:99], v[152:155], v[190:193], v[96:99]
	v_mfma_f32_16x16x32_bf16 v[84:87], v[144:147], v[218:221], v[84:87]
	v_mfma_f32_16x16x32_bf16 v[80:83], v[152:155], v[218:221], v[80:83]
	v_mfma_f32_16x16x32_bf16 v[132:135], v[148:151], v[164:167], v[132:135]
	v_mfma_f32_16x16x32_bf16 v[128:131], v[156:159], v[164:167], v[128:131]
	v_mfma_f32_16x16x32_bf16 v[116:119], v[148:151], v[172:175], v[116:119]
	v_mfma_f32_16x16x32_bf16 v[112:115], v[156:159], v[172:175], v[112:115]
	v_mfma_f32_16x16x32_bf16 v[100:103], v[148:151], v[214:217], v[100:103]
	v_mfma_f32_16x16x32_bf16 v[96:99], v[156:159], v[214:217], v[96:99]
	v_mfma_f32_16x16x32_bf16 v[84:87], v[148:151], v[222:225], v[84:87]
	v_mfma_f32_16x16x32_bf16 v[80:83], v[156:159], v[222:225], v[80:83]
	s_barrier
	s_setprio 0
	ds_read_b128 v[160:163], v212 offset:16384
	ds_read_b128 v[164:167], v212 offset:17408
	ds_read_b128 v[168:171], v212 offset:18432
	ds_read_b128 v[172:175], v212 offset:19456
	ds_read_b128 v[190:193], v212 offset:20480
	ds_read_b128 v[214:217], v212 offset:21504
	ds_read_b128 v[218:221], v212 offset:22528
	ds_read_b128 v[222:225], v212 offset:23552
	global_load_lds_dwordx4 v[194:195], off
	s_add_i32 m0, s28, 0x2000
	s_add_u32 s28, s88, 0x80000
	v_lshl_add_u64 v[198:199], s[88:89], 0, v[180:181]
	s_addc_u32 s29, s89, 0
	s_add_i32 s31, s31, s16
	global_load_lds_dwordx4 v[198:199], off
	v_lshl_add_u64 v[226:227], s[28:29], 0, v[178:179]
	s_mov_b32 m0, s31
	v_lshl_add_u64 v[228:229], s[4:5], 0, v[182:183]
	global_load_lds_dwordx4 v[226:227], off
	v_lshl_add_u64 v[226:227], s[28:29], 0, v[180:181]
	s_add_i32 m0, s31, 0x2000
	s_nop 0
	global_load_lds_dwordx4 v[226:227], off
	v_lshl_add_u64 v[226:227], s[4:5], 0, v[184:185]
	s_mov_b32 m0, s23
	s_nop 0
	global_load_lds_dwordx4 v[226:227], off
	s_mov_b32 m0, s26
	s_nop 0
	global_load_lds_dwordx4 v[228:229], off
	s_cmp_lg_u32 s99, 0
	s_cbranch_scc1 .Lrw_Glu_1_r
	s_waitcnt vmcnt(8)
	s_branch .Lrw_Glu_1_d

; #define PG8_STAGE(bufoff, gbase, voff) do { _Pragma("unroll") for (int _i = 0; _i < 2; ++_i) \
;         __builtin_amdgcn_global_load_lds((const unsigned*)((const char*)(gbase) + (voff)[_i]), (LAS unsigned*)(lds + (bufoff) + ldsw + _i * 8192), 16, 0, 0); } while (0)
; #define PG8_LDA(dst, b, h) do { _Pragma("unroll") for (int m = 0; m < 4; ++m) _Pragma("unroll") for (int k = 0; k < 2; ++k) dst[m][k] = *(const LAS bf16x8*)(lds + PG8_SA(b, h) + aoff + m * 2048 + k * 1024); } while (0)
; #define PG8_LDB(dst, b, h) do { _Pragma("unroll") for (int n = 0; n < 2; ++n) _Pragma("unroll") for (int k = 0; k < 2; ++k) dst[n][k] = *(const LAS bf16x8*)(lds + PG8_SB(b, h) + boff + n * 2048 + k * 1024); } while (0)
; #define PG8_MMA(ai, bj, At, Bt) do { __builtin_amdgcn_s_setprio(1); _Pragma("unroll") for (int m = 0; m < 4; ++m) _Pragma("unroll") for (int n = 0; n < 2; ++n) _Pragma("unroll") for (int k = 0; k < 2; ++k) \
;         acc[ai][bj][m][n] = __builtin_amdgcn_mfma_f32_16x16x32_bf16(Bt[n][k], At[m][k], acc[ai][bj][m][n], 0, 0, 0); __builtin_amdgcn_s_setprio(0); } while (0)
; #define PG8_WAIT_V(n) asm volatile("s_waitcnt vmcnt(" #n ")" ::: "memory")
; #define PG8_WAIT_L(n) asm volatile("s_waitcnt lgkmcnt(" #n ")" ::: "memory")
; #define PG8_BAR __builtin_amdgcn_s_barrier()
; #define PG8_SCHED __builtin_amdgcn_sched_barrier(0)
; template <class Epi>
; __device__ __forceinline__ void gemm_phase(LAS unsigned char* lds, const GemmD g, const Epi& E, int G, int c) {
;     ...
;             PG8_WAIT_V(8); PG8_WAIT_L(0); PG8_BAR; PG8_MMA(1, 0, At, B0); PG8_MMA(1, 1, At, B1); PG8_BAR; PG8_SCHED;
;             PG8_LDB(B0, 1, 0); PG8_LDB(B1, 1, 1); PG8_SCHED; PG8_LDA(At, 1, 0); PG8_STAGE(PG8_SA(0, 1), a2 + hstepA, voffA);
;             PG8_WAIT_V(8); PG8_WAIT_L(0); PG8_BAR; PG8_MMA(0, 0, At, B0); PG8_MMA(0, 1, At, B1); PG8_BAR; PG8_SCHED;
.Lrw_Glu_1_d:
	s_waitcnt lgkmcnt(0)
	s_setprio 1
	s_barrier
	v_mfma_f32_16x16x32_bf16 v[76:79], v[24:27], v[160:163], v[76:79]
	v_mfma_f32_16x16x32_bf16 v[72:75], v[36:39], v[160:163], v[72:75]
	v_mfma_f32_16x16x32_bf16 v[60:63], v[24:27], v[168:171], v[60:63]
	v_mfma_f32_16x16x32_bf16 v[56:59], v[36:39], v[168:171], v[56:59]
	v_mfma_f32_16x16x32_bf16 v[40:43], v[24:27], v[190:193], v[40:43]
	v_mfma_f32_16x16x32_bf16 v[32:35], v[36:39], v[190:193], v[32:35]
	v_mfma_f32_16x16x32_bf16 v[12:15], v[24:27], v[218:221], v[12:15]
	v_mfma_f32_16x16x32_bf16 v[8:11], v[36:39], v[218:221], v[8:11]
	v_mfma_f32_16x16x32_bf16 v[76:79], v[28:31], v[164:167], v[76:79]
	v_mfma_f32_16x16x32_bf16 v[72:75], v[44:47], v[164:167], v[72:75]
	v_mfma_f32_16x16x32_bf16 v[60:63], v[28:31], v[172:175], v[60:63]
	v_mfma_f32_16x16x32_bf16 v[56:59], v[44:47], v[172:175], v[56:59]
	v_mfma_f32_16x16x32_bf16 v[40:43], v[28:31], v[214:217], v[40:43]
	v_mfma_f32_16x16x32_bf16 v[32:35], v[44:47], v[214:217], v[32:35]
	v_mfma_f32_16x16x32_bf16 v[12:15], v[28:31], v[222:225], v[12:15]
	v_mfma_f32_16x16x32_bf16 v[8:11], v[44:47], v[222:225], v[8:11]
	s_setprio 0
	s_setprio 1
	v_mfma_f32_16x16x32_bf16 v[20:23], v[144:147], v[190:193], v[20:23]
	v_mfma_f32_16x16x32_bf16 v[16:19], v[152:155], v[190:193], v[16:19]
	v_mfma_f32_16x16x32_bf16 v[4:7], v[144:147], v[218:221], v[4:7]
	v_mfma_f32_16x16x32_bf16 v[0:3], v[152:155], v[218:221], v[0:3]
	v_mfma_f32_16x16x32_bf16 v[24:27], v[144:147], v[160:163], v[68:71]
	v_mfma_f32_16x16x32_bf16 v[28:31], v[152:155], v[160:163], v[64:67]
	v_mfma_f32_16x16x32_bf16 v[36:39], v[144:147], v[168:171], v[52:55]
	v_mfma_f32_16x16x32_bf16 v[44:47], v[152:155], v[168:171], v[48:51]
	v_mfma_f32_16x16x32_bf16 v[20:23], v[148:151], v[214:217], v[20:23]
	v_mfma_f32_16x16x32_bf16 v[16:19], v[156:159], v[214:217], v[16:19]
	v_mfma_f32_16x16x32_bf16 v[4:7], v[148:151], v[222:225], v[4:7]
	v_mfma_f32_16x16x32_bf16 v[0:3], v[156:159], v[222:225], v[0:3]
	v_mfma_f32_16x16x32_bf16 v[24:27], v[148:151], v[164:167], v[24:27]
	v_mfma_f32_16x16x32_bf16 v[28:31], v[156:159], v[164:167], v[28:31]
	v_mfma_f32_16x16x32_bf16 v[36:39], v[148:151], v[172:175], v[36:39]
	v_mfma_f32_16x16x32_bf16 v[44:47], v[156:159], v[172:175], v[44:47]
	s_barrier
	s_setprio 0
	s_add_i32 s28, 0, 0x18000
	s_add_i32 s29, 0, 0x1c000
	v_add_u32_e32 v68, s28, v210
	v_add_u32_e32 v156, s29, v210
	ds_read_b128 v[48:51], v68
	ds_read_b128 v[52:55], v68 offset:1024
	ds_read_b128 v[64:67], v68 offset:2048
	ds_read_b128 v[68:71], v68 offset:3072
	ds_read_b128 v[144:147], v156
	ds_read_b128 v[148:151], v156 offset:1024
	ds_read_b128 v[152:155], v156 offset:2048
	ds_read_b128 v[156:159], v156 offset:3072
	s_add_u32 s4, s4, 0x80000
	s_addc_u32 s5, s5, 0
	s_mov_b32 m0, s30
	v_lshl_add_u64 v[230:231], s[4:5], 0, v[184:185]
	ds_read_b128 v[160:163], v212 offset:32768
	ds_read_b128 v[164:167], v212 offset:33792
	ds_read_b128 v[168:171], v212 offset:34816
	ds_read_b128 v[172:175], v212 offset:35840
	ds_read_b128 v[190:193], v212 offset:36864
	ds_read_b128 v[214:217], v212 offset:37888
	ds_read_b128 v[218:221], v212 offset:38912
	ds_read_b128 v[222:225], v212 offset:39936
	global_load_lds_dwordx4 v[230:231], off
	v_lshl_add_u64 v[230:231], s[4:5], 0, v[182:183]
	s_mov_b32 m0, s35
	s_nop 0
	global_load_lds_dwordx4 v[230:231], off
	s_waitcnt vmcnt(8)
	s_waitcnt lgkmcnt(0)
	s_setprio 1
	s_barrier
	v_mfma_f32_16x16x32_bf16 v[140:143], v[48:51], v[160:163], v[140:143]
	v_mfma_f32_16x16x32_bf16 v[136:139], v[64:67], v[160:163], v[136:139]
	v_mfma_f32_16x16x32_bf16 v[124:127], v[48:51], v[168:171], v[124:127]
	v_mfma_f32_16x16x32_bf16 v[120:123], v[64:67], v[168:171], v[120:123]
	v_mfma_f32_16x16x32_bf16 v[108:111], v[48:51], v[190:193], v[108:111]
	v_mfma_f32_16x16x32_bf16 v[104:107], v[64:67], v[190:193], v[104:107]
	v_mfma_f32_16x16x32_bf16 v[92:95], v[48:51], v[218:221], v[92:95]
	v_mfma_f32_16x16x32_bf16 v[88:91], v[64:67], v[218:221], v[88:91]
	v_mfma_f32_16x16x32_bf16 v[140:143], v[52:55], v[164:167], v[140:143]
	v_mfma_f32_16x16x32_bf16 v[136:139], v[68:71], v[164:167], v[136:139]
	v_mfma_f32_16x16x32_bf16 v[124:127], v[52:55], v[172:175], v[124:127]
	v_mfma_f32_16x16x32_bf16 v[120:123], v[68:71], v[172:175], v[120:123]
	v_mfma_f32_16x16x32_bf16 v[108:111], v[52:55], v[214:217], v[108:111]
	v_mfma_f32_16x16x32_bf16 v[104:107], v[68:71], v[214:217], v[104:107]
	v_mfma_f32_16x16x32_bf16 v[92:95], v[52:55], v[222:225], v[92:95]
	v_mfma_f32_16x16x32_bf16 v[88:91], v[68:71], v[222:225], v[88:91]
	s_setprio 0
	s_setprio 1
	s_add_i32 s4, s28, s16
	v_lshl_add_u64 v[194:195], v[194:195], 0, s[48:49]
	s_mov_b32 m0, s4
	v_mfma_f32_16x16x32_bf16 v[132:135], v[144:147], v[160:163], v[132:135]
	v_mfma_f32_16x16x32_bf16 v[128:131], v[152:155], v[160:163], v[128:131]
	v_mfma_f32_16x16x32_bf16 v[116:119], v[144:147], v[168:171], v[116:119]
	v_mfma_f32_16x16x32_bf16 v[112:115], v[152:155], v[168:171], v[112:115]
	v_mfma_f32_16x16x32_bf16 v[100:103], v[144:147], v[190:193], v[100:103]
	v_mfma_f32_16x16x32_bf16 v[96:99], v[152:155], v[190:193], v[96:99]
	v_mfma_f32_16x16x32_bf16 v[84:87], v[144:147], v[218:221], v[84:87]
	v_mfma_f32_16x16x32_bf16 v[80:83], v[152:155], v[218:221], v[80:83]
	v_mfma_f32_16x16x32_bf16 v[132:135], v[148:151], v[164:167], v[132:135]
	v_mfma_f32_16x16x32_bf16 v[128:131], v[156:159], v[164:167], v[128:131]
	v_mfma_f32_16x16x32_bf16 v[116:119], v[148:151], v[172:175], v[116:119]
	v_mfma_f32_16x16x32_bf16 v[112:115], v[156:159], v[172:175], v[112:115]
	v_mfma_f32_16x16x32_bf16 v[100:103], v[148:151], v[214:217], v[100:103]
	v_mfma_f32_16x16x32_bf16 v[96:99], v[156:159], v[214:217], v[96:99]
	v_mfma_f32_16x16x32_bf16 v[84:87], v[148:151], v[222:225], v[84:87]
	v_mfma_f32_16x16x32_bf16 v[80:83], v[156:159], v[222:225], v[80:83]
	s_barrier
; #define PG8_STAGE(bufoff, gbase, voff) do { _Pragma("unroll") for (int _i = 0; _i < 2; ++_i) \
;         __builtin_amdgcn_global_load_lds((const unsigned*)((const char*)(gbase) + (voff)[_i]), (LAS unsigned*)(lds + (bufoff) + ldsw + _i * 8192), 16, 0, 0); } while (0)
; #define PG8_LDA(dst, b, h) do { _Pragma("unroll") for (int m = 0; m < 4; ++m) _Pragma("unroll") for (int k = 0; k < 2; ++k) dst[m][k] = *(const LAS bf16x8*)(lds + PG8_SA(b, h) + aoff + m * 2048 + k * 1024); } while (0)
; #define PG8_MMA(ai, bj, At, Bt) do { __builtin_amdgcn_s_setprio(1); _Pragma("unroll") for (int m = 0; m < 4; ++m) _Pragma("unroll") for (int n = 0; n < 2; ++n) _Pragma("unroll") for (int k = 0; k < 2; ++k) \
;         acc[ai][bj][m][n] = __builtin_amdgcn_mfma_f32_16x16x32_bf16(Bt[n][k], At[m][k], acc[ai][bj][m][n], 0, 0, 0); __builtin_amdgcn_s_setprio(0); } while (0)
; #define PG8_WAIT_V(n) asm volatile("s_waitcnt vmcnt(" #n ")" ::: "memory")
; #define PG8_WAIT_L(n) asm volatile("s_waitcnt lgkmcnt(" #n ")" ::: "memory")
; #define PG8_BAR __builtin_amdgcn_s_barrier()
; #define PG8_SCHED __builtin_amdgcn_sched_barrier(0)
; template <class Epi>
; __device__ __forceinline__ void gemm_phase(LAS unsigned char* lds, const GemmD g, const Epi& E, int G, int c) {
;     ...
;             PG8_LDA(At, 1, 1); PG8_STAGE(PG8_SB(1, 0), b3, voffB); PG8_STAGE(PG8_SB(1, 1), b3 + hstepB, voffB); PG8_STAGE(PG8_SA(1, 0), a3, voffA);
;             PG8_WAIT_V(8); PG8_WAIT_L(0); PG8_BAR; PG8_MMA(1, 0, At, B0); PG8_MMA(1, 1, At, B1); PG8_BAR; PG8_SCHED;
;         }
;         if (wr == 0) PG8_BAR;
	s_setprio 0
	ds_read_b128 v[160:163], v212 offset:49152
	ds_read_b128 v[164:167], v212 offset:50176
	ds_read_b128 v[168:171], v212 offset:51200
	ds_read_b128 v[172:175], v212 offset:52224
	ds_read_b128 v[190:193], v212 offset:53248
	ds_read_b128 v[214:217], v212 offset:54272
	ds_read_b128 v[218:221], v212 offset:55296
	ds_read_b128 v[222:225], v212 offset:56320
	global_load_lds_dwordx4 v[194:195], off
	s_add_i32 m0, s4, 0x2000
	s_add_u32 s4, s88, 0x80080
	v_lshl_add_u64 v[194:195], v[198:199], 0, s[48:49]
	s_addc_u32 s5, s89, 0
	s_add_i32 s28, s29, s16
	global_load_lds_dwordx4 v[194:195], off
	v_lshl_add_u64 v[194:195], s[4:5], 0, v[178:179]
	s_mov_b32 m0, s28
	s_nop 0
	global_load_lds_dwordx4 v[194:195], off
	v_lshl_add_u64 v[194:195], s[4:5], 0, v[180:181]
	s_add_i32 m0, s28, 0x2000
	s_nop 0
	global_load_lds_dwordx4 v[194:195], off
	v_lshl_add_u64 v[194:195], v[226:227], 0, s[48:49]
	s_mov_b32 m0, s36
	s_nop 0
	global_load_lds_dwordx4 v[194:195], off
	v_lshl_add_u64 v[194:195], v[228:229], 0, s[48:49]
	s_mov_b32 m0, s90
	s_nop 0
	global_load_lds_dwordx4 v[194:195], off
	s_waitcnt vmcnt(8)
	s_waitcnt lgkmcnt(0)
	s_setprio 1
	s_barrier
	v_mfma_f32_16x16x32_bf16 v[76:79], v[48:51], v[160:163], v[76:79]
	v_mfma_f32_16x16x32_bf16 v[72:75], v[64:67], v[160:163], v[72:75]
	v_mfma_f32_16x16x32_bf16 v[60:63], v[48:51], v[168:171], v[60:63]
	v_mfma_f32_16x16x32_bf16 v[56:59], v[64:67], v[168:171], v[56:59]
	v_mfma_f32_16x16x32_bf16 v[40:43], v[48:51], v[190:193], v[40:43]
	v_mfma_f32_16x16x32_bf16 v[32:35], v[64:67], v[190:193], v[32:35]
	v_mfma_f32_16x16x32_bf16 v[12:15], v[48:51], v[218:221], v[12:15]
	v_mfma_f32_16x16x32_bf16 v[8:11], v[64:67], v[218:221], v[8:11]
	v_mfma_f32_16x16x32_bf16 v[76:79], v[52:55], v[164:167], v[76:79]
	v_mfma_f32_16x16x32_bf16 v[72:75], v[68:71], v[164:167], v[72:75]
	v_mfma_f32_16x16x32_bf16 v[60:63], v[52:55], v[172:175], v[60:63]
	v_mfma_f32_16x16x32_bf16 v[56:59], v[68:71], v[172:175], v[56:59]
	v_mfma_f32_16x16x32_bf16 v[40:43], v[52:55], v[214:217], v[40:43]
	v_mfma_f32_16x16x32_bf16 v[32:35], v[68:71], v[214:217], v[32:35]
	v_mfma_f32_16x16x32_bf16 v[12:15], v[52:55], v[222:225], v[12:15]
	v_mfma_f32_16x16x32_bf16 v[8:11], v[68:71], v[222:225], v[8:11]
	s_setprio 0
	s_setprio 1
	v_mfma_f32_16x16x32_bf16 v[24:27], v[144:147], v[160:163], v[24:27]
	v_mfma_f32_16x16x32_bf16 v[68:71], v[148:151], v[164:167], v[24:27]
	v_mfma_f32_16x16x32_bf16 v[24:27], v[152:155], v[160:163], v[28:31]
	v_mfma_f32_16x16x32_bf16 v[64:67], v[156:159], v[164:167], v[24:27]
	v_mfma_f32_16x16x32_bf16 v[24:27], v[144:147], v[168:171], v[36:39]
	v_mfma_f32_16x16x32_bf16 v[52:55], v[148:151], v[172:175], v[24:27]
	v_mfma_f32_16x16x32_bf16 v[24:27], v[152:155], v[168:171], v[44:47]
	v_mfma_f32_16x16x32_bf16 v[20:23], v[144:147], v[190:193], v[20:23]
	v_mfma_f32_16x16x32_bf16 v[16:19], v[152:155], v[190:193], v[16:19]
	v_mfma_f32_16x16x32_bf16 v[4:7], v[144:147], v[218:221], v[4:7]
	v_mfma_f32_16x16x32_bf16 v[0:3], v[152:155], v[218:221], v[0:3]
	v_mfma_f32_16x16x32_bf16 v[48:51], v[156:159], v[172:175], v[24:27]
	v_mfma_f32_16x16x32_bf16 v[20:23], v[148:151], v[214:217], v[20:23]
	v_mfma_f32_16x16x32_bf16 v[16:19], v[156:159], v[214:217], v[16:19]
	v_mfma_f32_16x16x32_bf16 v[4:7], v[148:151], v[222:225], v[4:7]
	v_mfma_f32_16x16x32_bf16 v[0:3], v[156:159], v[222:225], v[0:3]
	s_barrier
	s_setprio 0
	s_add_i32 s27, s27, 2
	s_add_u32 s42, s42, 0x100
	s_addc_u32 s43, s43, 0
	s_add_u32 s19, s19, 0x100
	s_addc_u32 s22, s22, 0
	s_cmp_gt_u32 s27, 29
	s_cbranch_scc0 .LBB0_271
	s_and_b64 vcc, exec, s[66:67]
	s_cbranch_vccz .LBB0_274
	s_barrier

; #define PG8_STAGE(bufoff, gbase, voff) do { _Pragma("unroll") for (int _i = 0; _i < 2; ++_i) \
;         __builtin_amdgcn_global_load_lds((const unsigned*)((const char*)(gbase) + (voff)[_i]), (LAS unsigned*)(lds + (bufoff) + ldsw + _i * 8192), 16, 0, 0); } while (0)
; #define PG8_LDA(dst, b, h) do { _Pragma("unroll") for (int m = 0; m < 4; ++m) _Pragma("unroll") for (int k = 0; k < 2; ++k) dst[m][k] = *(const LAS bf16x8*)(lds + PG8_SA(b, h) + aoff + m * 2048 + k * 1024); } while (0)
; #define PG8_MMA(ai, bj, At, Bt) do { __builtin_amdgcn_s_setprio(1); _Pragma("unroll") for (int m = 0; m < 4; ++m) _Pragma("unroll") for (int n = 0; n < 2; ++n) _Pragma("unroll") for (int k = 0; k < 2; ++k) \
;         acc[ai][bj][m][n] = __builtin_amdgcn_mfma_f32_16x16x32_bf16(Bt[n][k], At[m][k], acc[ai][bj][m][n], 0, 0, 0); __builtin_amdgcn_s_setprio(0); } while (0)
; #define PG8_WAIT_V(n) asm volatile("s_waitcnt vmcnt(" #n ")" ::: "memory")
; #define PG8_WAIT_L(n) asm volatile("s_waitcnt lgkmcnt(" #n ")" ::: "memory")
; #define PG8_BAR __builtin_amdgcn_s_barrier()
; #define PG8_SCHED __builtin_amdgcn_sched_barrier(0)
; template <class Epi>
; __device__ __forceinline__ void gemm_phase(LAS unsigned char* lds, const GemmD g, const Epi& E, int G, int c) {
;     ...
;             PG8_WAIT_V(8); PG8_WAIT_L(0); PG8_BAR; PG8_MMA(0, 0, At, B0); PG8_MMA(0, 1, At, B1); PG8_BAR; PG8_SCHED;
;             PG8_LDA(At, 0, 1); PG8_STAGE(PG8_SB(0, 0), b2, voffB); PG8_STAGE(PG8_SB(0, 1), b2 + hstepB, voffB); PG8_STAGE(PG8_SA(0, 0), a2, voffA);
.Lrw_PV_0_d:
	s_waitcnt lgkmcnt(0)
	s_setprio 1
	s_barrier
	v_mfma_f32_16x16x32_bf16 v[124:127], v[146:149], v[184:187], v[124:127]
	v_mfma_f32_16x16x32_bf16 v[120:123], v[154:157], v[184:187], v[120:123]
	v_mfma_f32_16x16x32_bf16 v[112:115], v[146:149], v[192:195], v[112:115]
	v_mfma_f32_16x16x32_bf16 v[104:107], v[154:157], v[192:195], v[104:107]
	v_mfma_f32_16x16x32_bf16 v[96:99], v[146:149], v[214:217], v[96:99]
	v_mfma_f32_16x16x32_bf16 v[88:91], v[154:157], v[214:217], v[88:91]
	v_mfma_f32_16x16x32_bf16 v[80:83], v[146:149], v[222:225], v[80:83]
	v_mfma_f32_16x16x32_bf16 v[72:75], v[154:157], v[222:225], v[72:75]
	v_mfma_f32_16x16x32_bf16 v[124:127], v[150:153], v[188:191], v[124:127]
	v_mfma_f32_16x16x32_bf16 v[120:123], v[158:161], v[188:191], v[120:123]
	v_mfma_f32_16x16x32_bf16 v[112:115], v[150:153], v[210:213], v[112:115]
	v_mfma_f32_16x16x32_bf16 v[104:107], v[158:161], v[210:213], v[104:107]
	v_mfma_f32_16x16x32_bf16 v[96:99], v[150:153], v[218:221], v[96:99]
	v_mfma_f32_16x16x32_bf16 v[88:91], v[158:161], v[218:221], v[88:91]
	v_mfma_f32_16x16x32_bf16 v[80:83], v[150:153], v[226:229], v[80:83]
	v_mfma_f32_16x16x32_bf16 v[72:75], v[158:161], v[226:229], v[72:75]
	s_setprio 0
	s_setprio 1
	s_add_i32 s31, s31, s2
	v_lshl_add_u64 v[138:139], s[84:85], 0, v[178:179]
	s_mov_b32 m0, s31
	v_mfma_f32_16x16x32_bf16 v[116:119], v[162:165], v[184:187], v[116:119]
	v_mfma_f32_16x16x32_bf16 v[108:111], v[170:173], v[184:187], v[108:111]
	v_mfma_f32_16x16x32_bf16 v[100:103], v[162:165], v[192:195], v[100:103]
	v_mfma_f32_16x16x32_bf16 v[92:95], v[170:173], v[192:195], v[92:95]
	v_mfma_f32_16x16x32_bf16 v[84:87], v[162:165], v[214:217], v[84:87]
	v_mfma_f32_16x16x32_bf16 v[76:79], v[170:173], v[214:217], v[76:79]
	v_mfma_f32_16x16x32_bf16 v[68:71], v[162:165], v[222:225], v[68:71]
	v_mfma_f32_16x16x32_bf16 v[64:67], v[170:173], v[222:225], v[64:67]
	v_mfma_f32_16x16x32_bf16 v[116:119], v[166:169], v[188:191], v[116:119]
	v_mfma_f32_16x16x32_bf16 v[108:111], v[180:183], v[188:191], v[108:111]
	v_mfma_f32_16x16x32_bf16 v[100:103], v[166:169], v[210:213], v[100:103]
	v_mfma_f32_16x16x32_bf16 v[92:95], v[180:183], v[210:213], v[92:95]
	v_mfma_f32_16x16x32_bf16 v[84:87], v[166:169], v[218:221], v[84:87]
	v_mfma_f32_16x16x32_bf16 v[76:79], v[180:183], v[218:221], v[76:79]
	v_mfma_f32_16x16x32_bf16 v[68:71], v[166:169], v[226:229], v[68:71]
	v_mfma_f32_16x16x32_bf16 v[64:67], v[180:183], v[226:229], v[64:67]
	s_barrier
	s_setprio 0
	ds_read_b128 v[184:187], v143 offset:16384
	ds_read_b128 v[188:191], v143 offset:17408
	ds_read_b128 v[192:195], v143 offset:18432
	ds_read_b128 v[210:213], v143 offset:19456
	ds_read_b128 v[214:217], v143 offset:20480
	ds_read_b128 v[218:221], v143 offset:21504
	ds_read_b128 v[222:225], v143 offset:22528
	ds_read_b128 v[226:229], v143 offset:23552
	global_load_lds_dwordx4 v[138:139], off
	s_add_i32 m0, s31, 0x2000
	s_add_u32 s38, s84, 0x400000
	v_lshl_add_u64 v[174:175], s[84:85], 0, v[128:129]
	s_addc_u32 s39, s85, 0
	s_add_i32 s31, s33, s2
	global_load_lds_dwordx4 v[174:175], off
	v_lshl_add_u64 v[198:199], s[38:39], 0, v[178:179]
	s_mov_b32 m0, s31
	v_lshl_add_u64 v[230:231], s[4:5], 0, v[130:131]
	global_load_lds_dwordx4 v[198:199], off
	v_lshl_add_u64 v[198:199], s[38:39], 0, v[128:129]
	s_add_i32 m0, s31, 0x2000
	s_nop 0
	global_load_lds_dwordx4 v[198:199], off
	v_lshl_add_u64 v[198:199], s[4:5], 0, v[132:133]
	s_mov_b32 m0, s6
	s_nop 0
	global_load_lds_dwordx4 v[198:199], off
	s_mov_b32 m0, s9
	s_nop 0
	global_load_lds_dwordx4 v[230:231], off
	s_cmp_lg_u32 s99, 0
	s_cbranch_scc1 .Lrw_PV_1_r
	s_waitcnt vmcnt(8)
	s_branch .Lrw_PV_1_d

; #define PG8_STAGE(bufoff, gbase, voff) do { _Pragma("unroll") for (int _i = 0; _i < 2; ++_i) \
;         __builtin_amdgcn_global_load_lds((const unsigned*)((const char*)(gbase) + (voff)[_i]), (LAS unsigned*)(lds + (bufoff) + ldsw + _i * 8192), 16, 0, 0); } while (0)
; #define PG8_LDA(dst, b, h) do { _Pragma("unroll") for (int m = 0; m < 4; ++m) _Pragma("unroll") for (int k = 0; k < 2; ++k) dst[m][k] = *(const LAS bf16x8*)(lds + PG8_SA(b, h) + aoff + m * 2048 + k * 1024); } while (0)
; #define PG8_LDB(dst, b, h) do { _Pragma("unroll") for (int n = 0; n < 2; ++n) _Pragma("unroll") for (int k = 0; k < 2; ++k) dst[n][k] = *(const LAS bf16x8*)(lds + PG8_SB(b, h) + boff + n * 2048 + k * 1024); } while (0)
; #define PG8_MMA(ai, bj, At, Bt) do { __builtin_amdgcn_s_setprio(1); _Pragma("unroll") for (int m = 0; m < 4; ++m) _Pragma("unroll") for (int n = 0; n < 2; ++n) _Pragma("unroll") for (int k = 0; k < 2; ++k) \
;         acc[ai][bj][m][n] = __builtin_amdgcn_mfma_f32_16x16x32_bf16(Bt[n][k], At[m][k], acc[ai][bj][m][n], 0, 0, 0); __builtin_amdgcn_s_setprio(0); } while (0)
; #define PG8_WAIT_V(n) asm volatile("s_waitcnt vmcnt(" #n ")" ::: "memory")
; #define PG8_WAIT_L(n) asm volatile("s_waitcnt lgkmcnt(" #n ")" ::: "memory")
; #define PG8_BAR __builtin_amdgcn_s_barrier()
; #define PG8_SCHED __builtin_amdgcn_sched_barrier(0)
; template <class Epi>
; __device__ __forceinline__ void gemm_phase(LAS unsigned char* lds, const GemmD g, const Epi& E, int G, int c) {
;     ...
;             PG8_WAIT_V(8); PG8_WAIT_L(0); PG8_BAR; PG8_MMA(1, 0, At, B0); PG8_MMA(1, 1, At, B1); PG8_BAR; PG8_SCHED;
;             PG8_LDB(B0, 1, 0); PG8_LDB(B1, 1, 1); PG8_SCHED; PG8_LDA(At, 1, 0); PG8_STAGE(PG8_SA(0, 1), a2 + hstepA, voffA);
;             PG8_WAIT_V(8); PG8_WAIT_L(0); PG8_BAR; PG8_MMA(0, 0, At, B0); PG8_MMA(0, 1, At, B1); PG8_BAR; PG8_SCHED;
.Lrw_PV_1_d:
	s_waitcnt lgkmcnt(0)
	s_setprio 1
	s_barrier
	v_mfma_f32_16x16x32_bf16 v[60:63], v[146:149], v[184:187], v[60:63]
	v_mfma_f32_16x16x32_bf16 v[56:59], v[154:157], v[184:187], v[56:59]
	v_mfma_f32_16x16x32_bf16 v[52:55], v[146:149], v[192:195], v[52:55]
	v_mfma_f32_16x16x32_bf16 v[44:47], v[154:157], v[192:195], v[44:47]
	v_mfma_f32_16x16x32_bf16 v[36:39], v[146:149], v[214:217], v[36:39]
	v_mfma_f32_16x16x32_bf16 v[28:31], v[154:157], v[214:217], v[28:31]
	v_mfma_f32_16x16x32_bf16 v[20:23], v[146:149], v[222:225], v[20:23]
	v_mfma_f32_16x16x32_bf16 v[12:15], v[154:157], v[222:225], v[12:15]
	v_mfma_f32_16x16x32_bf16 v[60:63], v[150:153], v[188:191], v[60:63]
	v_mfma_f32_16x16x32_bf16 v[56:59], v[158:161], v[188:191], v[56:59]
	v_mfma_f32_16x16x32_bf16 v[52:55], v[150:153], v[210:213], v[52:55]
	v_mfma_f32_16x16x32_bf16 v[44:47], v[158:161], v[210:213], v[44:47]
	v_mfma_f32_16x16x32_bf16 v[36:39], v[150:153], v[218:221], v[36:39]
	v_mfma_f32_16x16x32_bf16 v[28:31], v[158:161], v[218:221], v[28:31]
	v_mfma_f32_16x16x32_bf16 v[20:23], v[150:153], v[226:229], v[20:23]
	v_mfma_f32_16x16x32_bf16 v[12:15], v[158:161], v[226:229], v[12:15]
	s_setprio 0
	s_setprio 1
	s_add_i32 s31, 0, 0x18000
	v_add_u32_e32 v145, s31, v141
	s_add_i32 s33, 0, 0x1c000
	v_mfma_f32_16x16x32_bf16 v[48:51], v[162:165], v[184:187], v[48:51]
	v_mfma_f32_16x16x32_bf16 v[40:43], v[170:173], v[184:187], v[40:43]
	v_mfma_f32_16x16x32_bf16 v[32:35], v[162:165], v[192:195], v[32:35]
	v_mfma_f32_16x16x32_bf16 v[24:27], v[170:173], v[192:195], v[24:27]
	v_mfma_f32_16x16x32_bf16 v[16:19], v[162:165], v[214:217], v[16:19]
	v_mfma_f32_16x16x32_bf16 v[8:11], v[170:173], v[214:217], v[8:11]
	v_mfma_f32_16x16x32_bf16 v[4:7], v[162:165], v[222:225], v[4:7]
	v_mfma_f32_16x16x32_bf16 v[0:3], v[170:173], v[222:225], v[0:3]
	v_mfma_f32_16x16x32_bf16 v[48:51], v[166:169], v[188:191], v[48:51]
	v_mfma_f32_16x16x32_bf16 v[40:43], v[180:183], v[188:191], v[40:43]
	v_mfma_f32_16x16x32_bf16 v[32:35], v[166:169], v[210:213], v[32:35]
	v_mfma_f32_16x16x32_bf16 v[24:27], v[180:183], v[210:213], v[24:27]
	v_mfma_f32_16x16x32_bf16 v[16:19], v[166:169], v[218:221], v[16:19]
	v_mfma_f32_16x16x32_bf16 v[8:11], v[180:183], v[218:221], v[8:11]
	v_mfma_f32_16x16x32_bf16 v[4:7], v[166:169], v[226:229], v[4:7]
	v_mfma_f32_16x16x32_bf16 v[0:3], v[180:183], v[226:229], v[0:3]
	s_barrier
	s_setprio 0
	ds_read_b128 v[146:149], v145
	ds_read_b128 v[150:153], v145 offset:1024
	ds_read_b128 v[154:157], v145 offset:2048
	ds_read_b128 v[158:161], v145 offset:3072
	v_add_u32_e32 v145, s33, v141
	ds_read_b128 v[162:165], v145
	ds_read_b128 v[166:169], v145 offset:1024
	ds_read_b128 v[170:173], v145 offset:2048
	ds_read_b128 v[180:183], v145 offset:3072
	s_add_u32 s4, s4, 0x80000
	s_addc_u32 s5, s5, 0
	s_mov_b32 m0, s10
	v_lshl_add_u64 v[232:233], s[4:5], 0, v[132:133]
	ds_read_b128 v[184:187], v143 offset:32768
	ds_read_b128 v[188:191], v143 offset:33792
	ds_read_b128 v[192:195], v143 offset:34816
	ds_read_b128 v[210:213], v143 offset:35840
	ds_read_b128 v[214:217], v143 offset:36864
	ds_read_b128 v[218:221], v143 offset:37888
	ds_read_b128 v[222:225], v143 offset:38912
	ds_read_b128 v[226:229], v143 offset:39936
	global_load_lds_dwordx4 v[232:233], off
	v_lshl_add_u64 v[232:233], s[4:5], 0, v[130:131]
	s_mov_b32 m0, s11
	s_nop 0
	global_load_lds_dwordx4 v[232:233], off
	s_waitcnt vmcnt(8)
	s_waitcnt lgkmcnt(0)
	s_setprio 1
	s_barrier
	v_mfma_f32_16x16x32_bf16 v[124:127], v[146:149], v[184:187], v[124:127]
	v_mfma_f32_16x16x32_bf16 v[120:123], v[154:157], v[184:187], v[120:123]
	v_mfma_f32_16x16x32_bf16 v[112:115], v[146:149], v[192:195], v[112:115]
	v_mfma_f32_16x16x32_bf16 v[104:107], v[154:157], v[192:195], v[104:107]
	v_mfma_f32_16x16x32_bf16 v[96:99], v[146:149], v[214:217], v[96:99]
	v_mfma_f32_16x16x32_bf16 v[88:91], v[154:157], v[214:217], v[88:91]
	v_mfma_f32_16x16x32_bf16 v[80:83], v[146:149], v[222:225], v[80:83]
	v_mfma_f32_16x16x32_bf16 v[72:75], v[154:157], v[222:225], v[72:75]
	v_mfma_f32_16x16x32_bf16 v[124:127], v[150:153], v[188:191], v[124:127]
	v_mfma_f32_16x16x32_bf16 v[120:123], v[158:161], v[188:191], v[120:123]
	v_mfma_f32_16x16x32_bf16 v[112:115], v[150:153], v[210:213], v[112:115]
	v_mfma_f32_16x16x32_bf16 v[104:107], v[158:161], v[210:213], v[104:107]
	v_mfma_f32_16x16x32_bf16 v[96:99], v[150:153], v[218:221], v[96:99]
	v_mfma_f32_16x16x32_bf16 v[88:91], v[158:161], v[218:221], v[88:91]
	v_mfma_f32_16x16x32_bf16 v[80:83], v[150:153], v[226:229], v[80:83]
	v_mfma_f32_16x16x32_bf16 v[72:75], v[158:161], v[226:229], v[72:75]
	s_setprio 0
	s_setprio 1
	s_add_i32 s4, s31, s2
	v_lshl_add_u64 v[138:139], v[138:139], 0, s[48:49]
	s_mov_b32 m0, s4
	v_mfma_f32_16x16x32_bf16 v[116:119], v[162:165], v[184:187], v[116:119]
	v_mfma_f32_16x16x32_bf16 v[108:111], v[170:173], v[184:187], v[108:111]
	v_mfma_f32_16x16x32_bf16 v[100:103], v[162:165], v[192:195], v[100:103]
	v_mfma_f32_16x16x32_bf16 v[92:95], v[170:173], v[192:195], v[92:95]
	v_mfma_f32_16x16x32_bf16 v[84:87], v[162:165], v[214:217], v[84:87]
	v_mfma_f32_16x16x32_bf16 v[76:79], v[170:173], v[214:217], v[76:79]
	v_mfma_f32_16x16x32_bf16 v[68:71], v[162:165], v[222:225], v[68:71]
	v_mfma_f32_16x16x32_bf16 v[64:67], v[170:173], v[222:225], v[64:67]
	v_mfma_f32_16x16x32_bf16 v[116:119], v[166:169], v[188:191], v[116:119]
	v_mfma_f32_16x16x32_bf16 v[108:111], v[180:183], v[188:191], v[108:111]
	v_mfma_f32_16x16x32_bf16 v[100:103], v[166:169], v[210:213], v[100:103]
	v_mfma_f32_16x16x32_bf16 v[92:95], v[180:183], v[210:213], v[92:95]
	v_mfma_f32_16x16x32_bf16 v[84:87], v[166:169], v[218:221], v[84:87]
	v_mfma_f32_16x16x32_bf16 v[76:79], v[180:183], v[218:221], v[76:79]
	v_mfma_f32_16x16x32_bf16 v[68:71], v[166:169], v[226:229], v[68:71]
	v_mfma_f32_16x16x32_bf16 v[64:67], v[180:183], v[226:229], v[64:67]
	s_barrier
; #define PG8_STAGE(bufoff, gbase, voff) do { _Pragma("unroll") for (int _i = 0; _i < 2; ++_i) \
;         __builtin_amdgcn_global_load_lds((const unsigned*)((const char*)(gbase) + (voff)[_i]), (LAS unsigned*)(lds + (bufoff) + ldsw + _i * 8192), 16, 0, 0); } while (0)
; #define PG8_LDA(dst, b, h) do { _Pragma("unroll") for (int m = 0; m < 4; ++m) _Pragma("unroll") for (int k = 0; k < 2; ++k) dst[m][k] = *(const LAS bf16x8*)(lds + PG8_SA(b, h) + aoff + m * 2048 + k * 1024); } while (0)
; #define PG8_MMA(ai, bj, At, Bt) do { __builtin_amdgcn_s_setprio(1); _Pragma("unroll") for (int m = 0; m < 4; ++m) _Pragma("unroll") for (int n = 0; n < 2; ++n) _Pragma("unroll") for (int k = 0; k < 2; ++k) \
;         acc[ai][bj][m][n] = __builtin_amdgcn_mfma_f32_16x16x32_bf16(Bt[n][k], At[m][k], acc[ai][bj][m][n], 0, 0, 0); __builtin_amdgcn_s_setprio(0); } while (0)
; #define PG8_WAIT_V(n) asm volatile("s_waitcnt vmcnt(" #n ")" ::: "memory")
; #define PG8_WAIT_L(n) asm volatile("s_waitcnt lgkmcnt(" #n ")" ::: "memory")
; #define PG8_BAR __builtin_amdgcn_s_barrier()
; #define PG8_SCHED __builtin_amdgcn_sched_barrier(0)
; template <class Epi>
; __device__ __forceinline__ void gemm_phase(LAS unsigned char* lds, const GemmD g, const Epi& E, int G, int c) {
;     ...
;             PG8_LDA(At, 1, 1); PG8_STAGE(PG8_SB(1, 0), b3, voffB); PG8_STAGE(PG8_SB(1, 1), b3 + hstepB, voffB); PG8_STAGE(PG8_SA(1, 0), a3, voffA);
;             PG8_WAIT_V(8); PG8_WAIT_L(0); PG8_BAR; PG8_MMA(1, 0, At, B0); PG8_MMA(1, 1, At, B1); PG8_BAR; PG8_SCHED;
;         }
;         if (wr == 0) PG8_BAR;
	s_setprio 0
	ds_read_b128 v[184:187], v143 offset:49152
	ds_read_b128 v[188:191], v143 offset:50176
	ds_read_b128 v[192:195], v143 offset:51200
	ds_read_b128 v[210:213], v143 offset:52224
	ds_read_b128 v[214:217], v143 offset:53248
	ds_read_b128 v[218:221], v143 offset:54272
	ds_read_b128 v[222:225], v143 offset:55296
	ds_read_b128 v[226:229], v143 offset:56320
	global_load_lds_dwordx4 v[138:139], off
	s_add_i32 m0, s4, 0x2000
	s_add_u32 s4, s84, 0x400080
	v_lshl_add_u64 v[138:139], v[174:175], 0, s[48:49]
	s_addc_u32 s5, s85, 0
	s_add_i32 s31, s33, s2
	global_load_lds_dwordx4 v[138:139], off
	v_lshl_add_u64 v[138:139], s[4:5], 0, v[178:179]
	s_mov_b32 m0, s31
	s_nop 0
	global_load_lds_dwordx4 v[138:139], off
	v_lshl_add_u64 v[138:139], s[4:5], 0, v[128:129]
	s_add_i32 m0, s31, 0x2000
	s_nop 0
	global_load_lds_dwordx4 v[138:139], off
	v_lshl_add_u64 v[138:139], v[198:199], 0, s[48:49]
	s_mov_b32 m0, s16
	s_nop 0
	global_load_lds_dwordx4 v[138:139], off
	v_lshl_add_u64 v[138:139], v[230:231], 0, s[48:49]
	s_mov_b32 m0, s17
	s_nop 0
	global_load_lds_dwordx4 v[138:139], off
	s_waitcnt vmcnt(8)
	s_waitcnt lgkmcnt(0)
	s_setprio 1
	s_barrier
	v_mfma_f32_16x16x32_bf16 v[60:63], v[146:149], v[184:187], v[60:63]
	v_mfma_f32_16x16x32_bf16 v[56:59], v[154:157], v[184:187], v[56:59]
	v_mfma_f32_16x16x32_bf16 v[52:55], v[146:149], v[192:195], v[52:55]
	v_mfma_f32_16x16x32_bf16 v[44:47], v[154:157], v[192:195], v[44:47]
	v_mfma_f32_16x16x32_bf16 v[36:39], v[146:149], v[214:217], v[36:39]
	v_mfma_f32_16x16x32_bf16 v[28:31], v[154:157], v[214:217], v[28:31]
	v_mfma_f32_16x16x32_bf16 v[20:23], v[146:149], v[222:225], v[20:23]
	v_mfma_f32_16x16x32_bf16 v[12:15], v[154:157], v[222:225], v[12:15]
	v_mfma_f32_16x16x32_bf16 v[60:63], v[150:153], v[188:191], v[60:63]
	v_mfma_f32_16x16x32_bf16 v[56:59], v[158:161], v[188:191], v[56:59]
	v_mfma_f32_16x16x32_bf16 v[52:55], v[150:153], v[210:213], v[52:55]
	v_mfma_f32_16x16x32_bf16 v[44:47], v[158:161], v[210:213], v[44:47]
	v_mfma_f32_16x16x32_bf16 v[36:39], v[150:153], v[218:221], v[36:39]
	v_mfma_f32_16x16x32_bf16 v[28:31], v[158:161], v[218:221], v[28:31]
	v_mfma_f32_16x16x32_bf16 v[20:23], v[150:153], v[226:229], v[20:23]
	v_mfma_f32_16x16x32_bf16 v[12:15], v[158:161], v[226:229], v[12:15]
	s_setprio 0
	s_setprio 1
	v_mfma_f32_16x16x32_bf16 v[48:51], v[162:165], v[184:187], v[48:51]
	v_mfma_f32_16x16x32_bf16 v[40:43], v[170:173], v[184:187], v[40:43]
	v_mfma_f32_16x16x32_bf16 v[32:35], v[162:165], v[192:195], v[32:35]
	v_mfma_f32_16x16x32_bf16 v[24:27], v[170:173], v[192:195], v[24:27]
	v_mfma_f32_16x16x32_bf16 v[16:19], v[162:165], v[214:217], v[16:19]
	v_mfma_f32_16x16x32_bf16 v[8:11], v[170:173], v[214:217], v[8:11]
	v_mfma_f32_16x16x32_bf16 v[4:7], v[162:165], v[222:225], v[4:7]
	v_mfma_f32_16x16x32_bf16 v[0:3], v[170:173], v[222:225], v[0:3]
	v_mfma_f32_16x16x32_bf16 v[48:51], v[166:169], v[188:191], v[48:51]
	v_mfma_f32_16x16x32_bf16 v[40:43], v[180:183], v[188:191], v[40:43]
	v_mfma_f32_16x16x32_bf16 v[32:35], v[166:169], v[210:213], v[32:35]
	v_mfma_f32_16x16x32_bf16 v[24:27], v[180:183], v[210:213], v[24:27]
	v_mfma_f32_16x16x32_bf16 v[16:19], v[166:169], v[218:221], v[16:19]
	v_mfma_f32_16x16x32_bf16 v[8:11], v[180:183], v[218:221], v[8:11]
	v_mfma_f32_16x16x32_bf16 v[4:7], v[166:169], v[226:229], v[4:7]
	v_mfma_f32_16x16x32_bf16 v[0:3], v[180:183], v[226:229], v[0:3]
	s_barrier
	s_setprio 0
	s_add_i32 s30, s30, 2
	s_add_u32 s82, s82, 0x100
	s_addc_u32 s83, s83, 0
	s_add_u32 s28, s28, 0x100
	s_addc_u32 s29, s29, 0
	s_cmp_gt_u32 s30, 29
	s_cbranch_scc0 .LBB0_297
	s_and_b64 vcc, exec, s[60:61]
	s_cbranch_vccz .LBB0_300
	s_barrier

; #define PG8_STAGE(bufoff, gbase, voff) do { _Pragma("unroll") for (int _i = 0; _i < 2; ++_i) \
;         __builtin_amdgcn_global_load_lds((const unsigned*)((const char*)(gbase) + (voff)[_i]), (LAS unsigned*)(lds + (bufoff) + ldsw + _i * 8192), 16, 0, 0); } while (0)
; #define PG8_LDA(dst, b, h) do { _Pragma("unroll") for (int m = 0; m < 4; ++m) _Pragma("unroll") for (int k = 0; k < 2; ++k) dst[m][k] = *(const LAS bf16x8*)(lds + PG8_SA(b, h) + aoff + m * 2048 + k * 1024); } while (0)
; #define PG8_MMA(ai, bj, At, Bt) do { __builtin_amdgcn_s_setprio(1); _Pragma("unroll") for (int m = 0; m < 4; ++m) _Pragma("unroll") for (int n = 0; n < 2; ++n) _Pragma("unroll") for (int k = 0; k < 2; ++k) \
;         acc[ai][bj][m][n] = __builtin_amdgcn_mfma_f32_16x16x32_bf16(Bt[n][k], At[m][k], acc[ai][bj][m][n], 0, 0, 0); __builtin_amdgcn_s_setprio(0); } while (0)
; #define PG8_WAIT_V(n) asm volatile("s_waitcnt vmcnt(" #n ")" ::: "memory")
; #define PG8_WAIT_L(n) asm volatile("s_waitcnt lgkmcnt(" #n ")" ::: "memory")
; #define PG8_BAR __builtin_amdgcn_s_barrier()
; #define PG8_SCHED __builtin_amdgcn_sched_barrier(0)
; template <class Epi>
; __device__ __forceinline__ void gemm_phase(LAS unsigned char* lds, const GemmD g, const Epi& E, int G, int c) {
;     ...
;             PG8_WAIT_V(8); PG8_WAIT_L(0); PG8_BAR; PG8_MMA(0, 0, At, B0); PG8_MMA(0, 1, At, B1); PG8_BAR; PG8_SCHED;
;             PG8_LDA(At, 0, 1); PG8_STAGE(PG8_SB(0, 0), b2, voffB); PG8_STAGE(PG8_SB(0, 1), b2 + hstepB, voffB); PG8_STAGE(PG8_SA(0, 0), a2, voffA);
.Lrw_S_0_d:
	s_waitcnt lgkmcnt(0)
	s_setprio 1
	s_barrier
	v_mfma_f32_16x16x32_bf16 v[124:127], v[128:131], v[166:169], v[124:127]
	v_mfma_f32_16x16x32_bf16 v[120:123], v[142:145], v[166:169], v[120:123]
	v_mfma_f32_16x16x32_bf16 v[108:111], v[128:131], v[184:187], v[108:111]
	v_mfma_f32_16x16x32_bf16 v[104:107], v[142:145], v[184:187], v[104:107]
	v_mfma_f32_16x16x32_bf16 v[92:95], v[128:131], v[192:195], v[92:95]
	v_mfma_f32_16x16x32_bf16 v[88:91], v[142:145], v[192:195], v[88:91]
	v_mfma_f32_16x16x32_bf16 v[76:79], v[128:131], v[214:217], v[76:79]
	v_mfma_f32_16x16x32_bf16 v[72:75], v[142:145], v[214:217], v[72:75]
	v_mfma_f32_16x16x32_bf16 v[124:127], v[138:141], v[180:183], v[124:127]
	v_mfma_f32_16x16x32_bf16 v[120:123], v[146:149], v[180:183], v[120:123]
	v_mfma_f32_16x16x32_bf16 v[108:111], v[138:141], v[188:191], v[108:111]
	v_mfma_f32_16x16x32_bf16 v[104:107], v[146:149], v[188:191], v[104:107]
	v_mfma_f32_16x16x32_bf16 v[92:95], v[138:141], v[210:213], v[92:95]
	v_mfma_f32_16x16x32_bf16 v[88:91], v[146:149], v[210:213], v[88:91]
	v_mfma_f32_16x16x32_bf16 v[76:79], v[138:141], v[218:221], v[76:79]
	v_mfma_f32_16x16x32_bf16 v[72:75], v[146:149], v[218:221], v[72:75]
	s_setprio 0
	s_setprio 1
	s_mov_b32 m0, s38
	v_lshl_add_u64 v[174:175], s[94:95], 0, v[178:179]
	v_mfma_f32_16x16x32_bf16 v[116:119], v[150:153], v[166:169], v[116:119]
	v_mfma_f32_16x16x32_bf16 v[112:115], v[158:161], v[166:169], v[112:115]
	v_mfma_f32_16x16x32_bf16 v[100:103], v[150:153], v[184:187], v[100:103]
	v_mfma_f32_16x16x32_bf16 v[96:99], v[158:161], v[184:187], v[96:99]
	v_mfma_f32_16x16x32_bf16 v[84:87], v[150:153], v[192:195], v[84:87]
	v_mfma_f32_16x16x32_bf16 v[80:83], v[158:161], v[192:195], v[80:83]
	v_mfma_f32_16x16x32_bf16 v[68:71], v[150:153], v[214:217], v[68:71]
	v_mfma_f32_16x16x32_bf16 v[64:67], v[158:161], v[214:217], v[64:67]
	v_mfma_f32_16x16x32_bf16 v[116:119], v[154:157], v[180:183], v[116:119]
	v_mfma_f32_16x16x32_bf16 v[112:115], v[162:165], v[180:183], v[112:115]
	v_mfma_f32_16x16x32_bf16 v[100:103], v[154:157], v[188:191], v[100:103]
	v_mfma_f32_16x16x32_bf16 v[96:99], v[162:165], v[188:191], v[96:99]
	v_mfma_f32_16x16x32_bf16 v[84:87], v[154:157], v[210:213], v[84:87]
	v_mfma_f32_16x16x32_bf16 v[80:83], v[162:165], v[210:213], v[80:83]
	v_mfma_f32_16x16x32_bf16 v[68:71], v[154:157], v[218:221], v[68:71]
	v_mfma_f32_16x16x32_bf16 v[64:67], v[162:165], v[218:221], v[64:67]
	s_barrier
	s_setprio 0
	ds_read_b128 v[166:169], v173 offset:16384
	ds_read_b128 v[180:183], v173 offset:17408
	ds_read_b128 v[184:187], v173 offset:18432
	ds_read_b128 v[188:191], v173 offset:19456
	ds_read_b128 v[192:195], v173 offset:20480
	ds_read_b128 v[210:213], v173 offset:21504
	ds_read_b128 v[214:217], v173 offset:22528
	ds_read_b128 v[218:221], v173 offset:23552
	global_load_lds_dwordx4 v[174:175], off
	v_lshl_add_u64 v[198:199], s[94:95], 0, v[132:133]
	s_mov_b32 m0, s29
	v_lshl_add_u64 v[222:223], s[96:97], 0, v[178:179]
	global_load_lds_dwordx4 v[198:199], off
	s_mov_b32 m0, s33
	v_lshl_add_u64 v[224:225], s[92:93], 0, v[134:135]
	global_load_lds_dwordx4 v[222:223], off
	v_lshl_add_u64 v[222:223], s[96:97], 0, v[132:133]
	s_mov_b32 m0, s31
	s_nop 0
	global_load_lds_dwordx4 v[222:223], off
	v_lshl_add_u64 v[222:223], s[92:93], 0, v[136:137]
	s_mov_b32 m0, s30
	s_nop 0
	global_load_lds_dwordx4 v[222:223], off
	s_mov_b32 m0, s35
	s_nop 0
	global_load_lds_dwordx4 v[224:225], off
	s_cmp_lg_u32 s99, 0
	s_cbranch_scc1 .Lrw_S_1_r
	s_waitcnt vmcnt(8)
	s_branch .Lrw_S_1_d

; #define PG8_STAGE(bufoff, gbase, voff) do { _Pragma("unroll") for (int _i = 0; _i < 2; ++_i) \
;         __builtin_amdgcn_global_load_lds((const unsigned*)((const char*)(gbase) + (voff)[_i]), (LAS unsigned*)(lds + (bufoff) + ldsw + _i * 8192), 16, 0, 0); } while (0)
; #define PG8_LDA(dst, b, h) do { _Pragma("unroll") for (int m = 0; m < 4; ++m) _Pragma("unroll") for (int k = 0; k < 2; ++k) dst[m][k] = *(const LAS bf16x8*)(lds + PG8_SA(b, h) + aoff + m * 2048 + k * 1024); } while (0)
; #define PG8_LDB(dst, b, h) do { _Pragma("unroll") for (int n = 0; n < 2; ++n) _Pragma("unroll") for (int k = 0; k < 2; ++k) dst[n][k] = *(const LAS bf16x8*)(lds + PG8_SB(b, h) + boff + n * 2048 + k * 1024); } while (0)
; #define PG8_MMA(ai, bj, At, Bt) do { __builtin_amdgcn_s_setprio(1); _Pragma("unroll") for (int m = 0; m < 4; ++m) _Pragma("unroll") for (int n = 0; n < 2; ++n) _Pragma("unroll") for (int k = 0; k < 2; ++k) \
;         acc[ai][bj][m][n] = __builtin_amdgcn_mfma_f32_16x16x32_bf16(Bt[n][k], At[m][k], acc[ai][bj][m][n], 0, 0, 0); __builtin_amdgcn_s_setprio(0); } while (0)
; #define PG8_WAIT_V(n) asm volatile("s_waitcnt vmcnt(" #n ")" ::: "memory")
; #define PG8_WAIT_L(n) asm volatile("s_waitcnt lgkmcnt(" #n ")" ::: "memory")
; #define PG8_BAR __builtin_amdgcn_s_barrier()
; #define PG8_SCHED __builtin_amdgcn_sched_barrier(0)
; template <class Epi>
; __device__ __forceinline__ void gemm_phase(LAS unsigned char* lds, const GemmD g, const Epi& E, int G, int c) {
;     ...
;             PG8_WAIT_V(8); PG8_WAIT_L(0); PG8_BAR; PG8_MMA(1, 0, At, B0); PG8_MMA(1, 1, At, B1); PG8_BAR; PG8_SCHED;
;             PG8_LDB(B0, 1, 0); PG8_LDB(B1, 1, 1); PG8_SCHED; PG8_LDA(At, 1, 0); PG8_STAGE(PG8_SA(0, 1), a2 + hstepA, voffA);
;             PG8_WAIT_V(8); PG8_WAIT_L(0); PG8_BAR; PG8_MMA(0, 0, At, B0); PG8_MMA(0, 1, At, B1); PG8_BAR; PG8_SCHED;
.Lrw_S_1_d:
	s_waitcnt lgkmcnt(0)
	s_setprio 1
	s_barrier
	v_mfma_f32_16x16x32_bf16 v[60:63], v[128:131], v[166:169], v[60:63]
	v_mfma_f32_16x16x32_bf16 v[56:59], v[142:145], v[166:169], v[56:59]
	v_mfma_f32_16x16x32_bf16 v[44:47], v[128:131], v[184:187], v[44:47]
	v_mfma_f32_16x16x32_bf16 v[40:43], v[142:145], v[184:187], v[40:43]
	v_mfma_f32_16x16x32_bf16 v[28:31], v[128:131], v[192:195], v[28:31]
	v_mfma_f32_16x16x32_bf16 v[24:27], v[142:145], v[192:195], v[24:27]
	v_mfma_f32_16x16x32_bf16 v[12:15], v[128:131], v[214:217], v[12:15]
	v_mfma_f32_16x16x32_bf16 v[8:11], v[142:145], v[214:217], v[8:11]
	v_mfma_f32_16x16x32_bf16 v[60:63], v[138:141], v[180:183], v[60:63]
	v_mfma_f32_16x16x32_bf16 v[56:59], v[146:149], v[180:183], v[56:59]
	v_mfma_f32_16x16x32_bf16 v[44:47], v[138:141], v[188:191], v[44:47]
	v_mfma_f32_16x16x32_bf16 v[40:43], v[146:149], v[188:191], v[40:43]
	v_mfma_f32_16x16x32_bf16 v[28:31], v[138:141], v[210:213], v[28:31]
	v_mfma_f32_16x16x32_bf16 v[24:27], v[146:149], v[210:213], v[24:27]
	v_mfma_f32_16x16x32_bf16 v[12:15], v[138:141], v[218:221], v[12:15]
	v_mfma_f32_16x16x32_bf16 v[8:11], v[146:149], v[218:221], v[8:11]
	s_setprio 0
	s_setprio 1
	v_mfma_f32_16x16x32_bf16 v[52:55], v[150:153], v[166:169], v[52:55]
	v_mfma_f32_16x16x32_bf16 v[48:51], v[158:161], v[166:169], v[48:51]
	v_mfma_f32_16x16x32_bf16 v[36:39], v[150:153], v[184:187], v[36:39]
	v_mfma_f32_16x16x32_bf16 v[32:35], v[158:161], v[184:187], v[32:35]
	v_mfma_f32_16x16x32_bf16 v[20:23], v[150:153], v[192:195], v[20:23]
	v_mfma_f32_16x16x32_bf16 v[16:19], v[158:161], v[192:195], v[16:19]
	v_mfma_f32_16x16x32_bf16 v[4:7], v[150:153], v[214:217], v[4:7]
	v_mfma_f32_16x16x32_bf16 v[0:3], v[158:161], v[214:217], v[0:3]
	v_mfma_f32_16x16x32_bf16 v[52:55], v[154:157], v[180:183], v[52:55]
	v_mfma_f32_16x16x32_bf16 v[48:51], v[162:165], v[180:183], v[48:51]
	v_mfma_f32_16x16x32_bf16 v[36:39], v[154:157], v[188:191], v[36:39]
	v_mfma_f32_16x16x32_bf16 v[32:35], v[162:165], v[188:191], v[32:35]
	v_mfma_f32_16x16x32_bf16 v[20:23], v[154:157], v[210:213], v[20:23]
	v_mfma_f32_16x16x32_bf16 v[16:19], v[162:165], v[210:213], v[16:19]
	v_mfma_f32_16x16x32_bf16 v[4:7], v[154:157], v[218:221], v[4:7]
	v_mfma_f32_16x16x32_bf16 v[0:3], v[162:165], v[218:221], v[0:3]
	s_barrier
	s_setprio 0
	v_add_u32_e32 v146, s28, v171
	v_add_u32_e32 v162, s27, v171
	ds_read_b128 v[128:131], v146
	ds_read_b128 v[138:141], v146 offset:1024
	ds_read_b128 v[142:145], v146 offset:2048
	ds_read_b128 v[146:149], v146 offset:3072
	ds_read_b128 v[150:153], v162
	ds_read_b128 v[154:157], v162 offset:1024
	ds_read_b128 v[158:161], v162 offset:2048
	ds_read_b128 v[162:165], v162 offset:3072
	s_mov_b32 m0, s36
	v_lshl_add_u64 v[226:227], vcc, 0, v[136:137]
	ds_read_b128 v[166:169], v173 offset:32768
	ds_read_b128 v[180:183], v173 offset:33792
	ds_read_b128 v[184:187], v173 offset:34816
	ds_read_b128 v[188:191], v173 offset:35840
	ds_read_b128 v[192:195], v173 offset:36864
	ds_read_b128 v[210:213], v173 offset:37888
	ds_read_b128 v[214:217], v173 offset:38912
	ds_read_b128 v[218:221], v173 offset:39936
	global_load_lds_dwordx4 v[226:227], off
	v_lshl_add_u64 v[226:227], vcc, 0, v[134:135]
	s_mov_b32 m0, s9
	s_nop 0
	global_load_lds_dwordx4 v[226:227], off
	s_waitcnt vmcnt(8)
	s_waitcnt lgkmcnt(0)
	s_setprio 1
	s_barrier
	v_mfma_f32_16x16x32_bf16 v[124:127], v[128:131], v[166:169], v[124:127]
	v_mfma_f32_16x16x32_bf16 v[120:123], v[142:145], v[166:169], v[120:123]
	v_mfma_f32_16x16x32_bf16 v[108:111], v[128:131], v[184:187], v[108:111]
	v_mfma_f32_16x16x32_bf16 v[104:107], v[142:145], v[184:187], v[104:107]
	v_mfma_f32_16x16x32_bf16 v[92:95], v[128:131], v[192:195], v[92:95]
	v_mfma_f32_16x16x32_bf16 v[88:91], v[142:145], v[192:195], v[88:91]
	v_mfma_f32_16x16x32_bf16 v[76:79], v[128:131], v[214:217], v[76:79]
	v_mfma_f32_16x16x32_bf16 v[72:75], v[142:145], v[214:217], v[72:75]
	v_mfma_f32_16x16x32_bf16 v[124:127], v[138:141], v[180:183], v[124:127]
	v_mfma_f32_16x16x32_bf16 v[120:123], v[146:149], v[180:183], v[120:123]
	v_mfma_f32_16x16x32_bf16 v[108:111], v[138:141], v[188:191], v[108:111]
	v_mfma_f32_16x16x32_bf16 v[104:107], v[146:149], v[188:191], v[104:107]
	v_mfma_f32_16x16x32_bf16 v[92:95], v[138:141], v[210:213], v[92:95]
	v_mfma_f32_16x16x32_bf16 v[88:91], v[146:149], v[210:213], v[88:91]
	v_mfma_f32_16x16x32_bf16 v[76:79], v[138:141], v[218:221], v[76:79]
	v_mfma_f32_16x16x32_bf16 v[72:75], v[146:149], v[218:221], v[72:75]
	s_setprio 0
	s_setprio 1
	s_mov_b32 m0, s19
	v_lshl_add_u64 v[174:175], v[174:175], 0, s[48:49]
	v_mfma_f32_16x16x32_bf16 v[116:119], v[150:153], v[166:169], v[116:119]
	v_mfma_f32_16x16x32_bf16 v[112:115], v[158:161], v[166:169], v[112:115]
	v_mfma_f32_16x16x32_bf16 v[100:103], v[150:153], v[184:187], v[100:103]
	v_mfma_f32_16x16x32_bf16 v[96:99], v[158:161], v[184:187], v[96:99]
	v_mfma_f32_16x16x32_bf16 v[84:87], v[150:153], v[192:195], v[84:87]
	v_mfma_f32_16x16x32_bf16 v[80:83], v[158:161], v[192:195], v[80:83]
	v_mfma_f32_16x16x32_bf16 v[68:71], v[150:153], v[214:217], v[68:71]
	v_mfma_f32_16x16x32_bf16 v[64:67], v[158:161], v[214:217], v[64:67]
	v_mfma_f32_16x16x32_bf16 v[116:119], v[154:157], v[180:183], v[116:119]
	v_mfma_f32_16x16x32_bf16 v[112:115], v[162:165], v[180:183], v[112:115]
	v_mfma_f32_16x16x32_bf16 v[100:103], v[154:157], v[188:191], v[100:103]
	v_mfma_f32_16x16x32_bf16 v[96:99], v[162:165], v[188:191], v[96:99]
	v_mfma_f32_16x16x32_bf16 v[84:87], v[154:157], v[210:213], v[84:87]
	v_mfma_f32_16x16x32_bf16 v[80:83], v[162:165], v[210:213], v[80:83]
	v_mfma_f32_16x16x32_bf16 v[68:71], v[154:157], v[218:221], v[68:71]
	v_mfma_f32_16x16x32_bf16 v[64:67], v[162:165], v[218:221], v[64:67]
	s_barrier
; #define PG8_STAGE(bufoff, gbase, voff) do { _Pragma("unroll") for (int _i = 0; _i < 2; ++_i) \
;         __builtin_amdgcn_global_load_lds((const unsigned*)((const char*)(gbase) + (voff)[_i]), (LAS unsigned*)(lds + (bufoff) + ldsw + _i * 8192), 16, 0, 0); } while (0)
; #define PG8_LDA(dst, b, h) do { _Pragma("unroll") for (int m = 0; m < 4; ++m) _Pragma("unroll") for (int k = 0; k < 2; ++k) dst[m][k] = *(const LAS bf16x8*)(lds + PG8_SA(b, h) + aoff + m * 2048 + k * 1024); } while (0)
; #define PG8_MMA(ai, bj, At, Bt) do { __builtin_amdgcn_s_setprio(1); _Pragma("unroll") for (int m = 0; m < 4; ++m) _Pragma("unroll") for (int n = 0; n < 2; ++n) _Pragma("unroll") for (int k = 0; k < 2; ++k) \
;         acc[ai][bj][m][n] = __builtin_amdgcn_mfma_f32_16x16x32_bf16(Bt[n][k], At[m][k], acc[ai][bj][m][n], 0, 0, 0); __builtin_amdgcn_s_setprio(0); } while (0)
; #define PG8_WAIT_V(n) asm volatile("s_waitcnt vmcnt(" #n ")" ::: "memory")
; #define PG8_WAIT_L(n) asm volatile("s_waitcnt lgkmcnt(" #n ")" ::: "memory")
; #define PG8_BAR __builtin_amdgcn_s_barrier()
; #define PG8_SCHED __builtin_amdgcn_sched_barrier(0)
; template <class Epi>
; __device__ __forceinline__ void gemm_phase(LAS unsigned char* lds, const GemmD g, const Epi& E, int G, int c) {
;     ...
;         for (int t = 0; t < nt; t += 2) {
;     ...
;             PG8_LDA(At, 1, 1); PG8_STAGE(PG8_SB(1, 0), b3, voffB); PG8_STAGE(PG8_SB(1, 1), b3 + hstepB, voffB); PG8_STAGE(PG8_SA(1, 0), a3, voffA);
;             PG8_WAIT_V(8); PG8_WAIT_L(0); PG8_BAR; PG8_MMA(1, 0, At, B0); PG8_MMA(1, 1, At, B1); PG8_BAR; PG8_SCHED;
;         }
;         if (wr == 0) PG8_BAR;
	s_setprio 0
	ds_read_b128 v[166:169], v173 offset:49152
	ds_read_b128 v[180:183], v173 offset:50176
	ds_read_b128 v[184:187], v173 offset:51200
	ds_read_b128 v[188:191], v173 offset:52224
	ds_read_b128 v[192:195], v173 offset:53248
	ds_read_b128 v[210:213], v173 offset:54272
	ds_read_b128 v[214:217], v173 offset:55296
	ds_read_b128 v[218:221], v173 offset:56320
	global_load_lds_dwordx4 v[174:175], off
	v_lshl_add_u64 v[174:175], v[198:199], 0, s[48:49]
	s_mov_b32 m0, s17
	s_nop 0
	global_load_lds_dwordx4 v[174:175], off
	v_lshl_add_u64 v[174:175], s[90:91], 0, v[178:179]
	s_mov_b32 m0, s50
	s_nop 0
	global_load_lds_dwordx4 v[174:175], off
	v_lshl_add_u64 v[174:175], s[90:91], 0, v[132:133]
	s_mov_b32 m0, s39
	s_nop 0
	global_load_lds_dwordx4 v[174:175], off
	v_lshl_add_u64 v[174:175], v[222:223], 0, s[48:49]
	s_mov_b32 m0, s10
	s_nop 0
	global_load_lds_dwordx4 v[174:175], off
	v_lshl_add_u64 v[174:175], v[224:225], 0, s[48:49]
	s_mov_b32 m0, s11
	s_nop 0
	global_load_lds_dwordx4 v[174:175], off
	s_waitcnt vmcnt(8)
	s_waitcnt lgkmcnt(0)
	s_setprio 1
	s_barrier
	v_mfma_f32_16x16x32_bf16 v[60:63], v[128:131], v[166:169], v[60:63]
	v_mfma_f32_16x16x32_bf16 v[56:59], v[142:145], v[166:169], v[56:59]
	v_mfma_f32_16x16x32_bf16 v[44:47], v[128:131], v[184:187], v[44:47]
	v_mfma_f32_16x16x32_bf16 v[40:43], v[142:145], v[184:187], v[40:43]
	v_mfma_f32_16x16x32_bf16 v[28:31], v[128:131], v[192:195], v[28:31]
	v_mfma_f32_16x16x32_bf16 v[24:27], v[142:145], v[192:195], v[24:27]
	v_mfma_f32_16x16x32_bf16 v[12:15], v[128:131], v[214:217], v[12:15]
	v_mfma_f32_16x16x32_bf16 v[8:11], v[142:145], v[214:217], v[8:11]
	v_mfma_f32_16x16x32_bf16 v[60:63], v[138:141], v[180:183], v[60:63]
	v_mfma_f32_16x16x32_bf16 v[56:59], v[146:149], v[180:183], v[56:59]
	v_mfma_f32_16x16x32_bf16 v[44:47], v[138:141], v[188:191], v[44:47]
	v_mfma_f32_16x16x32_bf16 v[40:43], v[146:149], v[188:191], v[40:43]
	v_mfma_f32_16x16x32_bf16 v[28:31], v[138:141], v[210:213], v[28:31]
	v_mfma_f32_16x16x32_bf16 v[24:27], v[146:149], v[210:213], v[24:27]
	v_mfma_f32_16x16x32_bf16 v[12:15], v[138:141], v[218:221], v[12:15]
	v_mfma_f32_16x16x32_bf16 v[8:11], v[146:149], v[218:221], v[8:11]
	s_setprio 0
	s_setprio 1
	v_mfma_f32_16x16x32_bf16 v[52:55], v[150:153], v[166:169], v[52:55]
	v_mfma_f32_16x16x32_bf16 v[48:51], v[158:161], v[166:169], v[48:51]
	v_mfma_f32_16x16x32_bf16 v[36:39], v[150:153], v[184:187], v[36:39]
	v_mfma_f32_16x16x32_bf16 v[32:35], v[158:161], v[184:187], v[32:35]
	v_mfma_f32_16x16x32_bf16 v[20:23], v[150:153], v[192:195], v[20:23]
	v_mfma_f32_16x16x32_bf16 v[16:19], v[158:161], v[192:195], v[16:19]
	v_mfma_f32_16x16x32_bf16 v[4:7], v[150:153], v[214:217], v[4:7]
	v_mfma_f32_16x16x32_bf16 v[0:3], v[158:161], v[214:217], v[0:3]
	v_mfma_f32_16x16x32_bf16 v[52:55], v[154:157], v[180:183], v[52:55]
	v_mfma_f32_16x16x32_bf16 v[48:51], v[162:165], v[180:183], v[48:51]
	v_mfma_f32_16x16x32_bf16 v[36:39], v[154:157], v[188:191], v[36:39]
	v_mfma_f32_16x16x32_bf16 v[32:35], v[162:165], v[188:191], v[32:35]
	v_mfma_f32_16x16x32_bf16 v[20:23], v[154:157], v[210:213], v[20:23]
	v_mfma_f32_16x16x32_bf16 v[16:19], v[162:165], v[210:213], v[16:19]
	v_mfma_f32_16x16x32_bf16 v[4:7], v[154:157], v[218:221], v[4:7]
	v_mfma_f32_16x16x32_bf16 v[0:3], v[162:165], v[218:221], v[0:3]
	s_barrier
	s_setprio 0
	s_movk_i32 s4, 0x100
	s_andn2_b64 vcc, exec, s[88:89]
	s_mov_b64 s[90:91], -1
	s_mov_b64 s[88:89], 0
	s_cbranch_vccz .LBB0_329
	s_and_b64 vcc, exec, s[62:63]
	s_cbranch_vccz .LBB0_332
	s_barrier

; #define PG8_STAGE(bufoff, gbase, voff) do { _Pragma("unroll") for (int _i = 0; _i < 2; ++_i) \
;         __builtin_amdgcn_global_load_lds((const unsigned*)((const char*)(gbase) + (voff)[_i]), (LAS unsigned*)(lds + (bufoff) + ldsw + _i * 8192), 16, 0, 0); } while (0)
; #define PG8_LDA(dst, b, h) do { _Pragma("unroll") for (int m = 0; m < 4; ++m) _Pragma("unroll") for (int k = 0; k < 2; ++k) dst[m][k] = *(const LAS bf16x8*)(lds + PG8_SA(b, h) + aoff + m * 2048 + k * 1024); } while (0)
; #define PG8_MMA(ai, bj, At, Bt) do { __builtin_amdgcn_s_setprio(1); _Pragma("unroll") for (int m = 0; m < 4; ++m) _Pragma("unroll") for (int n = 0; n < 2; ++n) _Pragma("unroll") for (int k = 0; k < 2; ++k) \
;         acc[ai][bj][m][n] = __builtin_amdgcn_mfma_f32_16x16x32_bf16(Bt[n][k], At[m][k], acc[ai][bj][m][n], 0, 0, 0); __builtin_amdgcn_s_setprio(0); } while (0)
; #define PG8_WAIT_V(n) asm volatile("s_waitcnt vmcnt(" #n ")" ::: "memory")
; #define PG8_WAIT_L(n) asm volatile("s_waitcnt lgkmcnt(" #n ")" ::: "memory")
; #define PG8_BAR __builtin_amdgcn_s_barrier()
; #define PG8_SCHED __builtin_amdgcn_sched_barrier(0)
; template <class Epi>
; __device__ __forceinline__ void gemm_phase(LAS unsigned char* lds, const GemmD g, const Epi& E, int G, int c) {
;     ...
;             PG8_WAIT_V(8); PG8_WAIT_L(0); PG8_BAR; PG8_MMA(0, 0, At, B0); PG8_MMA(0, 1, At, B1); PG8_BAR; PG8_SCHED;
;             PG8_LDA(At, 0, 1); PG8_STAGE(PG8_SB(0, 0), b2, voffB); PG8_STAGE(PG8_SB(0, 1), b2 + hstepB, voffB); PG8_STAGE(PG8_SA(0, 0), a2, voffA);
.Lrw_In_0_d:
	s_waitcnt lgkmcnt(0)
	s_setprio 1
	s_barrier
	v_mfma_f32_16x16x32_bf16 v[124:127], v[128:131], v[184:187], v[124:127]
	v_mfma_f32_16x16x32_bf16 v[120:123], v[136:139], v[184:187], v[120:123]
	v_mfma_f32_16x16x32_bf16 v[108:111], v[128:131], v[210:213], v[108:111]
	v_mfma_f32_16x16x32_bf16 v[104:107], v[136:139], v[210:213], v[104:107]
	v_mfma_f32_16x16x32_bf16 v[92:95], v[128:131], v[218:221], v[92:95]
	v_mfma_f32_16x16x32_bf16 v[88:91], v[136:139], v[218:221], v[88:91]
	v_mfma_f32_16x16x32_bf16 v[76:79], v[128:131], v[226:229], v[76:79]
	v_mfma_f32_16x16x32_bf16 v[72:75], v[136:139], v[226:229], v[72:75]
	v_mfma_f32_16x16x32_bf16 v[124:127], v[132:135], v[188:191], v[124:127]
	v_mfma_f32_16x16x32_bf16 v[120:123], v[140:143], v[188:191], v[120:123]
	v_mfma_f32_16x16x32_bf16 v[108:111], v[132:135], v[214:217], v[108:111]
	v_mfma_f32_16x16x32_bf16 v[104:107], v[140:143], v[214:217], v[104:107]
	v_mfma_f32_16x16x32_bf16 v[92:95], v[132:135], v[222:225], v[92:95]
	v_mfma_f32_16x16x32_bf16 v[88:91], v[140:143], v[222:225], v[88:91]
	v_mfma_f32_16x16x32_bf16 v[76:79], v[132:135], v[230:233], v[76:79]
	v_mfma_f32_16x16x32_bf16 v[72:75], v[140:143], v[230:233], v[72:75]
	s_setprio 0
	s_setprio 1
	s_add_i32 s28, s28, s16
	v_lshl_add_u64 v[174:175], s[80:81], 0, v[148:149]
	s_mov_b32 m0, s28
	v_mfma_f32_16x16x32_bf16 v[116:119], v[162:165], v[184:187], v[116:119]
	v_mfma_f32_16x16x32_bf16 v[112:115], v[170:173], v[184:187], v[112:115]
	v_mfma_f32_16x16x32_bf16 v[100:103], v[162:165], v[210:213], v[100:103]
	v_mfma_f32_16x16x32_bf16 v[96:99], v[170:173], v[210:213], v[96:99]
	v_mfma_f32_16x16x32_bf16 v[84:87], v[162:165], v[218:221], v[84:87]
	v_mfma_f32_16x16x32_bf16 v[80:83], v[170:173], v[218:221], v[80:83]
	v_mfma_f32_16x16x32_bf16 v[68:71], v[162:165], v[226:229], v[68:71]
	v_mfma_f32_16x16x32_bf16 v[64:67], v[170:173], v[226:229], v[64:67]
	v_mfma_f32_16x16x32_bf16 v[116:119], v[166:169], v[188:191], v[116:119]
	v_mfma_f32_16x16x32_bf16 v[112:115], v[180:183], v[188:191], v[112:115]
	v_mfma_f32_16x16x32_bf16 v[100:103], v[166:169], v[214:217], v[100:103]
	v_mfma_f32_16x16x32_bf16 v[96:99], v[180:183], v[214:217], v[96:99]
	v_mfma_f32_16x16x32_bf16 v[84:87], v[166:169], v[222:225], v[84:87]
	v_mfma_f32_16x16x32_bf16 v[80:83], v[180:183], v[222:225], v[80:83]
	v_mfma_f32_16x16x32_bf16 v[68:71], v[166:169], v[230:233], v[68:71]
	v_mfma_f32_16x16x32_bf16 v[64:67], v[180:183], v[230:233], v[64:67]
	s_barrier
	s_setprio 0
	ds_read_b128 v[184:187], v196 offset:16384
	ds_read_b128 v[188:191], v196 offset:17408
	ds_read_b128 v[210:213], v196 offset:18432
	ds_read_b128 v[214:217], v196 offset:19456
	ds_read_b128 v[218:221], v196 offset:20480
	ds_read_b128 v[222:225], v196 offset:21504
	ds_read_b128 v[226:229], v196 offset:22528
	ds_read_b128 v[230:233], v196 offset:23552
	global_load_lds_dwordx4 v[174:175], off
	s_add_i32 m0, s28, 0x2000
	s_add_u32 s28, s80, 0x80000
	v_lshl_add_u64 v[192:193], s[80:81], 0, v[144:145]
	s_addc_u32 s29, s81, 0
	s_add_i32 s31, s31, s16
	global_load_lds_dwordx4 v[192:193], off
	v_lshl_add_u64 v[198:199], s[28:29], 0, v[148:149]
	s_mov_b32 m0, s31
	v_lshl_add_u64 v[234:235], s[4:5], 0, v[146:147]
	global_load_lds_dwordx4 v[198:199], off
	v_lshl_add_u64 v[198:199], s[28:29], 0, v[144:145]
	s_add_i32 m0, s31, 0x2000
	s_nop 0
	global_load_lds_dwordx4 v[198:199], off
	v_lshl_add_u64 v[198:199], s[4:5], 0, v[150:151]
	s_mov_b32 m0, s23
	s_nop 0
	global_load_lds_dwordx4 v[198:199], off
	s_mov_b32 m0, s26
	s_nop 0
	global_load_lds_dwordx4 v[234:235], off
	s_cmp_lg_u32 s99, 0
	s_cbranch_scc1 .Lrw_In_1_r
	s_waitcnt vmcnt(8)
	s_branch .Lrw_In_1_d

; #define PG8_STAGE(bufoff, gbase, voff) do { _Pragma("unroll") for (int _i = 0; _i < 2; ++_i) \
;         __builtin_amdgcn_global_load_lds((const unsigned*)((const char*)(gbase) + (voff)[_i]), (LAS unsigned*)(lds + (bufoff) + ldsw + _i * 8192), 16, 0, 0); } while (0)
; #define PG8_LDA(dst, b, h) do { _Pragma("unroll") for (int m = 0; m < 4; ++m) _Pragma("unroll") for (int k = 0; k < 2; ++k) dst[m][k] = *(const LAS bf16x8*)(lds + PG8_SA(b, h) + aoff + m * 2048 + k * 1024); } while (0)
; #define PG8_LDB(dst, b, h) do { _Pragma("unroll") for (int n = 0; n < 2; ++n) _Pragma("unroll") for (int k = 0; k < 2; ++k) dst[n][k] = *(const LAS bf16x8*)(lds + PG8_SB(b, h) + boff + n * 2048 + k * 1024); } while (0)
; #define PG8_MMA(ai, bj, At, Bt) do { __builtin_amdgcn_s_setprio(1); _Pragma("unroll") for (int m = 0; m < 4; ++m) _Pragma("unroll") for (int n = 0; n < 2; ++n) _Pragma("unroll") for (int k = 0; k < 2; ++k) \
;         acc[ai][bj][m][n] = __builtin_amdgcn_mfma_f32_16x16x32_bf16(Bt[n][k], At[m][k], acc[ai][bj][m][n], 0, 0, 0); __builtin_amdgcn_s_setprio(0); } while (0)
; #define PG8_WAIT_V(n) asm volatile("s_waitcnt vmcnt(" #n ")" ::: "memory")
; #define PG8_WAIT_L(n) asm volatile("s_waitcnt lgkmcnt(" #n ")" ::: "memory")
; #define PG8_BAR __builtin_amdgcn_s_barrier()
; #define PG8_SCHED __builtin_amdgcn_sched_barrier(0)
; template <class Epi>
; __device__ __forceinline__ void gemm_phase(LAS unsigned char* lds, const GemmD g, const Epi& E, int G, int c) {
;     ...
;             PG8_WAIT_V(8); PG8_WAIT_L(0); PG8_BAR; PG8_MMA(1, 0, At, B0); PG8_MMA(1, 1, At, B1); PG8_BAR; PG8_SCHED;
;             PG8_LDB(B0, 1, 0); PG8_LDB(B1, 1, 1); PG8_SCHED; PG8_LDA(At, 1, 0); PG8_STAGE(PG8_SA(0, 1), a2 + hstepA, voffA);
;             PG8_WAIT_V(8); PG8_WAIT_L(0); PG8_BAR; PG8_MMA(0, 0, At, B0); PG8_MMA(0, 1, At, B1); PG8_BAR; PG8_SCHED;
.Lrw_In_1_d:
	s_waitcnt lgkmcnt(0)
	s_setprio 1
	s_barrier
	v_mfma_f32_16x16x32_bf16 v[60:63], v[128:131], v[184:187], v[60:63]
	v_mfma_f32_16x16x32_bf16 v[56:59], v[136:139], v[184:187], v[56:59]
	v_mfma_f32_16x16x32_bf16 v[44:47], v[128:131], v[210:213], v[44:47]
	v_mfma_f32_16x16x32_bf16 v[40:43], v[136:139], v[210:213], v[40:43]
	v_mfma_f32_16x16x32_bf16 v[28:31], v[128:131], v[218:221], v[28:31]
	v_mfma_f32_16x16x32_bf16 v[24:27], v[136:139], v[218:221], v[24:27]
	v_mfma_f32_16x16x32_bf16 v[12:15], v[128:131], v[226:229], v[12:15]
	v_mfma_f32_16x16x32_bf16 v[8:11], v[136:139], v[226:229], v[8:11]
	v_mfma_f32_16x16x32_bf16 v[60:63], v[132:135], v[188:191], v[60:63]
	v_mfma_f32_16x16x32_bf16 v[56:59], v[140:143], v[188:191], v[56:59]
	v_mfma_f32_16x16x32_bf16 v[44:47], v[132:135], v[214:217], v[44:47]
	v_mfma_f32_16x16x32_bf16 v[40:43], v[140:143], v[214:217], v[40:43]
	v_mfma_f32_16x16x32_bf16 v[28:31], v[132:135], v[222:225], v[28:31]
	v_mfma_f32_16x16x32_bf16 v[24:27], v[140:143], v[222:225], v[24:27]
	v_mfma_f32_16x16x32_bf16 v[12:15], v[132:135], v[230:233], v[12:15]
	v_mfma_f32_16x16x32_bf16 v[8:11], v[140:143], v[230:233], v[8:11]
	s_setprio 0
	s_setprio 1
	s_add_i32 s28, 0, 0x18000
	s_add_i32 s29, 0, 0x1c000
	v_add_u32_e32 v140, s28, v194
	v_add_u32_e32 v178, s29, v194
	v_mfma_f32_16x16x32_bf16 v[52:55], v[162:165], v[184:187], v[52:55]
	v_mfma_f32_16x16x32_bf16 v[48:51], v[170:173], v[184:187], v[48:51]
	v_mfma_f32_16x16x32_bf16 v[36:39], v[162:165], v[210:213], v[36:39]
	v_mfma_f32_16x16x32_bf16 v[32:35], v[170:173], v[210:213], v[32:35]
	v_mfma_f32_16x16x32_bf16 v[20:23], v[162:165], v[218:221], v[20:23]
	v_mfma_f32_16x16x32_bf16 v[16:19], v[170:173], v[218:221], v[16:19]
	v_mfma_f32_16x16x32_bf16 v[4:7], v[162:165], v[226:229], v[4:7]
	v_mfma_f32_16x16x32_bf16 v[0:3], v[170:173], v[226:229], v[0:3]
	v_mfma_f32_16x16x32_bf16 v[52:55], v[166:169], v[188:191], v[52:55]
	v_mfma_f32_16x16x32_bf16 v[48:51], v[180:183], v[188:191], v[48:51]
	v_mfma_f32_16x16x32_bf16 v[36:39], v[166:169], v[214:217], v[36:39]
	v_mfma_f32_16x16x32_bf16 v[32:35], v[180:183], v[214:217], v[32:35]
	v_mfma_f32_16x16x32_bf16 v[20:23], v[166:169], v[222:225], v[20:23]
	v_mfma_f32_16x16x32_bf16 v[16:19], v[180:183], v[222:225], v[16:19]
	v_mfma_f32_16x16x32_bf16 v[4:7], v[166:169], v[230:233], v[4:7]
	v_mfma_f32_16x16x32_bf16 v[0:3], v[180:183], v[230:233], v[0:3]
	s_barrier
	s_setprio 0
	ds_read_b128 v[128:131], v140
	ds_read_b128 v[132:135], v140 offset:1024
	ds_read_b128 v[136:139], v140 offset:2048
	ds_read_b128 v[140:143], v140 offset:3072
	ds_read_b128 v[162:165], v178
	ds_read_b128 v[166:169], v178 offset:1024
	ds_read_b128 v[170:173], v178 offset:2048
	ds_read_b128 v[180:183], v178 offset:3072
	s_add_u32 s4, s4, 0x80000
	s_addc_u32 s5, s5, 0
	s_mov_b32 m0, s30
	v_lshl_add_u64 v[236:237], s[4:5], 0, v[150:151]
	ds_read_b128 v[184:187], v196 offset:32768
	ds_read_b128 v[188:191], v196 offset:33792
	ds_read_b128 v[210:213], v196 offset:34816
	ds_read_b128 v[214:217], v196 offset:35840
	ds_read_b128 v[218:221], v196 offset:36864
	ds_read_b128 v[222:225], v196 offset:37888
	ds_read_b128 v[226:229], v196 offset:38912
	ds_read_b128 v[230:233], v196 offset:39936
	global_load_lds_dwordx4 v[236:237], off
	v_lshl_add_u64 v[236:237], s[4:5], 0, v[146:147]
	s_mov_b32 m0, s35
	s_nop 0
	global_load_lds_dwordx4 v[236:237], off
	s_waitcnt vmcnt(8)
	s_waitcnt lgkmcnt(0)
	s_setprio 1
	s_barrier
	v_mfma_f32_16x16x32_bf16 v[124:127], v[128:131], v[184:187], v[124:127]
	v_mfma_f32_16x16x32_bf16 v[120:123], v[136:139], v[184:187], v[120:123]
	v_mfma_f32_16x16x32_bf16 v[108:111], v[128:131], v[210:213], v[108:111]
	v_mfma_f32_16x16x32_bf16 v[104:107], v[136:139], v[210:213], v[104:107]
	v_mfma_f32_16x16x32_bf16 v[92:95], v[128:131], v[218:221], v[92:95]
	v_mfma_f32_16x16x32_bf16 v[88:91], v[136:139], v[218:221], v[88:91]
	v_mfma_f32_16x16x32_bf16 v[76:79], v[128:131], v[226:229], v[76:79]
	v_mfma_f32_16x16x32_bf16 v[72:75], v[136:139], v[226:229], v[72:75]
	v_mfma_f32_16x16x32_bf16 v[124:127], v[132:135], v[188:191], v[124:127]
	v_mfma_f32_16x16x32_bf16 v[120:123], v[140:143], v[188:191], v[120:123]
	v_mfma_f32_16x16x32_bf16 v[108:111], v[132:135], v[214:217], v[108:111]
	v_mfma_f32_16x16x32_bf16 v[104:107], v[140:143], v[214:217], v[104:107]
	v_mfma_f32_16x16x32_bf16 v[92:95], v[132:135], v[222:225], v[92:95]
	v_mfma_f32_16x16x32_bf16 v[88:91], v[140:143], v[222:225], v[88:91]
	v_mfma_f32_16x16x32_bf16 v[76:79], v[132:135], v[230:233], v[76:79]
	v_mfma_f32_16x16x32_bf16 v[72:75], v[140:143], v[230:233], v[72:75]
	s_setprio 0
	s_setprio 1
	s_add_i32 s4, s28, s16
	v_lshl_add_u64 v[174:175], v[174:175], 0, s[48:49]
	s_mov_b32 m0, s4
	v_mfma_f32_16x16x32_bf16 v[116:119], v[162:165], v[184:187], v[116:119]
	v_mfma_f32_16x16x32_bf16 v[112:115], v[170:173], v[184:187], v[112:115]
	v_mfma_f32_16x16x32_bf16 v[100:103], v[162:165], v[210:213], v[100:103]
	v_mfma_f32_16x16x32_bf16 v[96:99], v[170:173], v[210:213], v[96:99]
	v_mfma_f32_16x16x32_bf16 v[84:87], v[162:165], v[218:221], v[84:87]
	v_mfma_f32_16x16x32_bf16 v[80:83], v[170:173], v[218:221], v[80:83]
	v_mfma_f32_16x16x32_bf16 v[68:71], v[162:165], v[226:229], v[68:71]
	v_mfma_f32_16x16x32_bf16 v[64:67], v[170:173], v[226:229], v[64:67]
	v_mfma_f32_16x16x32_bf16 v[116:119], v[166:169], v[188:191], v[116:119]
	v_mfma_f32_16x16x32_bf16 v[112:115], v[180:183], v[188:191], v[112:115]
	v_mfma_f32_16x16x32_bf16 v[100:103], v[166:169], v[214:217], v[100:103]
	v_mfma_f32_16x16x32_bf16 v[96:99], v[180:183], v[214:217], v[96:99]
	v_mfma_f32_16x16x32_bf16 v[84:87], v[166:169], v[222:225], v[84:87]
	v_mfma_f32_16x16x32_bf16 v[80:83], v[180:183], v[222:225], v[80:83]
	v_mfma_f32_16x16x32_bf16 v[68:71], v[166:169], v[230:233], v[68:71]
	v_mfma_f32_16x16x32_bf16 v[64:67], v[180:183], v[230:233], v[64:67]
	s_barrier
; #define PG8_STAGE(bufoff, gbase, voff) do { _Pragma("unroll") for (int _i = 0; _i < 2; ++_i) \
;         __builtin_amdgcn_global_load_lds((const unsigned*)((const char*)(gbase) + (voff)[_i]), (LAS unsigned*)(lds + (bufoff) + ldsw + _i * 8192), 16, 0, 0); } while (0)
; #define PG8_LDA(dst, b, h) do { _Pragma("unroll") for (int m = 0; m < 4; ++m) _Pragma("unroll") for (int k = 0; k < 2; ++k) dst[m][k] = *(const LAS bf16x8*)(lds + PG8_SA(b, h) + aoff + m * 2048 + k * 1024); } while (0)
; #define PG8_MMA(ai, bj, At, Bt) do { __builtin_amdgcn_s_setprio(1); _Pragma("unroll") for (int m = 0; m < 4; ++m) _Pragma("unroll") for (int n = 0; n < 2; ++n) _Pragma("unroll") for (int k = 0; k < 2; ++k) \
;         acc[ai][bj][m][n] = __builtin_amdgcn_mfma_f32_16x16x32_bf16(Bt[n][k], At[m][k], acc[ai][bj][m][n], 0, 0, 0); __builtin_amdgcn_s_setprio(0); } while (0)
; #define PG8_WAIT_V(n) asm volatile("s_waitcnt vmcnt(" #n ")" ::: "memory")
; #define PG8_WAIT_L(n) asm volatile("s_waitcnt lgkmcnt(" #n ")" ::: "memory")
; #define PG8_BAR __builtin_amdgcn_s_barrier()
; #define PG8_SCHED __builtin_amdgcn_sched_barrier(0)
; template <class Epi>
; __device__ __forceinline__ void gemm_phase(LAS unsigned char* lds, const GemmD g, const Epi& E, int G, int c) {
;     ...
;             PG8_LDA(At, 1, 1); PG8_STAGE(PG8_SB(1, 0), b3, voffB); PG8_STAGE(PG8_SB(1, 1), b3 + hstepB, voffB); PG8_STAGE(PG8_SA(1, 0), a3, voffA);
;             PG8_WAIT_V(8); PG8_WAIT_L(0); PG8_BAR; PG8_MMA(1, 0, At, B0); PG8_MMA(1, 1, At, B1); PG8_BAR; PG8_SCHED;
;         }
;         if (wr == 0) PG8_BAR;
	s_setprio 0
	ds_read_b128 v[184:187], v196 offset:49152
	ds_read_b128 v[188:191], v196 offset:50176
	ds_read_b128 v[210:213], v196 offset:51200
	ds_read_b128 v[214:217], v196 offset:52224
	ds_read_b128 v[218:221], v196 offset:53248
	ds_read_b128 v[222:225], v196 offset:54272
	ds_read_b128 v[226:229], v196 offset:55296
	ds_read_b128 v[230:233], v196 offset:56320
	global_load_lds_dwordx4 v[174:175], off
	s_add_i32 m0, s4, 0x2000
	s_add_u32 s4, s80, 0x80080
	v_lshl_add_u64 v[174:175], v[192:193], 0, s[48:49]
	s_addc_u32 s5, s81, 0
	s_add_i32 s28, s29, s16
	global_load_lds_dwordx4 v[174:175], off
	v_lshl_add_u64 v[174:175], s[4:5], 0, v[148:149]
	s_mov_b32 m0, s28
	s_nop 0
	global_load_lds_dwordx4 v[174:175], off
	v_lshl_add_u64 v[174:175], s[4:5], 0, v[144:145]
	s_add_i32 m0, s28, 0x2000
	s_nop 0
	global_load_lds_dwordx4 v[174:175], off
	v_lshl_add_u64 v[174:175], v[198:199], 0, s[48:49]
	s_mov_b32 m0, s36
	s_nop 0
	global_load_lds_dwordx4 v[174:175], off
	v_lshl_add_u64 v[174:175], v[234:235], 0, s[48:49]
	s_mov_b32 m0, s82
	s_nop 0
	global_load_lds_dwordx4 v[174:175], off
	s_waitcnt vmcnt(8)
	s_waitcnt lgkmcnt(0)
	s_setprio 1
	s_barrier
	v_mfma_f32_16x16x32_bf16 v[60:63], v[128:131], v[184:187], v[60:63]
	v_mfma_f32_16x16x32_bf16 v[56:59], v[136:139], v[184:187], v[56:59]
	v_mfma_f32_16x16x32_bf16 v[44:47], v[128:131], v[210:213], v[44:47]
	v_mfma_f32_16x16x32_bf16 v[40:43], v[136:139], v[210:213], v[40:43]
	v_mfma_f32_16x16x32_bf16 v[28:31], v[128:131], v[218:221], v[28:31]
	v_mfma_f32_16x16x32_bf16 v[24:27], v[136:139], v[218:221], v[24:27]
	v_mfma_f32_16x16x32_bf16 v[12:15], v[128:131], v[226:229], v[12:15]
	v_mfma_f32_16x16x32_bf16 v[8:11], v[136:139], v[226:229], v[8:11]
	v_mfma_f32_16x16x32_bf16 v[60:63], v[132:135], v[188:191], v[60:63]
	v_mfma_f32_16x16x32_bf16 v[56:59], v[140:143], v[188:191], v[56:59]
	v_mfma_f32_16x16x32_bf16 v[44:47], v[132:135], v[214:217], v[44:47]
	v_mfma_f32_16x16x32_bf16 v[40:43], v[140:143], v[214:217], v[40:43]
	v_mfma_f32_16x16x32_bf16 v[28:31], v[132:135], v[222:225], v[28:31]
	v_mfma_f32_16x16x32_bf16 v[24:27], v[140:143], v[222:225], v[24:27]
	v_mfma_f32_16x16x32_bf16 v[12:15], v[132:135], v[230:233], v[12:15]
	v_mfma_f32_16x16x32_bf16 v[8:11], v[140:143], v[230:233], v[8:11]
	s_setprio 0
	s_setprio 1
	v_mfma_f32_16x16x32_bf16 v[52:55], v[162:165], v[184:187], v[52:55]
	v_mfma_f32_16x16x32_bf16 v[48:51], v[170:173], v[184:187], v[48:51]
	v_mfma_f32_16x16x32_bf16 v[36:39], v[162:165], v[210:213], v[36:39]
	v_mfma_f32_16x16x32_bf16 v[32:35], v[170:173], v[210:213], v[32:35]
	v_mfma_f32_16x16x32_bf16 v[20:23], v[162:165], v[218:221], v[20:23]
	v_mfma_f32_16x16x32_bf16 v[16:19], v[170:173], v[218:221], v[16:19]
	v_mfma_f32_16x16x32_bf16 v[4:7], v[162:165], v[226:229], v[4:7]
	v_mfma_f32_16x16x32_bf16 v[0:3], v[170:173], v[226:229], v[0:3]
	v_mfma_f32_16x16x32_bf16 v[52:55], v[166:169], v[188:191], v[52:55]
	v_mfma_f32_16x16x32_bf16 v[48:51], v[180:183], v[188:191], v[48:51]
	v_mfma_f32_16x16x32_bf16 v[36:39], v[166:169], v[214:217], v[36:39]
	v_mfma_f32_16x16x32_bf16 v[32:35], v[180:183], v[214:217], v[32:35]
	v_mfma_f32_16x16x32_bf16 v[20:23], v[166:169], v[222:225], v[20:23]
	v_mfma_f32_16x16x32_bf16 v[16:19], v[180:183], v[222:225], v[16:19]
	v_mfma_f32_16x16x32_bf16 v[4:7], v[166:169], v[230:233], v[4:7]
	v_mfma_f32_16x16x32_bf16 v[0:3], v[180:183], v[230:233], v[0:3]
	s_barrier
	s_setprio 0
	s_add_i32 s27, s27, 2
	s_add_u32 s42, s42, 0x100
	s_addc_u32 s43, s43, 0
	s_add_u32 s19, s19, 0x100
	s_addc_u32 s22, s22, 0
	s_cmp_gt_u32 s27, 29
	s_cbranch_scc0 .LBB0_394
	s_and_b64 vcc, exec, s[46:47]
	s_cbranch_vccz .LBB0_397
	s_barrier

; #define PG8_STAGE(bufoff, gbase, voff) do { _Pragma("unroll") for (int _i = 0; _i < 2; ++_i) \
;         __builtin_amdgcn_global_load_lds((const unsigned*)((const char*)(gbase) + (voff)[_i]), (LAS unsigned*)(lds + (bufoff) + ldsw + _i * 8192), 16, 0, 0); } while (0)
; #define PG8_LDA(dst, b, h) do { _Pragma("unroll") for (int m = 0; m < 4; ++m) _Pragma("unroll") for (int k = 0; k < 2; ++k) dst[m][k] = *(const LAS bf16x8*)(lds + PG8_SA(b, h) + aoff + m * 2048 + k * 1024); } while (0)
; #define PG8_MMA(ai, bj, At, Bt) do { __builtin_amdgcn_s_setprio(1); _Pragma("unroll") for (int m = 0; m < 4; ++m) _Pragma("unroll") for (int n = 0; n < 2; ++n) _Pragma("unroll") for (int k = 0; k < 2; ++k) \
;         acc[ai][bj][m][n] = __builtin_amdgcn_mfma_f32_16x16x32_bf16(Bt[n][k], At[m][k], acc[ai][bj][m][n], 0, 0, 0); __builtin_amdgcn_s_setprio(0); } while (0)
; #define PG8_WAIT_V(n) asm volatile("s_waitcnt vmcnt(" #n ")" ::: "memory")
; #define PG8_WAIT_L(n) asm volatile("s_waitcnt lgkmcnt(" #n ")" ::: "memory")
; #define PG8_BAR __builtin_amdgcn_s_barrier()
; #define PG8_SCHED __builtin_amdgcn_sched_barrier(0)
; template <class Epi>
; __device__ __forceinline__ void gemm_phase(LAS unsigned char* lds, const GemmD g, const Epi& E, int G, int c) {
;     ...
;             PG8_WAIT_V(8); PG8_WAIT_L(0); PG8_BAR; PG8_MMA(0, 0, At, B0); PG8_MMA(0, 1, At, B1); PG8_BAR; PG8_SCHED;
;             PG8_LDA(At, 0, 1); PG8_STAGE(PG8_SB(0, 0), b2, voffB); PG8_STAGE(PG8_SB(0, 1), b2 + hstepB, voffB); PG8_STAGE(PG8_SA(0, 0), a2, voffA);
.Lrw_Bf16_0_d:
	s_waitcnt lgkmcnt(0)
	s_setprio 1
	s_barrier
	v_mfma_f32_16x16x32_bf16 v[124:127], v[128:131], v[180:183], v[124:127]
	v_mfma_f32_16x16x32_bf16 v[120:123], v[146:149], v[180:183], v[120:123]
	v_mfma_f32_16x16x32_bf16 v[112:115], v[128:131], v[188:191], v[112:115]
	v_mfma_f32_16x16x32_bf16 v[108:111], v[146:149], v[188:191], v[108:111]
	v_mfma_f32_16x16x32_bf16 v[100:103], v[128:131], v[210:213], v[100:103]
	v_mfma_f32_16x16x32_bf16 v[92:95], v[146:149], v[210:213], v[92:95]
	v_mfma_f32_16x16x32_bf16 v[84:87], v[128:131], v[218:221], v[84:87]
	v_mfma_f32_16x16x32_bf16 v[76:79], v[146:149], v[218:221], v[76:79]
	v_mfma_f32_16x16x32_bf16 v[124:127], v[132:135], v[184:187], v[124:127]
	v_mfma_f32_16x16x32_bf16 v[120:123], v[150:153], v[184:187], v[120:123]
	v_mfma_f32_16x16x32_bf16 v[112:115], v[132:135], v[192:195], v[112:115]
	v_mfma_f32_16x16x32_bf16 v[108:111], v[150:153], v[192:195], v[108:111]
	v_mfma_f32_16x16x32_bf16 v[100:103], v[132:135], v[214:217], v[100:103]
	v_mfma_f32_16x16x32_bf16 v[92:95], v[150:153], v[214:217], v[92:95]
	v_mfma_f32_16x16x32_bf16 v[84:87], v[132:135], v[222:225], v[84:87]
	v_mfma_f32_16x16x32_bf16 v[76:79], v[150:153], v[222:225], v[76:79]
	s_setprio 0
	s_setprio 1
	s_add_i32 s38, s38, s9
	v_lshl_add_u64 v[174:175], s[76:77], 0, v[178:179]
	s_mov_b32 m0, s38
	v_mfma_f32_16x16x32_bf16 v[116:119], v[154:157], v[180:183], v[116:119]
	v_mfma_f32_16x16x32_bf16 v[104:107], v[166:169], v[180:183], v[104:107]
	v_mfma_f32_16x16x32_bf16 v[96:99], v[154:157], v[188:191], v[96:99]
	v_mfma_f32_16x16x32_bf16 v[88:91], v[166:169], v[188:191], v[88:91]
	v_mfma_f32_16x16x32_bf16 v[80:83], v[154:157], v[210:213], v[80:83]
	v_mfma_f32_16x16x32_bf16 v[72:75], v[166:169], v[210:213], v[72:75]
	v_mfma_f32_16x16x32_bf16 v[68:71], v[154:157], v[218:221], v[68:71]
	v_mfma_f32_16x16x32_bf16 v[64:67], v[166:169], v[218:221], v[64:67]
	v_mfma_f32_16x16x32_bf16 v[116:119], v[162:165], v[184:187], v[116:119]
	v_mfma_f32_16x16x32_bf16 v[104:107], v[170:173], v[184:187], v[104:107]
	v_mfma_f32_16x16x32_bf16 v[96:99], v[162:165], v[192:195], v[96:99]
	v_mfma_f32_16x16x32_bf16 v[88:91], v[170:173], v[192:195], v[88:91]
	v_mfma_f32_16x16x32_bf16 v[80:83], v[162:165], v[214:217], v[80:83]
	v_mfma_f32_16x16x32_bf16 v[72:75], v[170:173], v[214:217], v[72:75]
	v_mfma_f32_16x16x32_bf16 v[68:71], v[162:165], v[222:225], v[68:71]
	v_mfma_f32_16x16x32_bf16 v[64:67], v[170:173], v[222:225], v[64:67]
	s_barrier
	s_setprio 0
	ds_read_b128 v[180:183], v161 offset:16384
	ds_read_b128 v[184:187], v161 offset:17408
	ds_read_b128 v[188:191], v161 offset:18432
	ds_read_b128 v[192:195], v161 offset:19456
	ds_read_b128 v[210:213], v161 offset:20480
	ds_read_b128 v[214:217], v161 offset:21504
	ds_read_b128 v[218:221], v161 offset:22528
	ds_read_b128 v[222:225], v161 offset:23552
	global_load_lds_dwordx4 v[174:175], off
	s_add_i32 m0, s38, 0x2000
	s_add_u32 s38, s76, 0x80000
	v_lshl_add_u64 v[198:199], s[76:77], 0, v[136:137]
	s_addc_u32 s39, s77, 0
	s_add_i32 s50, s50, s9
	global_load_lds_dwordx4 v[198:199], off
	v_lshl_add_u64 v[226:227], s[38:39], 0, v[178:179]
	s_mov_b32 m0, s50
	v_lshl_add_u64 v[228:229], s[4:5], 0, v[138:139]
	global_load_lds_dwordx4 v[226:227], off
	v_lshl_add_u64 v[226:227], s[38:39], 0, v[136:137]
	s_add_i32 m0, s50, 0x2000
	s_nop 0
	global_load_lds_dwordx4 v[226:227], off
	v_lshl_add_u64 v[226:227], s[4:5], 0, v[140:141]
	s_mov_b32 m0, s10
	s_nop 0
	global_load_lds_dwordx4 v[226:227], off
	s_mov_b32 m0, s11
	s_nop 0
	global_load_lds_dwordx4 v[228:229], off
	s_cmp_lg_u32 s99, 0
	s_cbranch_scc1 .Lrw_Bf16_1_r
	s_waitcnt vmcnt(8)
	s_branch .Lrw_Bf16_1_d

; #define PG8_STAGE(bufoff, gbase, voff) do { _Pragma("unroll") for (int _i = 0; _i < 2; ++_i) \
;         __builtin_amdgcn_global_load_lds((const unsigned*)((const char*)(gbase) + (voff)[_i]), (LAS unsigned*)(lds + (bufoff) + ldsw + _i * 8192), 16, 0, 0); } while (0)
; #define PG8_LDA(dst, b, h) do { _Pragma("unroll") for (int m = 0; m < 4; ++m) _Pragma("unroll") for (int k = 0; k < 2; ++k) dst[m][k] = *(const LAS bf16x8*)(lds + PG8_SA(b, h) + aoff + m * 2048 + k * 1024); } while (0)
; #define PG8_LDB(dst, b, h) do { _Pragma("unroll") for (int n = 0; n < 2; ++n) _Pragma("unroll") for (int k = 0; k < 2; ++k) dst[n][k] = *(const LAS bf16x8*)(lds + PG8_SB(b, h) + boff + n * 2048 + k * 1024); } while (0)
; #define PG8_MMA(ai, bj, At, Bt) do { __builtin_amdgcn_s_setprio(1); _Pragma("unroll") for (int m = 0; m < 4; ++m) _Pragma("unroll") for (int n = 0; n < 2; ++n) _Pragma("unroll") for (int k = 0; k < 2; ++k) \
;         acc[ai][bj][m][n] = __builtin_amdgcn_mfma_f32_16x16x32_bf16(Bt[n][k], At[m][k], acc[ai][bj][m][n], 0, 0, 0); __builtin_amdgcn_s_setprio(0); } while (0)
; #define PG8_WAIT_V(n) asm volatile("s_waitcnt vmcnt(" #n ")" ::: "memory")
; #define PG8_WAIT_L(n) asm volatile("s_waitcnt lgkmcnt(" #n ")" ::: "memory")
; #define PG8_BAR __builtin_amdgcn_s_barrier()
; #define PG8_SCHED __builtin_amdgcn_sched_barrier(0)
; template <class Epi>
; __device__ __forceinline__ void gemm_phase(LAS unsigned char* lds, const GemmD g, const Epi& E, int G, int c) {
;     ...
;             PG8_WAIT_V(8); PG8_WAIT_L(0); PG8_BAR; PG8_MMA(1, 0, At, B0); PG8_MMA(1, 1, At, B1); PG8_BAR; PG8_SCHED;
;             PG8_LDB(B0, 1, 0); PG8_LDB(B1, 1, 1); PG8_SCHED; PG8_LDA(At, 1, 0); PG8_STAGE(PG8_SA(0, 1), a2 + hstepA, voffA);
;             PG8_WAIT_V(8); PG8_WAIT_L(0); PG8_BAR; PG8_MMA(0, 0, At, B0); PG8_MMA(0, 1, At, B1); PG8_BAR; PG8_SCHED;
.Lrw_Bf16_1_d:
	s_waitcnt lgkmcnt(0)
	s_setprio 1
	s_barrier
	v_mfma_f32_16x16x32_bf16 v[60:63], v[128:131], v[180:183], v[60:63]
	v_mfma_f32_16x16x32_bf16 v[56:59], v[146:149], v[180:183], v[56:59]
	v_mfma_f32_16x16x32_bf16 v[52:55], v[128:131], v[188:191], v[52:55]
	v_mfma_f32_16x16x32_bf16 v[44:47], v[146:149], v[188:191], v[44:47]
	v_mfma_f32_16x16x32_bf16 v[36:39], v[128:131], v[210:213], v[36:39]
	v_mfma_f32_16x16x32_bf16 v[28:31], v[146:149], v[210:213], v[28:31]
	v_mfma_f32_16x16x32_bf16 v[20:23], v[128:131], v[218:221], v[20:23]
	v_mfma_f32_16x16x32_bf16 v[12:15], v[146:149], v[218:221], v[12:15]
	v_mfma_f32_16x16x32_bf16 v[60:63], v[132:135], v[184:187], v[60:63]
	v_mfma_f32_16x16x32_bf16 v[56:59], v[150:153], v[184:187], v[56:59]
	v_mfma_f32_16x16x32_bf16 v[52:55], v[132:135], v[192:195], v[52:55]
	v_mfma_f32_16x16x32_bf16 v[44:47], v[150:153], v[192:195], v[44:47]
	v_mfma_f32_16x16x32_bf16 v[36:39], v[132:135], v[214:217], v[36:39]
	v_mfma_f32_16x16x32_bf16 v[28:31], v[150:153], v[214:217], v[28:31]
	v_mfma_f32_16x16x32_bf16 v[20:23], v[132:135], v[222:225], v[20:23]
	v_mfma_f32_16x16x32_bf16 v[12:15], v[150:153], v[222:225], v[12:15]
	s_setprio 0
	s_setprio 1
	v_mfma_f32_16x16x32_bf16 v[48:51], v[154:157], v[180:183], v[48:51]
	v_mfma_f32_16x16x32_bf16 v[40:43], v[166:169], v[180:183], v[40:43]
	v_mfma_f32_16x16x32_bf16 v[32:35], v[154:157], v[188:191], v[32:35]
	v_mfma_f32_16x16x32_bf16 v[24:27], v[166:169], v[188:191], v[24:27]
	v_mfma_f32_16x16x32_bf16 v[16:19], v[154:157], v[210:213], v[16:19]
	v_mfma_f32_16x16x32_bf16 v[8:11], v[166:169], v[210:213], v[8:11]
	v_mfma_f32_16x16x32_bf16 v[4:7], v[154:157], v[218:221], v[4:7]
	v_mfma_f32_16x16x32_bf16 v[0:3], v[166:169], v[218:221], v[0:3]
	v_mfma_f32_16x16x32_bf16 v[48:51], v[162:165], v[184:187], v[48:51]
	v_mfma_f32_16x16x32_bf16 v[40:43], v[170:173], v[184:187], v[40:43]
	v_mfma_f32_16x16x32_bf16 v[32:35], v[162:165], v[192:195], v[32:35]
	v_mfma_f32_16x16x32_bf16 v[24:27], v[170:173], v[192:195], v[24:27]
	v_mfma_f32_16x16x32_bf16 v[16:19], v[162:165], v[214:217], v[16:19]
	v_mfma_f32_16x16x32_bf16 v[8:11], v[170:173], v[214:217], v[8:11]
	v_mfma_f32_16x16x32_bf16 v[4:7], v[162:165], v[222:225], v[4:7]
	v_mfma_f32_16x16x32_bf16 v[0:3], v[170:173], v[222:225], v[0:3]
	s_barrier
	s_setprio 0
	s_add_i32 s38, 0, 0x18000
	s_add_i32 s39, 0, 0x1c000
	v_add_u32_e32 v150, s38, v159
	v_add_u32_e32 v170, s39, v159
	ds_read_b128 v[128:131], v150
	ds_read_b128 v[132:135], v150 offset:1024
	ds_read_b128 v[146:149], v150 offset:2048
	ds_read_b128 v[150:153], v150 offset:3072
	ds_read_b128 v[154:157], v170
	ds_read_b128 v[162:165], v170 offset:1024
	ds_read_b128 v[166:169], v170 offset:2048
	ds_read_b128 v[170:173], v170 offset:3072
	s_add_u32 s4, s4, 0x80000
	s_addc_u32 s5, s5, 0
	s_mov_b32 m0, s16
	v_lshl_add_u64 v[230:231], s[4:5], 0, v[140:141]
	ds_read_b128 v[180:183], v161 offset:32768
	ds_read_b128 v[184:187], v161 offset:33792
	ds_read_b128 v[188:191], v161 offset:34816
	ds_read_b128 v[192:195], v161 offset:35840
	ds_read_b128 v[210:213], v161 offset:36864
	ds_read_b128 v[214:217], v161 offset:37888
	ds_read_b128 v[218:221], v161 offset:38912
	ds_read_b128 v[222:225], v161 offset:39936
	global_load_lds_dwordx4 v[230:231], off
	v_lshl_add_u64 v[230:231], s[4:5], 0, v[138:139]
	s_mov_b32 m0, s17
	s_nop 0
	global_load_lds_dwordx4 v[230:231], off
	s_waitcnt vmcnt(8)
	s_waitcnt lgkmcnt(0)
	s_setprio 1
	s_barrier
	v_mfma_f32_16x16x32_bf16 v[124:127], v[128:131], v[180:183], v[124:127]
	v_mfma_f32_16x16x32_bf16 v[120:123], v[146:149], v[180:183], v[120:123]
	v_mfma_f32_16x16x32_bf16 v[112:115], v[128:131], v[188:191], v[112:115]
	v_mfma_f32_16x16x32_bf16 v[108:111], v[146:149], v[188:191], v[108:111]
	v_mfma_f32_16x16x32_bf16 v[100:103], v[128:131], v[210:213], v[100:103]
	v_mfma_f32_16x16x32_bf16 v[92:95], v[146:149], v[210:213], v[92:95]
	v_mfma_f32_16x16x32_bf16 v[84:87], v[128:131], v[218:221], v[84:87]
	v_mfma_f32_16x16x32_bf16 v[76:79], v[146:149], v[218:221], v[76:79]
	v_mfma_f32_16x16x32_bf16 v[124:127], v[132:135], v[184:187], v[124:127]
	v_mfma_f32_16x16x32_bf16 v[120:123], v[150:153], v[184:187], v[120:123]
	v_mfma_f32_16x16x32_bf16 v[112:115], v[132:135], v[192:195], v[112:115]
	v_mfma_f32_16x16x32_bf16 v[108:111], v[150:153], v[192:195], v[108:111]
	v_mfma_f32_16x16x32_bf16 v[100:103], v[132:135], v[214:217], v[100:103]
	v_mfma_f32_16x16x32_bf16 v[92:95], v[150:153], v[214:217], v[92:95]
	v_mfma_f32_16x16x32_bf16 v[84:87], v[132:135], v[222:225], v[84:87]
	v_mfma_f32_16x16x32_bf16 v[76:79], v[150:153], v[222:225], v[76:79]
	s_setprio 0
	s_setprio 1
	s_add_i32 s4, s38, s9
	v_lshl_add_u64 v[174:175], v[174:175], 0, s[48:49]
	s_mov_b32 m0, s4
	v_mfma_f32_16x16x32_bf16 v[116:119], v[154:157], v[180:183], v[116:119]
	v_mfma_f32_16x16x32_bf16 v[104:107], v[166:169], v[180:183], v[104:107]
	v_mfma_f32_16x16x32_bf16 v[96:99], v[154:157], v[188:191], v[96:99]
	v_mfma_f32_16x16x32_bf16 v[88:91], v[166:169], v[188:191], v[88:91]
	v_mfma_f32_16x16x32_bf16 v[80:83], v[154:157], v[210:213], v[80:83]
	v_mfma_f32_16x16x32_bf16 v[72:75], v[166:169], v[210:213], v[72:75]
	v_mfma_f32_16x16x32_bf16 v[68:71], v[154:157], v[218:221], v[68:71]
	v_mfma_f32_16x16x32_bf16 v[64:67], v[166:169], v[218:221], v[64:67]
	v_mfma_f32_16x16x32_bf16 v[116:119], v[162:165], v[184:187], v[116:119]
	v_mfma_f32_16x16x32_bf16 v[104:107], v[170:173], v[184:187], v[104:107]
	v_mfma_f32_16x16x32_bf16 v[96:99], v[162:165], v[192:195], v[96:99]
	v_mfma_f32_16x16x32_bf16 v[88:91], v[170:173], v[192:195], v[88:91]
	v_mfma_f32_16x16x32_bf16 v[80:83], v[162:165], v[214:217], v[80:83]
	v_mfma_f32_16x16x32_bf16 v[72:75], v[170:173], v[214:217], v[72:75]
	v_mfma_f32_16x16x32_bf16 v[68:71], v[162:165], v[222:225], v[68:71]
	v_mfma_f32_16x16x32_bf16 v[64:67], v[170:173], v[222:225], v[64:67]
	s_barrier
; #define PG8_STAGE(bufoff, gbase, voff) do { _Pragma("unroll") for (int _i = 0; _i < 2; ++_i) \
;         __builtin_amdgcn_global_load_lds((const unsigned*)((const char*)(gbase) + (voff)[_i]), (LAS unsigned*)(lds + (bufoff) + ldsw + _i * 8192), 16, 0, 0); } while (0)
; #define PG8_LDA(dst, b, h) do { _Pragma("unroll") for (int m = 0; m < 4; ++m) _Pragma("unroll") for (int k = 0; k < 2; ++k) dst[m][k] = *(const LAS bf16x8*)(lds + PG8_SA(b, h) + aoff + m * 2048 + k * 1024); } while (0)
; #define PG8_MMA(ai, bj, At, Bt) do { __builtin_amdgcn_s_setprio(1); _Pragma("unroll") for (int m = 0; m < 4; ++m) _Pragma("unroll") for (int n = 0; n < 2; ++n) _Pragma("unroll") for (int k = 0; k < 2; ++k) \
;         acc[ai][bj][m][n] = __builtin_amdgcn_mfma_f32_16x16x32_bf16(Bt[n][k], At[m][k], acc[ai][bj][m][n], 0, 0, 0); __builtin_amdgcn_s_setprio(0); } while (0)
; #define PG8_WAIT_V(n) asm volatile("s_waitcnt vmcnt(" #n ")" ::: "memory")
; #define PG8_WAIT_L(n) asm volatile("s_waitcnt lgkmcnt(" #n ")" ::: "memory")
; #define PG8_BAR __builtin_amdgcn_s_barrier()
; #define PG8_SCHED __builtin_amdgcn_sched_barrier(0)
; template <class Epi>
; __device__ __forceinline__ void gemm_phase(LAS unsigned char* lds, const GemmD g, const Epi& E, int G, int c) {
;     ...
;             PG8_LDA(At, 1, 1); PG8_STAGE(PG8_SB(1, 0), b3, voffB); PG8_STAGE(PG8_SB(1, 1), b3 + hstepB, voffB); PG8_STAGE(PG8_SA(1, 0), a3, voffA);
;             PG8_WAIT_V(8); PG8_WAIT_L(0); PG8_BAR; PG8_MMA(1, 0, At, B0); PG8_MMA(1, 1, At, B1); PG8_BAR; PG8_SCHED;
;         }
;         if (wr == 0) PG8_BAR;
	s_setprio 0
	ds_read_b128 v[180:183], v161 offset:49152
	ds_read_b128 v[184:187], v161 offset:50176
	ds_read_b128 v[188:191], v161 offset:51200
	ds_read_b128 v[192:195], v161 offset:52224
	ds_read_b128 v[210:213], v161 offset:53248
	ds_read_b128 v[214:217], v161 offset:54272
	ds_read_b128 v[218:221], v161 offset:55296
	ds_read_b128 v[222:225], v161 offset:56320
	global_load_lds_dwordx4 v[174:175], off
	s_add_i32 m0, s4, 0x2000
	s_add_u32 s4, s76, 0x80080
	v_lshl_add_u64 v[174:175], v[198:199], 0, s[48:49]
	s_addc_u32 s5, s77, 0
	s_add_i32 s38, s39, s9
	global_load_lds_dwordx4 v[174:175], off
	v_lshl_add_u64 v[174:175], s[4:5], 0, v[178:179]
	s_mov_b32 m0, s38
	s_nop 0
	global_load_lds_dwordx4 v[174:175], off
	v_lshl_add_u64 v[174:175], s[4:5], 0, v[136:137]
	s_add_i32 m0, s38, 0x2000
	s_nop 0
	global_load_lds_dwordx4 v[174:175], off
	v_lshl_add_u64 v[174:175], v[226:227], 0, s[48:49]
	s_mov_b32 m0, s19
	s_nop 0
	global_load_lds_dwordx4 v[174:175], off
	v_lshl_add_u64 v[174:175], v[228:229], 0, s[48:49]
	s_mov_b32 m0, s22
	s_nop 0
	global_load_lds_dwordx4 v[174:175], off
	s_waitcnt vmcnt(8)
	s_waitcnt lgkmcnt(0)
	s_setprio 1
	s_barrier
	v_mfma_f32_16x16x32_bf16 v[60:63], v[128:131], v[180:183], v[60:63]
	v_mfma_f32_16x16x32_bf16 v[56:59], v[146:149], v[180:183], v[56:59]
	v_mfma_f32_16x16x32_bf16 v[52:55], v[128:131], v[188:191], v[52:55]
	v_mfma_f32_16x16x32_bf16 v[44:47], v[146:149], v[188:191], v[44:47]
	v_mfma_f32_16x16x32_bf16 v[36:39], v[128:131], v[210:213], v[36:39]
	v_mfma_f32_16x16x32_bf16 v[28:31], v[146:149], v[210:213], v[28:31]
	v_mfma_f32_16x16x32_bf16 v[20:23], v[128:131], v[218:221], v[20:23]
	v_mfma_f32_16x16x32_bf16 v[12:15], v[146:149], v[218:221], v[12:15]
	v_mfma_f32_16x16x32_bf16 v[60:63], v[132:135], v[184:187], v[60:63]
	v_mfma_f32_16x16x32_bf16 v[56:59], v[150:153], v[184:187], v[56:59]
	v_mfma_f32_16x16x32_bf16 v[52:55], v[132:135], v[192:195], v[52:55]
	v_mfma_f32_16x16x32_bf16 v[44:47], v[150:153], v[192:195], v[44:47]
	v_mfma_f32_16x16x32_bf16 v[36:39], v[132:135], v[214:217], v[36:39]
	v_mfma_f32_16x16x32_bf16 v[28:31], v[150:153], v[214:217], v[28:31]
	v_mfma_f32_16x16x32_bf16 v[20:23], v[132:135], v[222:225], v[20:23]
	v_mfma_f32_16x16x32_bf16 v[12:15], v[150:153], v[222:225], v[12:15]
	s_setprio 0
	s_setprio 1
	v_mfma_f32_16x16x32_bf16 v[48:51], v[154:157], v[180:183], v[48:51]
	v_mfma_f32_16x16x32_bf16 v[40:43], v[166:169], v[180:183], v[40:43]
	v_mfma_f32_16x16x32_bf16 v[32:35], v[154:157], v[188:191], v[32:35]
	v_mfma_f32_16x16x32_bf16 v[24:27], v[166:169], v[188:191], v[24:27]
	v_mfma_f32_16x16x32_bf16 v[16:19], v[154:157], v[210:213], v[16:19]
	v_mfma_f32_16x16x32_bf16 v[8:11], v[166:169], v[210:213], v[8:11]
	v_mfma_f32_16x16x32_bf16 v[4:7], v[154:157], v[218:221], v[4:7]
	v_mfma_f32_16x16x32_bf16 v[0:3], v[166:169], v[218:221], v[0:3]
	v_mfma_f32_16x16x32_bf16 v[48:51], v[162:165], v[184:187], v[48:51]
	v_mfma_f32_16x16x32_bf16 v[40:43], v[170:173], v[184:187], v[40:43]
	v_mfma_f32_16x16x32_bf16 v[32:35], v[162:165], v[192:195], v[32:35]
	v_mfma_f32_16x16x32_bf16 v[24:27], v[170:173], v[192:195], v[24:27]
	v_mfma_f32_16x16x32_bf16 v[16:19], v[162:165], v[214:217], v[16:19]
	v_mfma_f32_16x16x32_bf16 v[8:11], v[170:173], v[214:217], v[8:11]
	v_mfma_f32_16x16x32_bf16 v[4:7], v[162:165], v[222:225], v[4:7]
	v_mfma_f32_16x16x32_bf16 v[0:3], v[170:173], v[222:225], v[0:3]
	s_barrier
	s_setprio 0
	s_add_i32 s36, s36, 2
	s_add_u32 s42, s42, 0x100
	s_addc_u32 s43, s43, 0
	s_add_u32 s33, s33, 0x100
	s_addc_u32 s35, s35, 0
	s_cmp_gt_u32 s36, 29
	s_cbranch_scc0 .LBB0_486
	s_and_b64 vcc, exec, s[46:47]
	s_cbranch_vccz .LBB0_489
	s_barrier
